# GEMM K-loops: ds_reads reordered to first-use order and per-MFMA progressive lgkmcnt waits instead of one lgkmcnt(0) per cluster
# baseline (speedup 1.0000x reference)
; #define PG8_STAGE(bufoff, gbase, voff) do { _Pragma("unroll") for (int _i = 0; _i < 2; ++_i) \
;         __builtin_amdgcn_global_load_lds((const unsigned*)((const char*)(gbase) + (voff)[_i]), (PG8_LAS unsigned*)(lds + (bufoff) + ldsw + _i * 8192), 16, 0, 0); } while (0)
; #define PG8_LDA(dst, b, h) do { _Pragma("unroll") for (int m = 0; m < 4; ++m) _Pragma("unroll") for (int k = 0; k < 2; ++k) dst[m][k] = *(const PG8_LAS bf16x8*)(lds + PG8_SA(b, h) + aoff + m * 2048 + k * 1024); } while (0)
; #define PG8_LDB(dst, b, h) do { _Pragma("unroll") for (int n = 0; n < 2; ++n) _Pragma("unroll") for (int k = 0; k < 2; ++k) dst[n][k] = *(const PG8_LAS bf16x8*)(lds + PG8_SB(b, h) + boff + n * 2048 + k * 1024); } while (0)
; #define PG8_WAIT_V(n) asm volatile("s_waitcnt vmcnt(" #n ")" ::: "memory")
; #define PG8_BAR __builtin_amdgcn_s_barrier()
; template <class Epi, class Sched>
; __device__ __forceinline__ void gemm_phase(PG8_LAS unsigned char* lds, const Gemm g, const Sched& S, const Epi& E) {
;     ...
;         for (int t = 0; t < nt; t += 2) {
;             const bool last = (t == nt - 2);
;             const char* a1 = cA + (size_t)(t + 1) * kstep;
;             const char* a2 = last ? nA : cA + (size_t)(t + 2) * kstep; const char* b2 = last ? nB : cB + (size_t)(t + 2) * kstep;
;             const char* a3 = a2 + kstep; const char* b3 = b2 + kstep;
;             if (last && has_next) S.a_ready(nxt);
;             PG8_LDB(B0, 0, 0); PG8_SCHED; PG8_LDA(At, 0, 0); PG8_STAGE(PG8_SA(1, 1), a1 + hstep, voffA);
;             PG8_WAIT_L(8); PG8_BAR; PG8_WAIT_L(0); PG8_MMA(0, 0, At, B0); PG8_BAR; PG8_SCHED;
;             PG8_LDB(B1, 0, 1); PG8_STAGE(PG8_SB(0, 0), b2, voffB);
;             PG8_BAR; PG8_WAIT_L(0); PG8_MMA(0, 1, At, B1); PG8_BAR;
;             PG8_LDA(At, 0, 1); PG8_STAGE(PG8_SA(0, 0), a2, voffA);
;             PG8_BAR; PG8_WAIT_L(0); PG8_MMA(1, 0, At, B0); PG8_BAR; PG8_SCHED;
;             PG8_STAGE(PG8_SB(0, 1), b2 + hstep, voffB);
;             PG8_WAIT_V(6); PG8_BAR; PG8_MMA(1, 1, At, B1); PG8_BAR;
;             PG8_LDB(B0, 1, 0); PG8_SCHED; PG8_LDA(At, 1, 0); PG8_STAGE(PG8_SA(0, 1), a2 + hstep, voffA);
;             PG8_WAIT_L(8); PG8_BAR; PG8_WAIT_L(0); PG8_MMA(0, 0, At, B0); PG8_BAR; PG8_SCHED;
;             PG8_LDB(B1, 1, 1); PG8_STAGE(PG8_SB(1, 0), b3, voffB);
;             PG8_BAR; PG8_WAIT_L(0); PG8_MMA(0, 1, At, B1); PG8_BAR;
.Lgp_1873:
.LBB0_47:
	s_add_u32 s52, s50, 0x100
	s_addc_u32 s53, s51, 0
	s_add_i32 s42, 0, 0x10000
	v_add_u32_e32 v134, s42, v225
	ds_read_b128 v[118:121], v134
	ds_read_b128 v[126:129], v134 offset:1024
	ds_read_b128 v[130:133], v134 offset:2048
	ds_read_b128 v[134:137], v134 offset:3072
	s_cmp_eq_u32 s94, 60
	s_cselect_b32 s1, s41, s53
	s_cselect_b32 s0, s68, s52
	s_cselect_b32 vcc_hi, s39, s71
	s_cselect_b32 vcc_lo, s69, s70
	v_lshl_add_u64 v[178:179], s[50:51], 0, v[210:211]
	s_add_i32 m0, s49, 0xc000
	ds_read_b128 v[146:149], v240
	ds_read_b128 v[154:157], v240 offset:2048
	ds_read_b128 v[162:165], v240 offset:4096
	ds_read_b128 v[170:173], v240 offset:6144
	ds_read_b128 v[150:153], v240 offset:1024
	ds_read_b128 v[158:161], v240 offset:3072
	ds_read_b128 v[166:169], v240 offset:5120
	ds_read_b128 v[174:177], v240 offset:7168
	global_load_lds_dwordx4 v[178:179], off
	v_lshl_add_u64 v[178:179], s[50:51], 0, v[212:213]
	s_add_i32 m0, s49, 0xe000
	s_nop 0
	global_load_lds_dwordx4 v[178:179], off
	s_waitcnt lgkmcnt(8)
	s_barrier
	s_waitcnt lgkmcnt(7)
	v_mfma_f32_16x16x32_bf16 v[142:145], v[118:121], v[146:149], v[142:145]
	v_mfma_f32_16x16x32_bf16 v[138:141], v[130:133], v[146:149], v[138:141]
	s_waitcnt lgkmcnt(6)
	v_mfma_f32_16x16x32_bf16 v[114:117], v[118:121], v[154:157], v[114:117]
	v_mfma_f32_16x16x32_bf16 v[106:109], v[130:133], v[154:157], v[106:109]
	s_waitcnt lgkmcnt(5)
	v_mfma_f32_16x16x32_bf16 v[102:105], v[118:121], v[162:165], v[102:105]
	v_mfma_f32_16x16x32_bf16 v[92:95], v[130:133], v[162:165], v[92:95]
	s_waitcnt lgkmcnt(4)
	v_mfma_f32_16x16x32_bf16 v[84:87], v[118:121], v[170:173], v[84:87]
	v_mfma_f32_16x16x32_bf16 v[76:79], v[130:133], v[170:173], v[76:79]
	s_waitcnt lgkmcnt(3)
	v_mfma_f32_16x16x32_bf16 v[142:145], v[126:129], v[150:153], v[142:145]
	v_mfma_f32_16x16x32_bf16 v[138:141], v[134:137], v[150:153], v[138:141]
	s_waitcnt lgkmcnt(2)
	v_mfma_f32_16x16x32_bf16 v[114:117], v[126:129], v[158:161], v[114:117]
	v_mfma_f32_16x16x32_bf16 v[106:109], v[134:137], v[158:161], v[106:109]
	s_waitcnt lgkmcnt(1)
	v_mfma_f32_16x16x32_bf16 v[102:105], v[126:129], v[166:169], v[102:105]
	v_mfma_f32_16x16x32_bf16 v[92:95], v[134:137], v[166:169], v[92:95]
	s_waitcnt lgkmcnt(0)
	v_mfma_f32_16x16x32_bf16 v[84:87], v[126:129], v[174:177], v[84:87]
	v_mfma_f32_16x16x32_bf16 v[76:79], v[134:137], v[174:177], v[76:79]
	s_barrier
	s_add_i32 s43, 0, 0x14000
	s_add_i32 s42, s42, s58
	v_add_u32_e32 v190, s43, v225
	v_lshl_add_u64 v[194:195], vcc, 0, v[96:97]
	s_mov_b32 m0, s42
	ds_read_b128 v[178:181], v190
	ds_read_b128 v[186:189], v190 offset:2048
	ds_read_b128 v[182:185], v190 offset:1024
	ds_read_b128 v[190:193], v190 offset:3072
	global_load_lds_dwordx4 v[194:195], off
	v_lshl_add_u64 v[196:197], vcc, 0, v[208:209]
	s_add_i32 m0, s42, 0x2000
	s_nop 0
	global_load_lds_dwordx4 v[196:197], off
	s_barrier
	s_waitcnt lgkmcnt(3)
	v_mfma_f32_16x16x32_bf16 v[122:125], v[178:181], v[146:149], v[122:125]
	s_waitcnt lgkmcnt(2)
	v_mfma_f32_16x16x32_bf16 v[110:113], v[186:189], v[146:149], v[110:113]
	v_mfma_f32_16x16x32_bf16 v[98:101], v[178:181], v[154:157], v[98:101]
	v_mfma_f32_16x16x32_bf16 v[88:91], v[186:189], v[154:157], v[88:91]
	v_mfma_f32_16x16x32_bf16 v[80:83], v[178:181], v[162:165], v[80:83]
	v_mfma_f32_16x16x32_bf16 v[72:75], v[186:189], v[162:165], v[72:75]
	v_mfma_f32_16x16x32_bf16 v[68:71], v[178:181], v[170:173], v[68:71]
	v_mfma_f32_16x16x32_bf16 v[64:67], v[186:189], v[170:173], v[64:67]
	s_waitcnt lgkmcnt(1)
	v_mfma_f32_16x16x32_bf16 v[122:125], v[182:185], v[150:153], v[122:125]
	s_waitcnt lgkmcnt(0)
	v_mfma_f32_16x16x32_bf16 v[110:113], v[190:193], v[150:153], v[110:113]
	v_mfma_f32_16x16x32_bf16 v[98:101], v[182:185], v[158:161], v[98:101]
	v_mfma_f32_16x16x32_bf16 v[88:91], v[190:193], v[158:161], v[88:91]
	v_mfma_f32_16x16x32_bf16 v[80:83], v[182:185], v[166:169], v[80:83]
	v_mfma_f32_16x16x32_bf16 v[72:75], v[190:193], v[166:169], v[72:75]
	v_mfma_f32_16x16x32_bf16 v[68:71], v[182:185], v[174:177], v[68:71]
	v_mfma_f32_16x16x32_bf16 v[64:67], v[190:193], v[174:177], v[64:67]
	s_mov_b32 m0, s49
	v_lshl_add_u64 v[198:199], s[0:1], 0, v[96:97]
	s_barrier
	ds_read_b128 v[146:149], v240 offset:16384
	ds_read_b128 v[154:157], v240 offset:18432
	ds_read_b128 v[162:165], v240 offset:20480
	ds_read_b128 v[170:173], v240 offset:22528
	ds_read_b128 v[150:153], v240 offset:17408
	ds_read_b128 v[158:161], v240 offset:19456
	ds_read_b128 v[166:169], v240 offset:21504
	ds_read_b128 v[174:177], v240 offset:23552
	global_load_lds_dwordx4 v[198:199], off
	v_lshl_add_u64 v[200:201], s[0:1], 0, v[208:209]
	s_mov_b32 m0, s61
	s_nop 0
	global_load_lds_dwordx4 v[200:201], off
	s_barrier
	s_waitcnt lgkmcnt(7)
	v_mfma_f32_16x16x32_bf16 v[60:63], v[118:121], v[146:149], v[60:63]
	v_mfma_f32_16x16x32_bf16 v[56:59], v[130:133], v[146:149], v[56:59]
	s_waitcnt lgkmcnt(6)
	v_mfma_f32_16x16x32_bf16 v[52:55], v[118:121], v[154:157], v[52:55]
	v_mfma_f32_16x16x32_bf16 v[44:47], v[130:133], v[154:157], v[44:47]
	s_waitcnt lgkmcnt(5)
	v_mfma_f32_16x16x32_bf16 v[36:39], v[118:121], v[162:165], v[36:39]
	v_mfma_f32_16x16x32_bf16 v[28:31], v[130:133], v[162:165], v[28:31]
	s_waitcnt lgkmcnt(4)
	v_mfma_f32_16x16x32_bf16 v[20:23], v[118:121], v[170:173], v[20:23]
	v_mfma_f32_16x16x32_bf16 v[12:15], v[130:133], v[170:173], v[12:15]
	s_waitcnt lgkmcnt(3)
	v_mfma_f32_16x16x32_bf16 v[60:63], v[126:129], v[150:153], v[60:63]
	v_mfma_f32_16x16x32_bf16 v[56:59], v[134:137], v[150:153], v[56:59]
	s_waitcnt lgkmcnt(2)
	v_mfma_f32_16x16x32_bf16 v[52:55], v[126:129], v[158:161], v[52:55]
	v_mfma_f32_16x16x32_bf16 v[44:47], v[134:137], v[158:161], v[44:47]
	s_waitcnt lgkmcnt(1)
	v_mfma_f32_16x16x32_bf16 v[36:39], v[126:129], v[166:169], v[36:39]
	v_mfma_f32_16x16x32_bf16 v[28:31], v[134:137], v[166:169], v[28:31]
	s_waitcnt lgkmcnt(0)
	v_mfma_f32_16x16x32_bf16 v[20:23], v[126:129], v[174:177], v[20:23]
	v_mfma_f32_16x16x32_bf16 v[12:15], v[134:137], v[174:177], v[12:15]
	s_barrier
; #define PG8_STAGE(bufoff, gbase, voff) do { _Pragma("unroll") for (int _i = 0; _i < 2; ++_i) \
;         __builtin_amdgcn_global_load_lds((const unsigned*)((const char*)(gbase) + (voff)[_i]), (PG8_LAS unsigned*)(lds + (bufoff) + ldsw + _i * 8192), 16, 0, 0); } while (0)
; #define PG8_LDA(dst, b, h) do { _Pragma("unroll") for (int m = 0; m < 4; ++m) _Pragma("unroll") for (int k = 0; k < 2; ++k) dst[m][k] = *(const PG8_LAS bf16x8*)(lds + PG8_SA(b, h) + aoff + m * 2048 + k * 1024); } while (0)
; #define PG8_LDB(dst, b, h) do { _Pragma("unroll") for (int n = 0; n < 2; ++n) _Pragma("unroll") for (int k = 0; k < 2; ++k) dst[n][k] = *(const PG8_LAS bf16x8*)(lds + PG8_SB(b, h) + boff + n * 2048 + k * 1024); } while (0)
; #define PG8_MMA(ai, bj, At, Bt) do { __builtin_amdgcn_s_setprio(1); _Pragma("unroll") for (int m = 0; m < 4; ++m) _Pragma("unroll") for (int n = 0; n < 2; ++n) _Pragma("unroll") for (int k = 0; k < 2; ++k) \
;         acc[ai][bj][m][n] = __builtin_amdgcn_mfma_f32_16x16x32_bf16(Bt[n][k], At[m][k], acc[ai][bj][m][n], 0, 0, 0); __builtin_amdgcn_s_setprio(0); } while (0)
; #define PG8_WAIT_V(n) asm volatile("s_waitcnt vmcnt(" #n ")" ::: "memory")
; #define PG8_WAIT_L(n) asm volatile("s_waitcnt lgkmcnt(" #n ")" ::: "memory")
; #define PG8_BAR __builtin_amdgcn_s_barrier()
; #define PG8_SCHED __builtin_amdgcn_sched_barrier(0)
; template <class Epi, class Sched>
; __device__ __forceinline__ void gemm_phase(PG8_LAS unsigned char* lds, const Gemm g, const Sched& S, const Epi& E) {
;     ...
;             PG8_WAIT_V(6); PG8_BAR; PG8_MMA(1, 1, At, B1); PG8_BAR;
;             PG8_LDB(B0, 1, 0); PG8_SCHED; PG8_LDA(At, 1, 0); PG8_STAGE(PG8_SA(0, 1), a2 + hstep, voffA);
;             PG8_WAIT_L(8); PG8_BAR; PG8_WAIT_L(0); PG8_MMA(0, 0, At, B0); PG8_BAR; PG8_SCHED;
;             PG8_LDB(B1, 1, 1); PG8_STAGE(PG8_SB(1, 0), b3, voffB);
;             PG8_BAR; PG8_WAIT_L(0); PG8_MMA(0, 1, At, B1); PG8_BAR;
;             PG8_LDA(At, 1, 1); PG8_STAGE(PG8_SA(1, 0), a3, voffA);
;             PG8_BAR; PG8_WAIT_L(0); PG8_MMA(1, 0, At, B0); PG8_BAR; PG8_SCHED;
;             PG8_STAGE(PG8_SB(1, 1), b3 + hstep, voffB);
	s_add_u32 s50, vcc_lo, 0x100000
	s_addc_u32 s51, vcc_hi, 0
	s_add_i32 s42, s43, s58
	v_lshl_add_u64 v[118:119], s[50:51], 0, v[96:97]
	s_mov_b32 m0, s42
	s_nop 0
	global_load_lds_dwordx4 v[118:119], off
	v_lshl_add_u64 v[118:119], s[50:51], 0, v[208:209]
	s_add_i32 m0, s42, 0x2000
	s_nop 0
	global_load_lds_dwordx4 v[118:119], off
	s_waitcnt vmcnt(6)
	s_barrier
	v_mfma_f32_16x16x32_bf16 v[48:51], v[178:181], v[146:149], v[48:51]
	v_mfma_f32_16x16x32_bf16 v[40:43], v[186:189], v[146:149], v[40:43]
	v_mfma_f32_16x16x32_bf16 v[32:35], v[178:181], v[154:157], v[32:35]
	v_mfma_f32_16x16x32_bf16 v[24:27], v[186:189], v[154:157], v[24:27]
	v_mfma_f32_16x16x32_bf16 v[16:19], v[178:181], v[162:165], v[16:19]
	v_mfma_f32_16x16x32_bf16 v[8:11], v[186:189], v[162:165], v[8:11]
	v_mfma_f32_16x16x32_bf16 v[4:7], v[178:181], v[170:173], v[4:7]
	v_mfma_f32_16x16x32_bf16 v[0:3], v[186:189], v[170:173], v[0:3]
	v_mfma_f32_16x16x32_bf16 v[48:51], v[182:185], v[150:153], v[48:51]
	v_mfma_f32_16x16x32_bf16 v[40:43], v[190:193], v[150:153], v[40:43]
	v_mfma_f32_16x16x32_bf16 v[32:35], v[182:185], v[158:161], v[32:35]
	v_mfma_f32_16x16x32_bf16 v[24:27], v[190:193], v[158:161], v[24:27]
	v_mfma_f32_16x16x32_bf16 v[16:19], v[182:185], v[166:169], v[16:19]
	v_mfma_f32_16x16x32_bf16 v[8:11], v[190:193], v[166:169], v[8:11]
	v_mfma_f32_16x16x32_bf16 v[4:7], v[182:185], v[174:177], v[4:7]
	v_mfma_f32_16x16x32_bf16 v[0:3], v[190:193], v[174:177], v[0:3]
	s_add_i32 s42, 0, 0x18000
	v_add_u32_e32 v134, s42, v225
	s_barrier
	ds_read_b128 v[118:121], v134
	ds_read_b128 v[126:129], v134 offset:1024
	ds_read_b128 v[130:133], v134 offset:2048
	ds_read_b128 v[134:137], v134 offset:3072
	s_add_u32 s0, s0, 0x100000
	s_addc_u32 s1, s1, 0
	s_mov_b32 m0, s62
	v_lshl_add_u64 v[178:179], s[0:1], 0, v[96:97]
	ds_read_b128 v[146:149], v240 offset:32768
	ds_read_b128 v[154:157], v240 offset:34816
	ds_read_b128 v[162:165], v240 offset:36864
	ds_read_b128 v[170:173], v240 offset:38912
	ds_read_b128 v[150:153], v240 offset:33792
	ds_read_b128 v[158:161], v240 offset:35840
	ds_read_b128 v[166:169], v240 offset:37888
	ds_read_b128 v[174:177], v240 offset:39936
	global_load_lds_dwordx4 v[178:179], off
	v_lshl_add_u64 v[178:179], s[0:1], 0, v[208:209]
	s_mov_b32 m0, s63
	s_nop 0
	global_load_lds_dwordx4 v[178:179], off
	s_waitcnt lgkmcnt(8)
	s_barrier
	s_waitcnt lgkmcnt(7)
	v_mfma_f32_16x16x32_bf16 v[142:145], v[118:121], v[146:149], v[142:145]
	v_mfma_f32_16x16x32_bf16 v[138:141], v[130:133], v[146:149], v[138:141]
	s_waitcnt lgkmcnt(6)
	v_mfma_f32_16x16x32_bf16 v[114:117], v[118:121], v[154:157], v[114:117]
	v_mfma_f32_16x16x32_bf16 v[106:109], v[130:133], v[154:157], v[106:109]
	s_waitcnt lgkmcnt(5)
	v_mfma_f32_16x16x32_bf16 v[102:105], v[118:121], v[162:165], v[102:105]
	v_mfma_f32_16x16x32_bf16 v[92:95], v[130:133], v[162:165], v[92:95]
	s_waitcnt lgkmcnt(4)
	v_mfma_f32_16x16x32_bf16 v[84:87], v[118:121], v[170:173], v[84:87]
	v_mfma_f32_16x16x32_bf16 v[76:79], v[130:133], v[170:173], v[76:79]
	s_waitcnt lgkmcnt(3)
	v_mfma_f32_16x16x32_bf16 v[142:145], v[126:129], v[150:153], v[142:145]
	v_mfma_f32_16x16x32_bf16 v[138:141], v[134:137], v[150:153], v[138:141]
	s_waitcnt lgkmcnt(2)
	v_mfma_f32_16x16x32_bf16 v[114:117], v[126:129], v[158:161], v[114:117]
	v_mfma_f32_16x16x32_bf16 v[106:109], v[134:137], v[158:161], v[106:109]
	s_waitcnt lgkmcnt(1)
	v_mfma_f32_16x16x32_bf16 v[102:105], v[126:129], v[166:169], v[102:105]
	v_mfma_f32_16x16x32_bf16 v[92:95], v[134:137], v[166:169], v[92:95]
	s_waitcnt lgkmcnt(0)
	v_mfma_f32_16x16x32_bf16 v[84:87], v[126:129], v[174:177], v[84:87]
	v_mfma_f32_16x16x32_bf16 v[76:79], v[134:137], v[174:177], v[76:79]
	s_barrier
	s_add_i32 s43, 0, 0x1c000
	s_add_i32 s0, s42, s58
	v_add_u32_e32 v190, s43, v225
	v_lshl_add_u64 v[194:195], v[194:195], 0, s[2:3]
	s_mov_b32 m0, s0
	ds_read_b128 v[178:181], v190
	ds_read_b128 v[186:189], v190 offset:2048
	ds_read_b128 v[182:185], v190 offset:1024
	ds_read_b128 v[190:193], v190 offset:3072
	global_load_lds_dwordx4 v[194:195], off
	v_lshl_add_u64 v[194:195], v[196:197], 0, s[2:3]
	s_add_i32 m0, s0, 0x2000
	s_nop 0
	global_load_lds_dwordx4 v[194:195], off
	s_barrier
	s_waitcnt lgkmcnt(3)
	v_mfma_f32_16x16x32_bf16 v[122:125], v[178:181], v[146:149], v[122:125]
	s_waitcnt lgkmcnt(2)
	v_mfma_f32_16x16x32_bf16 v[110:113], v[186:189], v[146:149], v[110:113]
	v_mfma_f32_16x16x32_bf16 v[98:101], v[178:181], v[154:157], v[98:101]
	v_mfma_f32_16x16x32_bf16 v[88:91], v[186:189], v[154:157], v[88:91]
	v_mfma_f32_16x16x32_bf16 v[80:83], v[178:181], v[162:165], v[80:83]
	v_mfma_f32_16x16x32_bf16 v[72:75], v[186:189], v[162:165], v[72:75]
	v_mfma_f32_16x16x32_bf16 v[68:71], v[178:181], v[170:173], v[68:71]
	v_mfma_f32_16x16x32_bf16 v[64:67], v[186:189], v[170:173], v[64:67]
	s_waitcnt lgkmcnt(1)
	v_mfma_f32_16x16x32_bf16 v[122:125], v[182:185], v[150:153], v[122:125]
	s_waitcnt lgkmcnt(0)
	v_mfma_f32_16x16x32_bf16 v[110:113], v[190:193], v[150:153], v[110:113]
	v_mfma_f32_16x16x32_bf16 v[98:101], v[182:185], v[158:161], v[98:101]
	v_mfma_f32_16x16x32_bf16 v[88:91], v[190:193], v[158:161], v[88:91]
	v_mfma_f32_16x16x32_bf16 v[80:83], v[182:185], v[166:169], v[80:83]
	v_mfma_f32_16x16x32_bf16 v[72:75], v[190:193], v[166:169], v[72:75]
	v_mfma_f32_16x16x32_bf16 v[68:71], v[182:185], v[174:177], v[68:71]
	v_mfma_f32_16x16x32_bf16 v[64:67], v[190:193], v[174:177], v[64:67]
	s_mov_b32 m0, s64
	v_lshl_add_u64 v[194:195], v[198:199], 0, s[2:3]
	s_barrier
; #define PG8_STAGE(bufoff, gbase, voff) do { _Pragma("unroll") for (int _i = 0; _i < 2; ++_i) \
;         __builtin_amdgcn_global_load_lds((const unsigned*)((const char*)(gbase) + (voff)[_i]), (PG8_LAS unsigned*)(lds + (bufoff) + ldsw + _i * 8192), 16, 0, 0); } while (0)
; #define PG8_WAIT_V(n) asm volatile("s_waitcnt vmcnt(" #n ")" ::: "memory")
; #define PG8_WAIT_L(n) asm volatile("s_waitcnt lgkmcnt(" #n ")" ::: "memory")
; #define PG8_BAR __builtin_amdgcn_s_barrier()
; template <class Epi, class Sched>
; __device__ __forceinline__ void gemm_phase(PG8_LAS unsigned char* lds, const Gemm g, const Sched& S, const Epi& E) {
;     ...
;             PG8_WAIT_V(6); PG8_BAR; PG8_MMA(1, 1, At, B1); PG8_BAR;
;             PG8_LDB(B0, 1, 0); PG8_SCHED; PG8_LDA(At, 1, 0); PG8_STAGE(PG8_SA(0, 1), a2 + hstep, voffA);
;             PG8_WAIT_L(8); PG8_BAR; PG8_WAIT_L(0); PG8_MMA(0, 0, At, B0); PG8_BAR; PG8_SCHED;
;             PG8_LDB(B1, 1, 1); PG8_STAGE(PG8_SB(1, 0), b3, voffB);
;             PG8_BAR; PG8_WAIT_L(0); PG8_MMA(0, 1, At, B1); PG8_BAR;
;             PG8_LDA(At, 1, 1); PG8_STAGE(PG8_SA(1, 0), a3, voffA);
;             PG8_BAR; PG8_WAIT_L(0); PG8_MMA(1, 0, At, B0); PG8_BAR; PG8_SCHED;
;             PG8_STAGE(PG8_SB(1, 1), b3 + hstep, voffB);
;             PG8_WAIT_V(6); PG8_BAR; PG8_MMA(1, 1, At, B1); PG8_BAR;
;         }
;         if constexpr (!Epi::AFTER_DRAIN) { E(acc, cur, wr, wc, fr, fq); S.done(cur); }
;         if (!has_next) break;
;   DEV void operator()(const f32x4 (&acc)[2][2][4][2], const pg8::Unit& u, int wr, int wc, int fr, int fq) const {
;     const int row0 = u.pm * 256 + wr * 64 + fr, col0 = u.pn * 256 + wc * 32 + 4 * fq;
;     const float* gt = mod + (size_t)modrow(row0) * 6144;
;     f32x4 g4[2][2];
; #pragma unroll
;     for (int bj = 0; bj < 2; ++bj)
; #pragma unroll
;       for (int n = 0; n < 2; ++n) g4[bj][n] = *(const f32x4*)(gt + col0 + bj * 128 + n * 16);
; #pragma unroll
;     for (int ai = 0; ai < 2; ++ai) {
;       f32x4 xv[4][2][2];
; #pragma unroll
;       for (int m = 0; m < 4; ++m) {
;         const int row = row0 + ai * 128 + m * 16;
;         const float* xi = row < T_LAT ? rin_lat + (size_t)row * DM : rin_ctx + (size_t)(row - T_LAT) * DM;
; #pragma unroll
;         for (int bj = 0; bj < 2; ++bj)
; #pragma unroll
;           for (int n = 0; n < 2; ++n) xv[m][bj][n] = *(const f32x4*)(xi + col0 + bj * 128 + n * 16);
	ds_read_b128 v[146:149], v240 offset:49152
	ds_read_b128 v[154:157], v240 offset:51200
	ds_read_b128 v[162:165], v240 offset:53248
	ds_read_b128 v[170:173], v240 offset:55296
	ds_read_b128 v[150:153], v240 offset:50176
	ds_read_b128 v[158:161], v240 offset:52224
	ds_read_b128 v[166:169], v240 offset:54272
	ds_read_b128 v[174:177], v240 offset:56320
	global_load_lds_dwordx4 v[194:195], off
	v_lshl_add_u64 v[194:195], v[200:201], 0, s[2:3]
	s_mov_b32 m0, s65
	s_nop 0
	global_load_lds_dwordx4 v[194:195], off
	s_barrier
	s_waitcnt lgkmcnt(7)
	v_mfma_f32_16x16x32_bf16 v[60:63], v[118:121], v[146:149], v[60:63]
	v_mfma_f32_16x16x32_bf16 v[56:59], v[130:133], v[146:149], v[56:59]
	s_waitcnt lgkmcnt(6)
	v_mfma_f32_16x16x32_bf16 v[52:55], v[118:121], v[154:157], v[52:55]
	v_mfma_f32_16x16x32_bf16 v[44:47], v[130:133], v[154:157], v[44:47]
	s_waitcnt lgkmcnt(5)
	v_mfma_f32_16x16x32_bf16 v[36:39], v[118:121], v[162:165], v[36:39]
	v_mfma_f32_16x16x32_bf16 v[28:31], v[130:133], v[162:165], v[28:31]
	s_waitcnt lgkmcnt(4)
	v_mfma_f32_16x16x32_bf16 v[20:23], v[118:121], v[170:173], v[20:23]
	v_mfma_f32_16x16x32_bf16 v[12:15], v[130:133], v[170:173], v[12:15]
	s_waitcnt lgkmcnt(3)
	v_mfma_f32_16x16x32_bf16 v[60:63], v[126:129], v[150:153], v[60:63]
	v_mfma_f32_16x16x32_bf16 v[56:59], v[134:137], v[150:153], v[56:59]
	s_waitcnt lgkmcnt(2)
	v_mfma_f32_16x16x32_bf16 v[52:55], v[126:129], v[158:161], v[52:55]
	v_mfma_f32_16x16x32_bf16 v[44:47], v[134:137], v[158:161], v[44:47]
	s_waitcnt lgkmcnt(1)
	v_mfma_f32_16x16x32_bf16 v[36:39], v[126:129], v[166:169], v[36:39]
	v_mfma_f32_16x16x32_bf16 v[28:31], v[134:137], v[166:169], v[28:31]
	s_waitcnt lgkmcnt(0)
	v_mfma_f32_16x16x32_bf16 v[20:23], v[126:129], v[174:177], v[20:23]
	v_mfma_f32_16x16x32_bf16 v[12:15], v[134:137], v[174:177], v[12:15]
	s_barrier
	s_add_u32 s0, vcc_lo, 0x100080
	s_addc_u32 s1, vcc_hi, 0
	s_add_i32 s42, s43, s58
	v_lshl_add_u64 v[118:119], s[0:1], 0, v[96:97]
	s_mov_b32 m0, s42
	s_nop 0
	global_load_lds_dwordx4 v[118:119], off
	v_lshl_add_u64 v[118:119], s[0:1], 0, v[208:209]
	s_add_i32 m0, s42, 0x2000
	s_nop 0
	global_load_lds_dwordx4 v[118:119], off
	s_waitcnt vmcnt(6)
	s_barrier
	v_mfma_f32_16x16x32_bf16 v[48:51], v[178:181], v[146:149], v[48:51]
	v_mfma_f32_16x16x32_bf16 v[40:43], v[186:189], v[146:149], v[40:43]
	v_mfma_f32_16x16x32_bf16 v[32:35], v[178:181], v[154:157], v[32:35]
	v_mfma_f32_16x16x32_bf16 v[24:27], v[186:189], v[154:157], v[24:27]
	v_mfma_f32_16x16x32_bf16 v[16:19], v[178:181], v[162:165], v[16:19]
	v_mfma_f32_16x16x32_bf16 v[8:11], v[186:189], v[162:165], v[8:11]
	v_mfma_f32_16x16x32_bf16 v[4:7], v[178:181], v[170:173], v[4:7]
	v_mfma_f32_16x16x32_bf16 v[0:3], v[186:189], v[170:173], v[0:3]
	v_mfma_f32_16x16x32_bf16 v[48:51], v[182:185], v[150:153], v[48:51]
	v_mfma_f32_16x16x32_bf16 v[40:43], v[190:193], v[150:153], v[40:43]
	v_mfma_f32_16x16x32_bf16 v[32:35], v[182:185], v[158:161], v[32:35]
	v_mfma_f32_16x16x32_bf16 v[24:27], v[190:193], v[158:161], v[24:27]
	v_mfma_f32_16x16x32_bf16 v[16:19], v[182:185], v[166:169], v[16:19]
	v_mfma_f32_16x16x32_bf16 v[8:11], v[190:193], v[166:169], v[8:11]
	v_mfma_f32_16x16x32_bf16 v[4:7], v[182:185], v[174:177], v[4:7]
	v_mfma_f32_16x16x32_bf16 v[0:3], v[190:193], v[174:177], v[0:3]
	s_add_i32 s94, s94, 2
	s_add_u32 s70, s70, 0x100
	s_addc_u32 s71, s71, 0
	s_cmp_gt_u32 s94, 61
	s_mov_b64 s[50:51], s[52:53]
	s_barrier
	s_cbranch_scc0 .LBB0_47
	v_lshl_add_u32 v238, s48, 8, v224
	s_mov_b32 s71, 0x8000
	v_readlane_b32 s0, v251, 52
	v_min_i32_e32 v119, 0x8000, v238
	v_cmp_gt_i32_e32 vcc, s71, v238
	v_add_u32_e32 v146, 0xffff8000, v238
	v_ashrrev_i32_e32 v147, 31, v238
	v_mov_b32_e32 v241, s0
	v_readlane_b32 s0, v251, 51
	v_lshl_or_b32 v118, s67, 8, v239
	v_ashrrev_i32_e32 v119, 12, v119
	v_cndmask_b32_e32 v147, 0, v147, vcc
	v_cndmask_b32_e32 v146, v146, v238, vcc
	v_mov_b32_e32 v242, s73
	v_mov_b32_e32 v243, s0
	v_mov_b32_e32 v244, s72
	v_mul_hi_i32_i24_e32 v121, 0x6000, v119
	v_mul_i32_i24_e32 v120, 0x6000, v119
	v_ashrrev_i32_e32 v119, 31, v118
	v_cndmask_b32_e32 v149, v241, v242, vcc
	v_cndmask_b32_e32 v148, v243, v244, vcc
	v_lshlrev_b64 v[146:147], 12, v[146:147]
	v_lshlrev_b64 v[214:215], 2, v[118:119]
	v_lshl_add_u64 v[146:147], v[148:149], 0, v[146:147]
	v_lshl_add_u64 v[222:223], v[146:147], 0, v[214:215]
	v_or_b32_e32 v146, 16, v238
	v_cmp_gt_i32_e32 vcc, s71, v146
	v_ashrrev_i32_e32 v147, 31, v146
	v_add_u32_e32 v148, 0xffff8010, v238
	v_cndmask_b32_e32 v147, 0, v147, vcc
	v_cndmask_b32_e32 v146, v148, v146, vcc
	v_cndmask_b32_e32 v149, v241, v242, vcc
	v_cndmask_b32_e32 v148, v243, v244, vcc
	v_lshlrev_b64 v[146:147], 12, v[146:147]
	v_lshl_add_u64 v[146:147], v[148:149], 0, v[146:147]
	v_lshl_add_u64 v[220:221], v[146:147], 0, v[214:215]
	v_or_b32_e32 v146, 32, v238
	v_cmp_gt_i32_e32 vcc, s71, v146
	v_ashrrev_i32_e32 v147, 31, v146
	v_add_u32_e32 v148, 0xffff8020, v238
	v_cndmask_b32_e32 v147, 0, v147, vcc
	v_cndmask_b32_e32 v146, v148, v146, vcc
	v_cndmask_b32_e32 v149, v241, v242, vcc
	v_cndmask_b32_e32 v148, v243, v244, vcc
	v_lshlrev_b64 v[146:147], 12, v[146:147]
	v_lshl_add_u64 v[146:147], v[148:149], 0, v[146:147]
	v_lshl_add_u64 v[218:219], v[146:147], 0, v[214:215]
	v_or_b32_e32 v146, 48, v238
	v_cmp_gt_i32_e32 vcc, s71, v146
	v_ashrrev_i32_e32 v147, 31, v146
	v_add_u32_e32 v148, 0xffff8030, v238
	v_cndmask_b32_e32 v147, 0, v147, vcc
	v_cndmask_b32_e32 v146, v148, v146, vcc
	v_cndmask_b32_e32 v149, v241, v242, vcc
	v_cndmask_b32_e32 v148, v243, v244, vcc
	v_lshlrev_b64 v[146:147], 12, v[146:147]
	v_lshl_add_u64 v[120:121], s[30:31], 0, v[120:121]
	v_lshl_add_u64 v[146:147], v[148:149], 0, v[146:147]
;   DEV void operator()(const f32x4 (&acc)[2][2][4][2], const pg8::Unit& u, int wr, int wc, int fr, int fq) const {
;     const int row0 = u.pm * 256 + wr * 64 + fr, col0 = u.pn * 256 + wc * 32 + 4 * fq;
;     const float* gt = mod + (size_t)modrow(row0) * 6144;
;     f32x4 g4[2][2];
; #pragma unroll
;     for (int bj = 0; bj < 2; ++bj)
; #pragma unroll
;       for (int n = 0; n < 2; ++n) g4[bj][n] = *(const f32x4*)(gt + col0 + bj * 128 + n * 16);
; #pragma unroll
;     for (int ai = 0; ai < 2; ++ai) {
;       f32x4 xv[4][2][2];
; #pragma unroll
;       for (int m = 0; m < 4; ++m) {
;         const int row = row0 + ai * 128 + m * 16;
;         const float* xi = row < T_LAT ? rin_lat + (size_t)row * DM : rin_ctx + (size_t)(row - T_LAT) * DM;
; #pragma unroll
;         for (int bj = 0; bj < 2; ++bj)
; #pragma unroll
;           for (int n = 0; n < 2; ++n) xv[m][bj][n] = *(const f32x4*)(xi + col0 + bj * 128 + n * 16);
;       }
; #pragma unroll
;       for (int m = 0; m < 4; ++m) {
;         const int row = row0 + ai * 128 + m * 16;
;         float* xr = row < T_LAT ? out + (size_t)row * DM : xc + (size_t)(row - T_LAT) * DM;
; #pragma unroll
;         for (int bj = 0; bj < 2; ++bj)
; #pragma unroll
;           for (int n = 0; n < 2; ++n) {
;             const f32x4 r = xv[m][bj][n] + g4[bj][n] * acc[ai][bj][m][n];
;             if (store) *(f32x4*)(xr + col0 + bj * 128 + n * 16) = r;
;           }
;       }
;     }
;   }
	v_lshl_add_u64 v[118:119], v[120:121], 0, v[214:215]
	v_lshl_add_u64 v[216:217], v[146:147], 0, v[214:215]
	global_load_dwordx4 v[134:137], v[118:119], off
	global_load_dwordx4 v[130:133], v[118:119], off offset:64
	global_load_dwordx4 v[126:129], v[118:119], off offset:512
	s_nop 0
	global_load_dwordx4 v[118:121], v[118:119], off offset:576
	s_nop 0
	global_load_dwordx4 v[202:205], v[222:223], off offset:64
	global_load_dwordx4 v[198:201], v[222:223], off offset:512
	global_load_dwordx4 v[194:197], v[222:223], off offset:576
	global_load_dwordx4 v[190:193], v[220:221], off
	global_load_dwordx4 v[186:189], v[220:221], off offset:64
	global_load_dwordx4 v[182:185], v[220:221], off offset:512
	global_load_dwordx4 v[174:177], v[220:221], off offset:576
	global_load_dwordx4 v[178:181], v[218:219], off
	global_load_dwordx4 v[170:173], v[218:219], off offset:64
	global_load_dwordx4 v[166:169], v[218:219], off offset:512
	global_load_dwordx4 v[158:161], v[218:219], off offset:576
	global_load_dwordx4 v[162:165], v[216:217], off
	global_load_dwordx4 v[154:157], v[216:217], off offset:64
	global_load_dwordx4 v[150:153], v[216:217], off offset:512
	global_load_dwordx4 v[146:149], v[216:217], off offset:576
	global_load_dwordx4 v[228:231], v[222:223], off
	s_movk_i32 s0, 0x7f80
	v_cmp_gt_i32_e32 vcc, s0, v238
	s_movk_i32 s0, 0x7f70
	s_mov_b32 s67, s38
	s_mov_b32 s48, s40
	s_mov_b64 s[52:53], s[46:47]
	s_mov_b64 s[50:51], s[44:45]
	s_waitcnt vmcnt(0)
	v_pk_fma_f32 v[140:141], v[140:141], v[132:133], v[204:205]
	v_pk_fma_f32 v[138:139], v[138:139], v[130:131], v[202:203]
	v_pk_fma_f32 v[124:125], v[124:125], v[128:129], v[200:201]
	v_pk_fma_f32 v[122:123], v[122:123], v[126:127], v[198:199]
	v_pk_fma_f32 v[112:113], v[112:113], v[120:121], v[196:197]
	v_pk_fma_f32 v[144:145], v[144:145], v[136:137], v[230:231]
	v_pk_fma_f32 v[142:143], v[142:143], v[134:135], v[228:229]
	v_pk_fma_f32 v[110:111], v[110:111], v[118:119], v[194:195]
	v_pk_fma_f32 v[90:91], v[90:91], v[120:121], v[176:177]
	v_pk_fma_f32 v[88:89], v[88:89], v[118:119], v[174:175]
	global_store_dwordx4 v[222:223], v[142:145], off
	global_store_dwordx4 v[222:223], v[138:141], off offset:64
	global_store_dwordx4 v[222:223], v[122:125], off offset:512
	global_store_dwordx4 v[222:223], v[110:113], off offset:576
	v_pk_fma_f32 v[108:109], v[108:109], v[132:133], v[188:189]
	v_pk_fma_f32 v[106:107], v[106:107], v[130:131], v[186:187]
	v_pk_fma_f32 v[112:113], v[116:117], v[136:137], v[192:193]
	v_pk_fma_f32 v[110:111], v[114:115], v[134:135], v[190:191]
	v_pk_fma_f32 v[100:101], v[100:101], v[128:129], v[184:185]
	v_pk_fma_f32 v[98:99], v[98:99], v[126:127], v[182:183]
	global_store_dwordx4 v[220:221], v[88:91], off offset:576
	global_store_dwordx4 v[220:221], v[110:113], off
	global_store_dwordx4 v[220:221], v[106:109], off offset:64
	v_pk_fma_f32 v[90:91], v[104:105], v[136:137], v[180:181]
	v_pk_fma_f32 v[88:89], v[102:103], v[134:135], v[178:179]
	global_store_dwordx4 v[220:221], v[98:101], off offset:512
	global_store_dwordx4 v[218:219], v[88:91], off
	v_pk_fma_f32 v[82:83], v[82:83], v[128:129], v[168:169]
	v_pk_fma_f32 v[80:81], v[80:81], v[126:127], v[166:167]
	v_pk_fma_f32 v[90:91], v[94:95], v[132:133], v[172:173]
	v_pk_fma_f32 v[88:89], v[92:93], v[130:131], v[170:171]
	v_pk_fma_f32 v[74:75], v[74:75], v[120:121], v[160:161]
	v_pk_fma_f32 v[72:73], v[72:73], v[118:119], v[158:159]
	v_pk_fma_f32 v[66:67], v[66:67], v[120:121], v[148:149]
	v_pk_fma_f32 v[64:65], v[64:65], v[118:119], v[146:147]
	global_store_dwordx4 v[218:219], v[88:91], off offset:64
	global_store_dwordx4 v[218:219], v[80:83], off offset:512
	global_store_dwordx4 v[218:219], v[72:75], off offset:576
	global_store_dwordx4 v[216:217], v[64:67], off offset:576
	v_pk_fma_f32 v[70:71], v[70:71], v[128:129], v[152:153]
	v_pk_fma_f32 v[74:75], v[86:87], v[136:137], v[164:165]
	v_add_u32_e32 v64, 0x80, v238
	v_ashrrev_i32_e32 v65, 31, v64
	v_add_u32_e32 v66, 0xffff8080, v238
	v_cndmask_b32_e32 v65, 0, v65, vcc
	v_cndmask_b32_e32 v64, v66, v64, vcc
	v_cndmask_b32_e32 v67, v241, v242, vcc
	v_cndmask_b32_e32 v66, v243, v244, vcc
	v_lshlrev_b64 v[64:65], 12, v[64:65]
	v_lshl_add_u64 v[64:65], v[66:67], 0, v[64:65]
	v_lshl_add_u64 v[148:149], v[64:65], 0, v[214:215]
	v_add_u32_e32 v64, 0x90, v238
	v_cmp_gt_i32_e32 vcc, s0, v238
	v_ashrrev_i32_e32 v65, 31, v64
	v_add_u32_e32 v66, 0xffff8090, v238
	v_cndmask_b32_e32 v65, 0, v65, vcc
	v_cndmask_b32_e32 v64, v66, v64, vcc
	v_cndmask_b32_e32 v67, v241, v242, vcc
	v_cndmask_b32_e32 v66, v243, v244, vcc
	v_lshlrev_b64 v[64:65], 12, v[64:65]
	v_lshl_add_u64 v[64:65], v[66:67], 0, v[64:65]
	v_lshl_add_u64 v[146:147], v[64:65], 0, v[214:215]
	v_add_u32_e32 v64, 0xa0, v238
	s_movk_i32 s0, 0x7f60
	v_cmp_gt_i32_e32 vcc, s0, v238
	v_ashrrev_i32_e32 v65, 31, v64
	v_add_u32_e32 v66, 0xffff80a0, v238
	v_cndmask_b32_e32 v65, 0, v65, vcc
	v_cndmask_b32_e32 v64, v66, v64, vcc
	v_cndmask_b32_e32 v67, v241, v242, vcc
	v_cndmask_b32_e32 v66, v243, v244, vcc
	v_lshlrev_b64 v[64:65], 12, v[64:65]
	v_lshl_add_u64 v[64:65], v[66:67], 0, v[64:65]
	v_lshl_add_u64 v[144:145], v[64:65], 0, v[214:215]
	v_add_u32_e32 v64, 0xb0, v238
	s_movk_i32 s0, 0x7f50
	v_cmp_gt_i32_e32 vcc, s0, v238
	v_ashrrev_i32_e32 v65, 31, v64
	v_add_u32_e32 v66, 0xffff80b0, v238
	v_pk_fma_f32 v[72:73], v[84:85], v[134:135], v[162:163]
	v_cndmask_b32_e32 v65, 0, v65, vcc
	v_cndmask_b32_e32 v64, v66, v64, vcc
	global_store_dwordx4 v[216:217], v[72:75], off
	v_pk_fma_f32 v[68:69], v[68:69], v[126:127], v[150:151]
	v_cndmask_b32_e32 v67, v241, v242, vcc
	v_pk_fma_f32 v[74:75], v[78:79], v[132:133], v[156:157]
	v_pk_fma_f32 v[72:73], v[76:77], v[130:131], v[154:155]
	v_cndmask_b32_e32 v66, v243, v244, vcc
	v_lshlrev_b64 v[64:65], 12, v[64:65]
	global_store_dwordx4 v[216:217], v[72:75], off offset:64
	global_store_dwordx4 v[216:217], v[68:71], off offset:512
	v_lshl_add_u64 v[64:65], v[66:67], 0, v[64:65]
	global_load_dwordx4 v[138:141], v[148:149], off offset:64
	global_load_dwordx4 v[122:125], v[148:149], off offset:512
	global_load_dwordx4 v[110:113], v[148:149], off offset:576
	v_lshl_add_u64 v[142:143], v[64:65], 0, v[214:215]
	global_load_dwordx4 v[114:117], v[146:147], off
	global_load_dwordx4 v[106:109], v[146:147], off offset:64
	global_load_dwordx4 v[102:105], v[146:147], off offset:512
	global_load_dwordx4 v[92:95], v[146:147], off offset:576
	global_load_dwordx4 v[98:101], v[144:145], off
	global_load_dwordx4 v[88:91], v[144:145], off offset:64
	global_load_dwordx4 v[84:87], v[144:145], off offset:512
	global_load_dwordx4 v[76:79], v[144:145], off offset:576
	global_load_dwordx4 v[80:83], v[142:143], off
	global_load_dwordx4 v[72:75], v[142:143], off offset:64
	global_load_dwordx4 v[68:71], v[142:143], off offset:512
	global_load_dwordx4 v[64:67], v[142:143], off offset:576
	global_load_dwordx4 v[150:153], v[148:149], off
	s_and_b64 vcc, exec, s[36:37]
	s_waitcnt vmcnt(0)
; #define PG8_WAIT_V(n) asm volatile("s_waitcnt vmcnt(" #n ")" ::: "memory")
; #define PG8_BAR __builtin_amdgcn_s_barrier()
; template <class Epi, class Sched>
; __device__ __forceinline__ void gemm_phase(PG8_LAS unsigned char* lds, const Gemm g, const Sched& S, const Epi& E) {
;     ...
;         if constexpr (!Epi::AFTER_DRAIN) { E(acc, cur, wr, wc, fr, fq); S.done(cur); }
;         if (!has_next) break;
; #pragma unroll
;         for (int a = 0; a < 2; ++a)
; #pragma unroll
;             for (int b = 0; b < 2; ++b)
; #pragma unroll
;                 for (int m = 0; m < 4; ++m)
; #pragma unroll
;                     for (int n = 0; n < 2; ++n) acc[a][b][m][n] = (f32x4){0.f, 0.f, 0.f, 0.f};
;         cur = nxt; cA = nA; cB = nB; ++ui;
;     }
;     PG8_WAIT_V(0);
;     if (wr == 0) PG8_BAR;
;     PG8_BAR;
;   DEV void operator()(const f32x4 (&acc)[2][2][4][2], const pg8::Unit& u, int wr, int wc, int fr, int fq) const {
;     ...
;       for (int m = 0; m < 4; ++m) {
;         const int row = row0 + ai * 128 + m * 16;
;         float* xr = row < T_LAT ? out + (size_t)row * DM : xc + (size_t)(row - T_LAT) * DM;
; #pragma unroll
;         for (int bj = 0; bj < 2; ++bj)
; #pragma unroll
;           for (int n = 0; n < 2; ++n) {
;             const f32x4 r = xv[m][bj][n] + g4[bj][n] * acc[ai][bj][m][n];
;             if (store) *(f32x4*)(xr + col0 + bj * 128 + n * 16) = r;
;           }
;       }
;     }
;   }
	v_pk_fma_f32 v[58:59], v[58:59], v[132:133], v[140:141]
	v_pk_fma_f32 v[56:57], v[56:57], v[130:131], v[138:139]
	v_pk_fma_f32 v[42:43], v[42:43], v[120:121], v[112:113]
	v_pk_fma_f32 v[40:41], v[40:41], v[118:119], v[110:111]
	v_pk_fma_f32 v[50:51], v[50:51], v[128:129], v[124:125]
	v_pk_fma_f32 v[48:49], v[48:49], v[126:127], v[122:123]
	v_pk_fma_f32 v[62:63], v[62:63], v[136:137], v[152:153]
	v_pk_fma_f32 v[60:61], v[60:61], v[134:135], v[150:151]
	global_store_dwordx4 v[148:149], v[40:43], off offset:576
	v_pk_fma_f32 v[26:27], v[26:27], v[120:121], v[94:95]
	v_pk_fma_f32 v[24:25], v[24:25], v[118:119], v[92:93]
	v_pk_fma_f32 v[42:43], v[54:55], v[136:137], v[116:117]
	v_pk_fma_f32 v[40:41], v[52:53], v[134:135], v[114:115]
	global_store_dwordx4 v[148:149], v[60:63], off
	global_store_dwordx4 v[148:149], v[56:59], off offset:64
	global_store_dwordx4 v[148:149], v[48:51], off offset:512
	global_store_dwordx4 v[146:147], v[40:43], off
	v_pk_fma_f32 v[34:35], v[34:35], v[128:129], v[104:105]
	v_pk_fma_f32 v[32:33], v[32:33], v[126:127], v[102:103]
	v_pk_fma_f32 v[42:43], v[46:47], v[132:133], v[108:109]
	v_pk_fma_f32 v[40:41], v[44:45], v[130:131], v[106:107]
	global_store_dwordx4 v[146:147], v[24:27], off offset:576
	v_pk_fma_f32 v[10:11], v[10:11], v[120:121], v[78:79]
	v_pk_fma_f32 v[8:9], v[8:9], v[118:119], v[76:77]
	v_pk_fma_f32 v[26:27], v[38:39], v[136:137], v[100:101]
	v_pk_fma_f32 v[24:25], v[36:37], v[134:135], v[98:99]
	global_store_dwordx4 v[146:147], v[40:43], off offset:64
	global_store_dwordx4 v[146:147], v[32:35], off offset:512
	global_store_dwordx4 v[144:145], v[24:27], off
	v_pk_fma_f32 v[18:19], v[18:19], v[128:129], v[86:87]
	v_pk_fma_f32 v[16:17], v[16:17], v[126:127], v[84:85]
	v_pk_fma_f32 v[26:27], v[30:31], v[132:133], v[90:91]
	v_pk_fma_f32 v[24:25], v[28:29], v[130:131], v[88:89]
	global_store_dwordx4 v[144:145], v[8:11], off offset:576
	global_store_dwordx4 v[144:145], v[24:27], off offset:64
	global_store_dwordx4 v[144:145], v[16:19], off offset:512
	v_pk_fma_f32 v[10:11], v[22:23], v[136:137], v[82:83]
	v_pk_fma_f32 v[8:9], v[20:21], v[134:135], v[80:81]
	global_store_dwordx4 v[142:143], v[8:11], off
	v_pk_fma_f32 v[6:7], v[6:7], v[128:129], v[70:71]
	v_pk_fma_f32 v[4:5], v[4:5], v[126:127], v[68:69]
	v_pk_fma_f32 v[10:11], v[14:15], v[132:133], v[74:75]
	v_pk_fma_f32 v[8:9], v[12:13], v[130:131], v[72:73]
	v_pk_fma_f32 v[2:3], v[2:3], v[120:121], v[66:67]
	v_pk_fma_f32 v[0:1], v[0:1], v[118:119], v[64:65]
	global_store_dwordx4 v[142:143], v[8:11], off offset:64
	global_store_dwordx4 v[142:143], v[4:7], off offset:512
	global_store_dwordx4 v[142:143], v[0:3], off offset:576
	s_cbranch_vccz .LBB0_44
	s_waitcnt vmcnt(0)
	v_readlane_b32 s66, v255, 34
	v_readlane_b32 s64, v255, 38
	s_cmpk_gt_u32 s56, 0xff
	v_readlane_b32 s67, v255, 35
	v_readlane_b32 s65, v255, 39
	s_cbranch_scc1 .LBB0_51
	s_barrier

; #define PG8_STAGE(bufoff, gbase, voff) do { _Pragma("unroll") for (int _i = 0; _i < 2; ++_i) \
;         __builtin_amdgcn_global_load_lds((const unsigned*)((const char*)(gbase) + (voff)[_i]), (PG8_LAS unsigned*)(lds + (bufoff) + ldsw + _i * 8192), 16, 0, 0); } while (0)
; #define PG8_LDA(dst, b, h) do { _Pragma("unroll") for (int m = 0; m < 4; ++m) _Pragma("unroll") for (int k = 0; k < 2; ++k) dst[m][k] = *(const PG8_LAS bf16x8*)(lds + PG8_SA(b, h) + aoff + m * 2048 + k * 1024); } while (0)
; #define PG8_LDB(dst, b, h) do { _Pragma("unroll") for (int n = 0; n < 2; ++n) _Pragma("unroll") for (int k = 0; k < 2; ++k) dst[n][k] = *(const PG8_LAS bf16x8*)(lds + PG8_SB(b, h) + boff + n * 2048 + k * 1024); } while (0)
; #define PG8_WAIT_V(n) asm volatile("s_waitcnt vmcnt(" #n ")" ::: "memory")
; #define PG8_WAIT_L(n) asm volatile("s_waitcnt lgkmcnt(" #n ")" ::: "memory")
; #define PG8_BAR __builtin_amdgcn_s_barrier()
; #define PG8_SCHED __builtin_amdgcn_sched_barrier(0)
; template <class Epi, class Sched>
; __device__ __forceinline__ void gemm_phase(PG8_LAS unsigned char* lds, const Gemm g, const Sched& S, const Epi& E) {
;     ...
;         for (int t = 0; t < nt; t += 2) {
;             const bool last = (t == nt - 2);
;             const char* a1 = cA + (size_t)(t + 1) * kstep;
;             const char* a2 = last ? nA : cA + (size_t)(t + 2) * kstep; const char* b2 = last ? nB : cB + (size_t)(t + 2) * kstep;
;             const char* a3 = a2 + kstep; const char* b3 = b2 + kstep;
;             if (last && has_next) S.a_ready(nxt);
;             PG8_LDB(B0, 0, 0); PG8_SCHED; PG8_LDA(At, 0, 0); PG8_STAGE(PG8_SA(1, 1), a1 + hstep, voffA);
;             PG8_WAIT_L(8); PG8_BAR; PG8_WAIT_L(0); PG8_MMA(0, 0, At, B0); PG8_BAR; PG8_SCHED;
;             PG8_LDB(B1, 0, 1); PG8_STAGE(PG8_SB(0, 0), b2, voffB);
;             PG8_BAR; PG8_WAIT_L(0); PG8_MMA(0, 1, At, B1); PG8_BAR;
;             PG8_LDA(At, 0, 1); PG8_STAGE(PG8_SA(0, 0), a2, voffA);
;             PG8_BAR; PG8_WAIT_L(0); PG8_MMA(1, 0, At, B0); PG8_BAR; PG8_SCHED;
;             PG8_STAGE(PG8_SB(0, 1), b2 + hstep, voffB);
;             PG8_WAIT_V(6); PG8_BAR; PG8_MMA(1, 1, At, B1); PG8_BAR;
;             PG8_LDB(B0, 1, 0); PG8_SCHED; PG8_LDA(At, 1, 0); PG8_STAGE(PG8_SA(0, 1), a2 + hstep, voffA);
;             PG8_WAIT_L(8); PG8_BAR; PG8_WAIT_L(0); PG8_MMA(0, 0, At, B0); PG8_BAR; PG8_SCHED;
.Lgp_2972:
.LBB0_65:
	s_add_u32 s42, s46, 0xfffc0080
	s_addc_u32 s43, s47, -1
	s_add_i32 s71, 0, 0x10000
	v_add_u32_e32 v156, s71, v141
	ds_read_b128 v[144:147], v156
	ds_read_b128 v[148:151], v156 offset:1024
	ds_read_b128 v[152:155], v156 offset:2048
	ds_read_b128 v[156:159], v156 offset:3072
	s_cmp_eq_u32 s70, 12
	s_cselect_b32 s51, s31, s43
	s_cselect_b32 s50, s66, s42
	s_cselect_b32 s49, s1, s69
	s_cselect_b32 s48, s67, s68
	v_lshl_add_u64 v[192:193], s[46:47], 0, v[136:137]
	s_add_i32 m0, s45, 0xc000
	ds_read_b128 v[160:163], v143
	ds_read_b128 v[168:171], v143 offset:2048
	ds_read_b128 v[176:179], v143 offset:4096
	ds_read_b128 v[184:187], v143 offset:6144
	ds_read_b128 v[164:167], v143 offset:1024
	ds_read_b128 v[172:175], v143 offset:3072
	ds_read_b128 v[180:183], v143 offset:5120
	ds_read_b128 v[188:191], v143 offset:7168
	global_load_lds_dwordx4 v[192:193], off
	v_lshl_add_u64 v[192:193], s[46:47], 0, v[138:139]
	s_add_i32 m0, s45, 0xe000
	s_nop 0
	global_load_lds_dwordx4 v[192:193], off
	s_waitcnt lgkmcnt(8)
	s_barrier
	s_waitcnt lgkmcnt(7)
	v_mfma_f32_16x16x32_bf16 v[126:129], v[144:147], v[160:163], v[126:129]
	v_mfma_f32_16x16x32_bf16 v[122:125], v[152:155], v[160:163], v[122:125]
	s_waitcnt lgkmcnt(6)
	v_mfma_f32_16x16x32_bf16 v[110:113], v[144:147], v[168:171], v[110:113]
	v_mfma_f32_16x16x32_bf16 v[106:109], v[152:155], v[168:171], v[106:109]
	s_waitcnt lgkmcnt(5)
	v_mfma_f32_16x16x32_bf16 v[92:95], v[144:147], v[176:179], v[92:95]
	v_mfma_f32_16x16x32_bf16 v[88:91], v[152:155], v[176:179], v[88:91]
	s_waitcnt lgkmcnt(4)
	v_mfma_f32_16x16x32_bf16 v[76:79], v[144:147], v[184:187], v[76:79]
	v_mfma_f32_16x16x32_bf16 v[72:75], v[152:155], v[184:187], v[72:75]
	s_waitcnt lgkmcnt(3)
	v_mfma_f32_16x16x32_bf16 v[126:129], v[148:151], v[164:167], v[126:129]
	v_mfma_f32_16x16x32_bf16 v[122:125], v[156:159], v[164:167], v[122:125]
	s_waitcnt lgkmcnt(2)
	v_mfma_f32_16x16x32_bf16 v[110:113], v[148:151], v[172:175], v[110:113]
	v_mfma_f32_16x16x32_bf16 v[106:109], v[156:159], v[172:175], v[106:109]
	s_waitcnt lgkmcnt(1)
	v_mfma_f32_16x16x32_bf16 v[92:95], v[148:151], v[180:183], v[92:95]
	v_mfma_f32_16x16x32_bf16 v[88:91], v[156:159], v[180:183], v[88:91]
	s_waitcnt lgkmcnt(0)
	v_mfma_f32_16x16x32_bf16 v[76:79], v[148:151], v[188:191], v[76:79]
	v_mfma_f32_16x16x32_bf16 v[72:75], v[156:159], v[188:191], v[72:75]
	s_barrier
	s_add_i32 s42, 0, 0x14000
	v_add_u32_e32 v204, s42, v141
	s_add_i32 s43, s71, s56
	ds_read_b128 v[192:195], v204
	ds_read_b128 v[200:203], v204 offset:2048
	ds_read_b128 v[196:199], v204 offset:1024
	ds_read_b128 v[208:211], v204 offset:3072
	v_lshl_add_u64 v[204:205], s[48:49], 0, v[96:97]
	s_mov_b32 m0, s43
	v_lshl_add_u64 v[212:213], s[48:49], 0, v[130:131]
	global_load_lds_dwordx4 v[204:205], off
	s_add_i32 m0, s43, 0x2000
	s_nop 0
	global_load_lds_dwordx4 v[212:213], off
	s_barrier
	s_waitcnt lgkmcnt(3)
	v_mfma_f32_16x16x32_bf16 v[118:121], v[192:195], v[160:163], v[118:121]
	s_waitcnt lgkmcnt(2)
	v_mfma_f32_16x16x32_bf16 v[114:117], v[200:203], v[160:163], v[114:117]
	v_mfma_f32_16x16x32_bf16 v[102:105], v[192:195], v[168:171], v[102:105]
	v_mfma_f32_16x16x32_bf16 v[98:101], v[200:203], v[168:171], v[98:101]
	v_mfma_f32_16x16x32_bf16 v[84:87], v[192:195], v[176:179], v[84:87]
	v_mfma_f32_16x16x32_bf16 v[80:83], v[200:203], v[176:179], v[80:83]
	v_mfma_f32_16x16x32_bf16 v[68:71], v[192:195], v[184:187], v[68:71]
	v_mfma_f32_16x16x32_bf16 v[64:67], v[200:203], v[184:187], v[64:67]
	s_waitcnt lgkmcnt(1)
	v_mfma_f32_16x16x32_bf16 v[118:121], v[196:199], v[164:167], v[118:121]
	s_waitcnt lgkmcnt(0)
	v_mfma_f32_16x16x32_bf16 v[114:117], v[208:211], v[164:167], v[114:117]
	v_mfma_f32_16x16x32_bf16 v[102:105], v[196:199], v[172:175], v[102:105]
	v_mfma_f32_16x16x32_bf16 v[98:101], v[208:211], v[172:175], v[98:101]
	v_mfma_f32_16x16x32_bf16 v[84:87], v[196:199], v[180:183], v[84:87]
	v_mfma_f32_16x16x32_bf16 v[80:83], v[208:211], v[180:183], v[80:83]
	v_mfma_f32_16x16x32_bf16 v[68:71], v[196:199], v[188:191], v[68:71]
	v_mfma_f32_16x16x32_bf16 v[64:67], v[208:211], v[188:191], v[64:67]
	s_mov_b32 m0, s45
	v_lshl_add_u64 v[214:215], s[50:51], 0, v[134:135]
	s_barrier
	ds_read_b128 v[160:163], v143 offset:16384
	ds_read_b128 v[168:171], v143 offset:18432
	ds_read_b128 v[176:179], v143 offset:20480
	ds_read_b128 v[184:187], v143 offset:22528
	ds_read_b128 v[164:167], v143 offset:17408
	ds_read_b128 v[172:175], v143 offset:19456
	ds_read_b128 v[180:183], v143 offset:21504
	ds_read_b128 v[188:191], v143 offset:23552
	global_load_lds_dwordx4 v[214:215], off
	v_lshl_add_u64 v[216:217], s[50:51], 0, v[132:133]
	s_mov_b32 m0, s59
	s_nop 0
	global_load_lds_dwordx4 v[216:217], off
	s_barrier
	s_waitcnt lgkmcnt(7)
	v_mfma_f32_16x16x32_bf16 v[60:63], v[144:147], v[160:163], v[60:63]
	v_mfma_f32_16x16x32_bf16 v[56:59], v[152:155], v[160:163], v[56:59]
	s_waitcnt lgkmcnt(6)
	v_mfma_f32_16x16x32_bf16 v[44:47], v[144:147], v[168:171], v[44:47]
	v_mfma_f32_16x16x32_bf16 v[40:43], v[152:155], v[168:171], v[40:43]
	s_waitcnt lgkmcnt(5)
	v_mfma_f32_16x16x32_bf16 v[28:31], v[144:147], v[176:179], v[28:31]
	v_mfma_f32_16x16x32_bf16 v[24:27], v[152:155], v[176:179], v[24:27]
	s_waitcnt lgkmcnt(4)
	v_mfma_f32_16x16x32_bf16 v[12:15], v[144:147], v[184:187], v[12:15]
	v_mfma_f32_16x16x32_bf16 v[8:11], v[152:155], v[184:187], v[8:11]
	s_waitcnt lgkmcnt(3)
	v_mfma_f32_16x16x32_bf16 v[60:63], v[148:151], v[164:167], v[60:63]
	v_mfma_f32_16x16x32_bf16 v[56:59], v[156:159], v[164:167], v[56:59]
	s_waitcnt lgkmcnt(2)
	v_mfma_f32_16x16x32_bf16 v[44:47], v[148:151], v[172:175], v[44:47]
	v_mfma_f32_16x16x32_bf16 v[40:43], v[156:159], v[172:175], v[40:43]
	s_waitcnt lgkmcnt(1)
	v_mfma_f32_16x16x32_bf16 v[28:31], v[148:151], v[180:183], v[28:31]
	v_mfma_f32_16x16x32_bf16 v[24:27], v[156:159], v[180:183], v[24:27]
	s_waitcnt lgkmcnt(0)
	v_mfma_f32_16x16x32_bf16 v[12:15], v[148:151], v[188:191], v[12:15]
	v_mfma_f32_16x16x32_bf16 v[8:11], v[156:159], v[188:191], v[8:11]
	s_barrier
; #define PG8_STAGE(bufoff, gbase, voff) do { _Pragma("unroll") for (int _i = 0; _i < 2; ++_i) \
;         __builtin_amdgcn_global_load_lds((const unsigned*)((const char*)(gbase) + (voff)[_i]), (PG8_LAS unsigned*)(lds + (bufoff) + ldsw + _i * 8192), 16, 0, 0); } while (0)
; #define PG8_LDA(dst, b, h) do { _Pragma("unroll") for (int m = 0; m < 4; ++m) _Pragma("unroll") for (int k = 0; k < 2; ++k) dst[m][k] = *(const PG8_LAS bf16x8*)(lds + PG8_SA(b, h) + aoff + m * 2048 + k * 1024); } while (0)
; #define PG8_LDB(dst, b, h) do { _Pragma("unroll") for (int n = 0; n < 2; ++n) _Pragma("unroll") for (int k = 0; k < 2; ++k) dst[n][k] = *(const PG8_LAS bf16x8*)(lds + PG8_SB(b, h) + boff + n * 2048 + k * 1024); } while (0)
; #define PG8_MMA(ai, bj, At, Bt) do { __builtin_amdgcn_s_setprio(1); _Pragma("unroll") for (int m = 0; m < 4; ++m) _Pragma("unroll") for (int n = 0; n < 2; ++n) _Pragma("unroll") for (int k = 0; k < 2; ++k) \
;         acc[ai][bj][m][n] = __builtin_amdgcn_mfma_f32_16x16x32_bf16(Bt[n][k], At[m][k], acc[ai][bj][m][n], 0, 0, 0); __builtin_amdgcn_s_setprio(0); } while (0)
; #define PG8_WAIT_V(n) asm volatile("s_waitcnt vmcnt(" #n ")" ::: "memory")
; #define PG8_WAIT_L(n) asm volatile("s_waitcnt lgkmcnt(" #n ")" ::: "memory")
; #define PG8_BAR __builtin_amdgcn_s_barrier()
; #define PG8_SCHED __builtin_amdgcn_sched_barrier(0)
; template <class Epi, class Sched>
; __device__ __forceinline__ void gemm_phase(PG8_LAS unsigned char* lds, const Gemm g, const Sched& S, const Epi& E) {
;     ...
;             PG8_WAIT_V(6); PG8_BAR; PG8_MMA(1, 1, At, B1); PG8_BAR;
;             PG8_LDB(B0, 1, 0); PG8_SCHED; PG8_LDA(At, 1, 0); PG8_STAGE(PG8_SA(0, 1), a2 + hstep, voffA);
;             PG8_WAIT_L(8); PG8_BAR; PG8_WAIT_L(0); PG8_MMA(0, 0, At, B0); PG8_BAR; PG8_SCHED;
;             PG8_LDB(B1, 1, 1); PG8_STAGE(PG8_SB(1, 0), b3, voffB);
;             PG8_BAR; PG8_WAIT_L(0); PG8_MMA(0, 1, At, B1); PG8_BAR;
;             PG8_LDA(At, 1, 1); PG8_STAGE(PG8_SA(1, 0), a3, voffA);
;             PG8_BAR; PG8_WAIT_L(0); PG8_MMA(1, 0, At, B0); PG8_BAR; PG8_SCHED;
;             PG8_STAGE(PG8_SB(1, 1), b3 + hstep, voffB);
	s_add_u32 vcc_lo, s48, 0x40000
	s_addc_u32 vcc_hi, s49, 0
	s_add_i32 s42, s42, s56
	v_lshl_add_u64 v[144:145], vcc, 0, v[96:97]
	s_mov_b32 m0, s42
	s_nop 0
	global_load_lds_dwordx4 v[144:145], off
	v_lshl_add_u64 v[144:145], vcc, 0, v[130:131]
	s_add_i32 m0, s42, 0x2000
	s_nop 0
	global_load_lds_dwordx4 v[144:145], off
	s_waitcnt vmcnt(6)
	s_barrier
	v_mfma_f32_16x16x32_bf16 v[52:55], v[192:195], v[160:163], v[52:55]
	v_mfma_f32_16x16x32_bf16 v[48:51], v[200:203], v[160:163], v[48:51]
	v_mfma_f32_16x16x32_bf16 v[36:39], v[192:195], v[168:171], v[36:39]
	v_mfma_f32_16x16x32_bf16 v[32:35], v[200:203], v[168:171], v[32:35]
	v_mfma_f32_16x16x32_bf16 v[20:23], v[192:195], v[176:179], v[20:23]
	v_mfma_f32_16x16x32_bf16 v[16:19], v[200:203], v[176:179], v[16:19]
	v_mfma_f32_16x16x32_bf16 v[4:7], v[192:195], v[184:187], v[4:7]
	v_mfma_f32_16x16x32_bf16 v[0:3], v[200:203], v[184:187], v[0:3]
	v_mfma_f32_16x16x32_bf16 v[52:55], v[196:199], v[164:167], v[52:55]
	v_mfma_f32_16x16x32_bf16 v[48:51], v[208:211], v[164:167], v[48:51]
	v_mfma_f32_16x16x32_bf16 v[36:39], v[196:199], v[172:175], v[36:39]
	v_mfma_f32_16x16x32_bf16 v[32:35], v[208:211], v[172:175], v[32:35]
	v_mfma_f32_16x16x32_bf16 v[20:23], v[196:199], v[180:183], v[20:23]
	v_mfma_f32_16x16x32_bf16 v[16:19], v[208:211], v[180:183], v[16:19]
	v_mfma_f32_16x16x32_bf16 v[4:7], v[196:199], v[188:191], v[4:7]
	v_mfma_f32_16x16x32_bf16 v[0:3], v[208:211], v[188:191], v[0:3]
	s_add_i32 s42, 0, 0x18000
	v_add_u32_e32 v156, s42, v141
	s_barrier
	ds_read_b128 v[144:147], v156
	ds_read_b128 v[148:151], v156 offset:1024
	ds_read_b128 v[152:155], v156 offset:2048
	ds_read_b128 v[156:159], v156 offset:3072
	s_add_u32 s50, s50, 0x40000
	s_addc_u32 s51, s51, 0
	s_mov_b32 m0, s60
	v_lshl_add_u64 v[192:193], s[50:51], 0, v[134:135]
	ds_read_b128 v[160:163], v143 offset:32768
	ds_read_b128 v[168:171], v143 offset:34816
	ds_read_b128 v[176:179], v143 offset:36864
	ds_read_b128 v[184:187], v143 offset:38912
	ds_read_b128 v[164:167], v143 offset:33792
	ds_read_b128 v[172:175], v143 offset:35840
	ds_read_b128 v[180:183], v143 offset:37888
	ds_read_b128 v[188:191], v143 offset:39936
	global_load_lds_dwordx4 v[192:193], off
	v_lshl_add_u64 v[192:193], s[50:51], 0, v[132:133]
	s_mov_b32 m0, s61
	s_nop 0
	global_load_lds_dwordx4 v[192:193], off
	s_waitcnt lgkmcnt(8)
	s_barrier
	s_waitcnt lgkmcnt(7)
	v_mfma_f32_16x16x32_bf16 v[126:129], v[144:147], v[160:163], v[126:129]
	v_mfma_f32_16x16x32_bf16 v[122:125], v[152:155], v[160:163], v[122:125]
	s_waitcnt lgkmcnt(6)
	v_mfma_f32_16x16x32_bf16 v[110:113], v[144:147], v[168:171], v[110:113]
	v_mfma_f32_16x16x32_bf16 v[106:109], v[152:155], v[168:171], v[106:109]
	s_waitcnt lgkmcnt(5)
	v_mfma_f32_16x16x32_bf16 v[92:95], v[144:147], v[176:179], v[92:95]
	v_mfma_f32_16x16x32_bf16 v[88:91], v[152:155], v[176:179], v[88:91]
	s_waitcnt lgkmcnt(4)
	v_mfma_f32_16x16x32_bf16 v[76:79], v[144:147], v[184:187], v[76:79]
	v_mfma_f32_16x16x32_bf16 v[72:75], v[152:155], v[184:187], v[72:75]
	s_waitcnt lgkmcnt(3)
	v_mfma_f32_16x16x32_bf16 v[126:129], v[148:151], v[164:167], v[126:129]
	v_mfma_f32_16x16x32_bf16 v[122:125], v[156:159], v[164:167], v[122:125]
	s_waitcnt lgkmcnt(2)
	v_mfma_f32_16x16x32_bf16 v[110:113], v[148:151], v[172:175], v[110:113]
	v_mfma_f32_16x16x32_bf16 v[106:109], v[156:159], v[172:175], v[106:109]
	s_waitcnt lgkmcnt(1)
	v_mfma_f32_16x16x32_bf16 v[92:95], v[148:151], v[180:183], v[92:95]
	v_mfma_f32_16x16x32_bf16 v[88:91], v[156:159], v[180:183], v[88:91]
	s_waitcnt lgkmcnt(0)
	v_mfma_f32_16x16x32_bf16 v[76:79], v[148:151], v[188:191], v[76:79]
	v_mfma_f32_16x16x32_bf16 v[72:75], v[156:159], v[188:191], v[72:75]
	s_barrier
	s_add_i32 s43, 0, 0x1c000
	s_add_i32 s42, s42, s56
	v_add_u32_e32 v208, s43, v141
	v_lshl_add_u64 v[204:205], v[204:205], 0, s[2:3]
	s_mov_b32 m0, s42
	ds_read_b128 v[192:195], v208
	ds_read_b128 v[200:203], v208 offset:2048
	ds_read_b128 v[196:199], v208 offset:1024
	ds_read_b128 v[208:211], v208 offset:3072
	global_load_lds_dwordx4 v[204:205], off
	v_lshl_add_u64 v[204:205], v[212:213], 0, s[2:3]
	s_add_i32 m0, s42, 0x2000
	s_nop 0
	global_load_lds_dwordx4 v[204:205], off
	s_barrier
	s_waitcnt lgkmcnt(3)
	v_mfma_f32_16x16x32_bf16 v[118:121], v[192:195], v[160:163], v[118:121]
	s_waitcnt lgkmcnt(2)
	v_mfma_f32_16x16x32_bf16 v[114:117], v[200:203], v[160:163], v[114:117]
	v_mfma_f32_16x16x32_bf16 v[102:105], v[192:195], v[168:171], v[102:105]
	v_mfma_f32_16x16x32_bf16 v[98:101], v[200:203], v[168:171], v[98:101]
	v_mfma_f32_16x16x32_bf16 v[84:87], v[192:195], v[176:179], v[84:87]
	v_mfma_f32_16x16x32_bf16 v[80:83], v[200:203], v[176:179], v[80:83]
	v_mfma_f32_16x16x32_bf16 v[68:71], v[192:195], v[184:187], v[68:71]
	v_mfma_f32_16x16x32_bf16 v[64:67], v[200:203], v[184:187], v[64:67]
	s_waitcnt lgkmcnt(1)
	v_mfma_f32_16x16x32_bf16 v[118:121], v[196:199], v[164:167], v[118:121]
	s_waitcnt lgkmcnt(0)
	v_mfma_f32_16x16x32_bf16 v[114:117], v[208:211], v[164:167], v[114:117]
	v_mfma_f32_16x16x32_bf16 v[102:105], v[196:199], v[172:175], v[102:105]
	v_mfma_f32_16x16x32_bf16 v[98:101], v[208:211], v[172:175], v[98:101]
	v_mfma_f32_16x16x32_bf16 v[84:87], v[196:199], v[180:183], v[84:87]
	v_mfma_f32_16x16x32_bf16 v[80:83], v[208:211], v[180:183], v[80:83]
	v_mfma_f32_16x16x32_bf16 v[68:71], v[196:199], v[188:191], v[68:71]
	v_mfma_f32_16x16x32_bf16 v[64:67], v[208:211], v[188:191], v[64:67]
	s_mov_b32 m0, s62
	v_lshl_add_u64 v[204:205], v[214:215], 0, s[2:3]
	s_barrier
; #define PG8_STAGE(bufoff, gbase, voff) do { _Pragma("unroll") for (int _i = 0; _i < 2; ++_i) \
;         __builtin_amdgcn_global_load_lds((const unsigned*)((const char*)(gbase) + (voff)[_i]), (PG8_LAS unsigned*)(lds + (bufoff) + ldsw + _i * 8192), 16, 0, 0); } while (0)
; #define PG8_LDA(dst, b, h) do { _Pragma("unroll") for (int m = 0; m < 4; ++m) _Pragma("unroll") for (int k = 0; k < 2; ++k) dst[m][k] = *(const PG8_LAS bf16x8*)(lds + PG8_SA(b, h) + aoff + m * 2048 + k * 1024); } while (0)
; #define PG8_MMA(ai, bj, At, Bt) do { __builtin_amdgcn_s_setprio(1); _Pragma("unroll") for (int m = 0; m < 4; ++m) _Pragma("unroll") for (int n = 0; n < 2; ++n) _Pragma("unroll") for (int k = 0; k < 2; ++k) \
;         acc[ai][bj][m][n] = __builtin_amdgcn_mfma_f32_16x16x32_bf16(Bt[n][k], At[m][k], acc[ai][bj][m][n], 0, 0, 0); __builtin_amdgcn_s_setprio(0); } while (0)
; #define PG8_WAIT_V(n) asm volatile("s_waitcnt vmcnt(" #n ")" ::: "memory")
; #define PG8_WAIT_L(n) asm volatile("s_waitcnt lgkmcnt(" #n ")" ::: "memory")
; template <class Epi, class Sched>
; __device__ __forceinline__ void gemm_phase(PG8_LAS unsigned char* lds, const Gemm g, const Sched& S, const Epi& E) {
;     ...
;             PG8_LDA(At, 1, 1); PG8_STAGE(PG8_SA(1, 0), a3, voffA);
;             PG8_BAR; PG8_WAIT_L(0); PG8_MMA(1, 0, At, B0); PG8_BAR; PG8_SCHED;
;             PG8_STAGE(PG8_SB(1, 1), b3 + hstep, voffB);
;             PG8_WAIT_V(6); PG8_BAR; PG8_MMA(1, 1, At, B1); PG8_BAR;
;         }
;   DEV void operator()(const f32x4 (&acc)[2][2][4][2], const pg8::Unit& u, int wr, int wc, int fr, int fq) const {
;     const int row0 = u.pm * 256 + wr * 64 + fr, col0 = u.pn * 256 + wc * 32 + 8 * fq;
; #pragma unroll
;     for (int ai = 0; ai < 2; ++ai)
; #pragma unroll
;       for (int m = 0; m < 4; ++m) {
;         const int row = row0 + ai * 128 + m * 16;
; #pragma unroll
;         for (int bj = 0; bj < 2; ++bj) {
;           float v[8];
; #pragma unroll
;           for (int j = 0; j < 4; ++j) {
;             const float r0 = fmaxf(acc[ai][bj][m][0][j], 0.f), r1 = fmaxf(acc[ai][bj][m][1][j], 0.f);
;             v[j] = r0 * r0; v[4 + j] = r1 * r1;
;           }
;           u32x4 o;
;           o[0] = pk2(v[0], v[1]); o[1] = pk2(v[2], v[3]); o[2] = pk2(v[4], v[5]); o[3] = pk2(v[6], v[7]);
;           *(u32x4*)(HID + (size_t)row * 4096 + col0 + bj * 128) = o;
;         }
;       }
	ds_read_b128 v[160:163], v143 offset:49152
	ds_read_b128 v[168:171], v143 offset:51200
	ds_read_b128 v[176:179], v143 offset:53248
	ds_read_b128 v[184:187], v143 offset:55296
	ds_read_b128 v[164:167], v143 offset:50176
	ds_read_b128 v[172:175], v143 offset:52224
	ds_read_b128 v[180:183], v143 offset:54272
	ds_read_b128 v[188:191], v143 offset:56320
	global_load_lds_dwordx4 v[204:205], off
	v_lshl_add_u64 v[204:205], v[216:217], 0, s[2:3]
	s_mov_b32 m0, s63
	s_nop 0
	global_load_lds_dwordx4 v[204:205], off
	s_barrier
	s_waitcnt lgkmcnt(7)
	v_mfma_f32_16x16x32_bf16 v[60:63], v[144:147], v[160:163], v[60:63]
	v_mfma_f32_16x16x32_bf16 v[56:59], v[152:155], v[160:163], v[56:59]
	s_waitcnt lgkmcnt(6)
	v_mfma_f32_16x16x32_bf16 v[44:47], v[144:147], v[168:171], v[44:47]
	v_mfma_f32_16x16x32_bf16 v[40:43], v[152:155], v[168:171], v[40:43]
	s_waitcnt lgkmcnt(5)
	v_mfma_f32_16x16x32_bf16 v[28:31], v[144:147], v[176:179], v[28:31]
	v_mfma_f32_16x16x32_bf16 v[24:27], v[152:155], v[176:179], v[24:27]
	s_waitcnt lgkmcnt(4)
	v_mfma_f32_16x16x32_bf16 v[12:15], v[144:147], v[184:187], v[12:15]
	v_mfma_f32_16x16x32_bf16 v[8:11], v[152:155], v[184:187], v[8:11]
	s_waitcnt lgkmcnt(3)
	v_mfma_f32_16x16x32_bf16 v[60:63], v[148:151], v[164:167], v[60:63]
	v_mfma_f32_16x16x32_bf16 v[56:59], v[156:159], v[164:167], v[56:59]
	s_waitcnt lgkmcnt(2)
	v_mfma_f32_16x16x32_bf16 v[44:47], v[148:151], v[172:175], v[44:47]
	v_mfma_f32_16x16x32_bf16 v[40:43], v[156:159], v[172:175], v[40:43]
	s_waitcnt lgkmcnt(1)
	v_mfma_f32_16x16x32_bf16 v[28:31], v[148:151], v[180:183], v[28:31]
	v_mfma_f32_16x16x32_bf16 v[24:27], v[156:159], v[180:183], v[24:27]
	s_waitcnt lgkmcnt(0)
	v_mfma_f32_16x16x32_bf16 v[12:15], v[148:151], v[188:191], v[12:15]
	v_mfma_f32_16x16x32_bf16 v[8:11], v[156:159], v[188:191], v[8:11]
	s_barrier
	s_add_u32 s48, s48, 0x40080
	s_addc_u32 s49, s49, 0
	s_add_i32 s42, s43, s56
	v_lshl_add_u64 v[144:145], s[48:49], 0, v[96:97]
	s_mov_b32 m0, s42
	s_nop 0
	global_load_lds_dwordx4 v[144:145], off
	v_lshl_add_u64 v[144:145], s[48:49], 0, v[130:131]
	s_add_i32 m0, s42, 0x2000
	s_nop 0
	global_load_lds_dwordx4 v[144:145], off
	s_waitcnt vmcnt(6)
	s_barrier
	v_mfma_f32_16x16x32_bf16 v[52:55], v[192:195], v[160:163], v[52:55]
	v_mfma_f32_16x16x32_bf16 v[48:51], v[200:203], v[160:163], v[48:51]
	v_mfma_f32_16x16x32_bf16 v[36:39], v[192:195], v[168:171], v[36:39]
	v_mfma_f32_16x16x32_bf16 v[32:35], v[200:203], v[168:171], v[32:35]
	v_mfma_f32_16x16x32_bf16 v[20:23], v[192:195], v[176:179], v[20:23]
	v_mfma_f32_16x16x32_bf16 v[16:19], v[200:203], v[176:179], v[16:19]
	v_mfma_f32_16x16x32_bf16 v[4:7], v[192:195], v[184:187], v[4:7]
	v_mfma_f32_16x16x32_bf16 v[0:3], v[200:203], v[184:187], v[0:3]
	v_mfma_f32_16x16x32_bf16 v[52:55], v[196:199], v[164:167], v[52:55]
	v_mfma_f32_16x16x32_bf16 v[48:51], v[208:211], v[164:167], v[48:51]
	v_mfma_f32_16x16x32_bf16 v[36:39], v[196:199], v[172:175], v[36:39]
	v_mfma_f32_16x16x32_bf16 v[32:35], v[208:211], v[172:175], v[32:35]
	v_mfma_f32_16x16x32_bf16 v[20:23], v[196:199], v[180:183], v[20:23]
	v_mfma_f32_16x16x32_bf16 v[16:19], v[208:211], v[180:183], v[16:19]
	v_mfma_f32_16x16x32_bf16 v[4:7], v[196:199], v[188:191], v[4:7]
	v_mfma_f32_16x16x32_bf16 v[0:3], v[208:211], v[188:191], v[0:3]
	s_add_i32 s70, s70, 2
	s_add_u32 s46, s46, 0x100
	s_addc_u32 s47, s47, 0
	s_add_u32 s68, s68, 0x100
	s_addc_u32 s69, s69, 0
	s_cmp_gt_u32 s70, 13
	s_barrier
	s_cbranch_scc0 .LBB0_65
	v_lshl_add_u32 v144, s44, 8, v140
	v_max_f32_e32 v126, v126, v126
	v_max_f32_e32 v122, v122, v122
	v_max_f32_e32 v127, v127, v127
	v_max_f32_e32 v123, v123, v123
	v_max_f32_e32 v128, v128, v128
	v_max_f32_e32 v129, v129, v129
	v_lshl_or_b32 v146, s65, 8, v142
	v_ashrrev_i32_e32 v145, 31, v144
	v_max_f32_e32 v126, 0, v126
	v_max_f32_e32 v122, 0, v122
	v_max_f32_e32 v127, 0, v127
	v_max_f32_e32 v123, 0, v123
	v_max_f32_e32 v128, 0, v128
	v_max_f32_e32 v124, v124, v124
	v_max_f32_e32 v129, 0, v129
	v_max_f32_e32 v125, v125, v125
	v_readlane_b32 s42, v251, 49
	v_ashrrev_i32_e32 v147, 31, v146
	v_lshlrev_b64 v[148:149], 13, v[144:145]
	v_pk_mul_f32 v[126:127], v[126:127], v[126:127]
	v_pk_mul_f32 v[122:123], v[122:123], v[122:123]
	v_max_f32_e32 v124, 0, v124
	v_max_f32_e32 v125, 0, v125
	v_pk_mul_f32 v[128:129], v[128:129], v[128:129]
	v_readlane_b32 s43, v251, 50
	v_pk_mul_f32 v[150:151], v[124:125], v[124:125]
	v_cvt_pk_bf16_f32 v124, v126, v127
	v_cvt_pk_bf16_f32 v125, v128, v129
	v_cvt_pk_bf16_f32 v126, v122, v123
	v_lshl_add_u64 v[122:123], s[42:43], 0, v[148:149]
	v_lshlrev_b64 v[128:129], 1, v[146:147]
	v_max_f32_e32 v114, v114, v114
	v_max_f32_e32 v115, v115, v115
	v_cvt_pk_bf16_f32 v127, v150, v151
	v_lshl_add_u64 v[122:123], v[122:123], 0, v[128:129]
	v_max_f32_e32 v114, 0, v114
	v_max_f32_e32 v115, 0, v115
	global_store_dwordx4 v[122:123], v[124:127], off
	v_max_f32_e32 v118, v118, v118
	v_max_f32_e32 v119, v119, v119
	v_pk_mul_f32 v[124:125], v[114:115], v[114:115]
	v_max_f32_e32 v115, v116, v116
	v_max_f32_e32 v114, v120, v120
	v_max_f32_e32 v116, 0, v115
	v_max_f32_e32 v115, v121, v121
	v_max_f32_e32 v117, v117, v117
	v_max_f32_e32 v118, 0, v118
	v_max_f32_e32 v119, 0, v119
	v_max_f32_e32 v114, 0, v114
	v_max_f32_e32 v115, 0, v115
	v_max_f32_e32 v117, 0, v117
	v_pk_mul_f32 v[118:119], v[118:119], v[118:119]
	v_pk_mul_f32 v[120:121], v[114:115], v[114:115]
	v_pk_mul_f32 v[126:127], v[116:117], v[116:117]
	v_max_f32_e32 v106, v106, v106
	v_max_f32_e32 v107, v107, v107
	v_cvt_pk_bf16_f32 v114, v118, v119
	v_cvt_pk_bf16_f32 v115, v120, v121
	v_cvt_pk_bf16_f32 v116, v124, v125
	v_cvt_pk_bf16_f32 v117, v126, v127
	v_max_f32_e32 v106, 0, v106
	v_max_f32_e32 v107, 0, v107
;   DEV void operator()(const f32x4 (&acc)[2][2][4][2], const pg8::Unit& u, int wr, int wc, int fr, int fq) const {
;     ...
;     for (int ai = 0; ai < 2; ++ai)
; #pragma unroll
;       for (int m = 0; m < 4; ++m) {
;         const int row = row0 + ai * 128 + m * 16;
; #pragma unroll
;         for (int bj = 0; bj < 2; ++bj) {
;           float v[8];
; #pragma unroll
;           for (int j = 0; j < 4; ++j) {
;             const float r0 = fmaxf(acc[ai][bj][m][0][j], 0.f), r1 = fmaxf(acc[ai][bj][m][1][j], 0.f);
;             v[j] = r0 * r0; v[4 + j] = r1 * r1;
;           }
;           u32x4 o;
;           o[0] = pk2(v[0], v[1]); o[1] = pk2(v[2], v[3]); o[2] = pk2(v[4], v[5]); o[3] = pk2(v[6], v[7]);
;           *(u32x4*)(HID + (size_t)row * 4096 + col0 + bj * 128) = o;
;         }
;       }
	global_store_dwordx4 v[122:123], v[114:117], off offset:256
	v_max_f32_e32 v110, v110, v110
	v_max_f32_e32 v111, v111, v111
	v_or_b32_e32 v114, 16, v144
	v_pk_mul_f32 v[116:117], v[106:107], v[106:107]
	v_max_f32_e32 v107, v108, v108
	v_ashrrev_i32_e32 v115, 31, v114
	v_max_f32_e32 v110, 0, v110
	v_max_f32_e32 v111, 0, v111
	v_max_f32_e32 v106, v112, v112
	v_max_f32_e32 v108, 0, v107
	v_max_f32_e32 v107, v113, v113
	v_max_f32_e32 v109, v109, v109
	v_lshlrev_b64 v[114:115], 13, v[114:115]
	v_pk_mul_f32 v[110:111], v[110:111], v[110:111]
	v_max_f32_e32 v106, 0, v106
	v_max_f32_e32 v107, 0, v107
	v_max_f32_e32 v109, 0, v109
	v_pk_mul_f32 v[112:113], v[106:107], v[106:107]
	v_pk_mul_f32 v[118:119], v[108:109], v[108:109]
	v_cvt_pk_bf16_f32 v106, v110, v111
	v_lshl_add_u64 v[110:111], s[42:43], 0, v[114:115]
	v_max_f32_e32 v98, v98, v98
	v_max_f32_e32 v99, v99, v99
	v_cvt_pk_bf16_f32 v107, v112, v113
	v_cvt_pk_bf16_f32 v108, v116, v117
	v_cvt_pk_bf16_f32 v109, v118, v119
	v_lshl_add_u64 v[110:111], v[110:111], 0, v[128:129]
	v_max_f32_e32 v98, 0, v98
	v_max_f32_e32 v99, 0, v99
	global_store_dwordx4 v[110:111], v[106:109], off
	v_max_f32_e32 v102, v102, v102
	v_max_f32_e32 v103, v103, v103
	v_pk_mul_f32 v[106:107], v[98:99], v[98:99]
	v_max_f32_e32 v99, v100, v100
	v_max_f32_e32 v98, v104, v104
	v_max_f32_e32 v100, 0, v99
	v_max_f32_e32 v99, v105, v105
	v_max_f32_e32 v101, v101, v101
	v_max_f32_e32 v102, 0, v102
	v_max_f32_e32 v103, 0, v103
	v_max_f32_e32 v98, 0, v98
	v_max_f32_e32 v99, 0, v99
	v_max_f32_e32 v101, 0, v101
	v_pk_mul_f32 v[102:103], v[102:103], v[102:103]
	v_pk_mul_f32 v[104:105], v[98:99], v[98:99]
	v_pk_mul_f32 v[108:109], v[100:101], v[100:101]
	v_max_f32_e32 v88, v88, v88
	v_max_f32_e32 v89, v89, v89
	v_cvt_pk_bf16_f32 v98, v102, v103
	v_cvt_pk_bf16_f32 v99, v104, v105
	v_cvt_pk_bf16_f32 v100, v106, v107
	v_cvt_pk_bf16_f32 v101, v108, v109
	v_max_f32_e32 v88, 0, v88
	v_max_f32_e32 v89, 0, v89
	global_store_dwordx4 v[110:111], v[98:101], off offset:256
	v_max_f32_e32 v92, v92, v92
	v_max_f32_e32 v93, v93, v93
	v_or_b32_e32 v98, 32, v144
	v_pk_mul_f32 v[100:101], v[88:89], v[88:89]
	v_max_f32_e32 v89, v90, v90
	v_ashrrev_i32_e32 v99, 31, v98
	v_max_f32_e32 v92, 0, v92
	v_max_f32_e32 v93, 0, v93
	v_max_f32_e32 v88, v94, v94
	v_max_f32_e32 v90, 0, v89
	v_max_f32_e32 v89, v95, v95
	v_max_f32_e32 v91, v91, v91
	v_lshlrev_b64 v[98:99], 13, v[98:99]
	v_pk_mul_f32 v[92:93], v[92:93], v[92:93]
	v_max_f32_e32 v88, 0, v88
	v_max_f32_e32 v89, 0, v89
	v_max_f32_e32 v91, 0, v91
	v_pk_mul_f32 v[94:95], v[88:89], v[88:89]
	v_pk_mul_f32 v[102:103], v[90:91], v[90:91]
	v_cvt_pk_bf16_f32 v88, v92, v93
	v_lshl_add_u64 v[92:93], s[42:43], 0, v[98:99]
	v_max_f32_e32 v80, v80, v80
	v_max_f32_e32 v81, v81, v81
	v_cvt_pk_bf16_f32 v89, v94, v95
	v_cvt_pk_bf16_f32 v90, v100, v101
	v_cvt_pk_bf16_f32 v91, v102, v103
	v_lshl_add_u64 v[92:93], v[92:93], 0, v[128:129]
	v_max_f32_e32 v80, 0, v80
	v_max_f32_e32 v81, 0, v81
	global_store_dwordx4 v[92:93], v[88:91], off
	v_max_f32_e32 v84, v84, v84
	v_max_f32_e32 v85, v85, v85
	v_pk_mul_f32 v[88:89], v[80:81], v[80:81]
	v_max_f32_e32 v81, v82, v82
	v_max_f32_e32 v80, v86, v86
	v_max_f32_e32 v82, 0, v81
	v_max_f32_e32 v81, v87, v87
	v_max_f32_e32 v83, v83, v83
	v_max_f32_e32 v84, 0, v84
	v_max_f32_e32 v85, 0, v85
	v_max_f32_e32 v80, 0, v80
	v_max_f32_e32 v81, 0, v81
	v_max_f32_e32 v83, 0, v83
	v_pk_mul_f32 v[84:85], v[84:85], v[84:85]
	v_pk_mul_f32 v[86:87], v[80:81], v[80:81]
	v_pk_mul_f32 v[90:91], v[82:83], v[82:83]
	v_max_f32_e32 v72, v72, v72
	v_max_f32_e32 v73, v73, v73
	v_cvt_pk_bf16_f32 v80, v84, v85
	v_cvt_pk_bf16_f32 v81, v86, v87
	v_cvt_pk_bf16_f32 v82, v88, v89
	v_cvt_pk_bf16_f32 v83, v90, v91
	v_max_f32_e32 v72, 0, v72
	v_max_f32_e32 v73, 0, v73
	global_store_dwordx4 v[92:93], v[80:83], off offset:256
	v_max_f32_e32 v76, v76, v76
	v_max_f32_e32 v77, v77, v77
	v_or_b32_e32 v80, 48, v144
	v_pk_mul_f32 v[82:83], v[72:73], v[72:73]
	v_max_f32_e32 v73, v74, v74
	v_ashrrev_i32_e32 v81, 31, v80
	v_max_f32_e32 v76, 0, v76
	v_max_f32_e32 v77, 0, v77
	v_max_f32_e32 v72, v78, v78
	v_max_f32_e32 v74, 0, v73
	v_max_f32_e32 v73, v79, v79
	v_max_f32_e32 v75, v75, v75
	v_lshlrev_b64 v[80:81], 13, v[80:81]
	v_pk_mul_f32 v[76:77], v[76:77], v[76:77]
	v_max_f32_e32 v72, 0, v72
	v_max_f32_e32 v73, 0, v73
	v_max_f32_e32 v75, 0, v75
	v_pk_mul_f32 v[78:79], v[72:73], v[72:73]
	v_pk_mul_f32 v[84:85], v[74:75], v[74:75]
	v_cvt_pk_bf16_f32 v72, v76, v77
	v_lshl_add_u64 v[76:77], s[42:43], 0, v[80:81]
	v_max_f32_e32 v64, v64, v64
	v_max_f32_e32 v65, v65, v65
	v_cvt_pk_bf16_f32 v73, v78, v79
	v_cvt_pk_bf16_f32 v74, v82, v83
	v_cvt_pk_bf16_f32 v75, v84, v85
	v_lshl_add_u64 v[76:77], v[76:77], 0, v[128:129]
	v_max_f32_e32 v64, 0, v64
	v_max_f32_e32 v65, 0, v65
	global_store_dwordx4 v[76:77], v[72:75], off
	v_max_f32_e32 v68, v68, v68
	v_max_f32_e32 v69, v69, v69
	v_pk_mul_f32 v[72:73], v[64:65], v[64:65]
	v_max_f32_e32 v65, v66, v66
	v_max_f32_e32 v64, v70, v70
	v_max_f32_e32 v66, 0, v65
	v_max_f32_e32 v65, v71, v71
	v_max_f32_e32 v67, v67, v67
	v_max_f32_e32 v68, 0, v68
	v_max_f32_e32 v69, 0, v69
	v_max_f32_e32 v64, 0, v64
	v_max_f32_e32 v65, 0, v65
	v_max_f32_e32 v67, 0, v67
	v_pk_mul_f32 v[68:69], v[68:69], v[68:69]
	v_pk_mul_f32 v[70:71], v[64:65], v[64:65]
	v_pk_mul_f32 v[74:75], v[66:67], v[66:67]
	v_max_f32_e32 v56, v56, v56
	v_max_f32_e32 v57, v57, v57
	v_cvt_pk_bf16_f32 v64, v68, v69
	v_cvt_pk_bf16_f32 v65, v70, v71
	v_cvt_pk_bf16_f32 v66, v72, v73
	v_cvt_pk_bf16_f32 v67, v74, v75
	v_max_f32_e32 v56, 0, v56
	v_max_f32_e32 v57, 0, v57
	global_store_dwordx4 v[76:77], v[64:67], off offset:256
	v_max_f32_e32 v60, v60, v60
;   DEV void operator()(const f32x4 (&acc)[2][2][4][2], const pg8::Unit& u, int wr, int wc, int fr, int fq) const {
;     ...
;     for (int ai = 0; ai < 2; ++ai)
; #pragma unroll
;       for (int m = 0; m < 4; ++m) {
;         const int row = row0 + ai * 128 + m * 16;
; #pragma unroll
;         for (int bj = 0; bj < 2; ++bj) {
;           float v[8];
; #pragma unroll
;           for (int j = 0; j < 4; ++j) {
;             const float r0 = fmaxf(acc[ai][bj][m][0][j], 0.f), r1 = fmaxf(acc[ai][bj][m][1][j], 0.f);
;             v[j] = r0 * r0; v[4 + j] = r1 * r1;
;           }
;           u32x4 o;
;           o[0] = pk2(v[0], v[1]); o[1] = pk2(v[2], v[3]); o[2] = pk2(v[4], v[5]); o[3] = pk2(v[6], v[7]);
;           *(u32x4*)(HID + (size_t)row * 4096 + col0 + bj * 128) = o;
;         }
;       }
	v_max_f32_e32 v61, v61, v61
	v_pk_mul_f32 v[64:65], v[56:57], v[56:57]
	v_max_f32_e32 v57, v58, v58
	v_max_f32_e32 v56, v62, v62
	v_max_f32_e32 v58, 0, v57
	v_max_f32_e32 v57, v63, v63
	v_max_f32_e32 v56, 0, v56
	v_max_f32_e32 v57, 0, v57
	v_max_f32_e32 v59, v59, v59
	v_max_f32_e32 v60, 0, v60
	v_max_f32_e32 v61, 0, v61
	v_max_f32_e32 v59, 0, v59
	v_pk_mul_f32 v[62:63], v[56:57], v[56:57]
	s_mov_b32 s1, 0x100000
	v_pk_mul_f32 v[60:61], v[60:61], v[60:61]
	v_pk_mul_f32 v[66:67], v[58:59], v[58:59]
	v_cvt_pk_bf16_f32 v57, v62, v63
	v_add_co_u32_e32 v62, vcc, s1, v122
	v_max_f32_e32 v48, v48, v48
	v_max_f32_e32 v49, v49, v49
	v_cvt_pk_bf16_f32 v56, v60, v61
	v_cvt_pk_bf16_f32 v58, v64, v65
	v_cvt_pk_bf16_f32 v59, v66, v67
	v_addc_co_u32_e32 v63, vcc, 0, v123, vcc
	v_max_f32_e32 v48, 0, v48
	v_max_f32_e32 v49, 0, v49
	global_store_dwordx4 v[62:63], v[56:59], off
	v_max_f32_e32 v52, v52, v52
	v_max_f32_e32 v53, v53, v53
	v_pk_mul_f32 v[56:57], v[48:49], v[48:49]
	v_max_f32_e32 v49, v50, v50
	v_max_f32_e32 v48, v54, v54
	v_max_f32_e32 v50, 0, v49
	v_max_f32_e32 v49, v55, v55
	v_max_f32_e32 v51, v51, v51
	v_max_f32_e32 v52, 0, v52
	v_max_f32_e32 v53, 0, v53
	v_max_f32_e32 v48, 0, v48
	v_max_f32_e32 v49, 0, v49
	v_max_f32_e32 v51, 0, v51
	s_mov_b64 s[46:47], 0x100000
	v_pk_mul_f32 v[52:53], v[52:53], v[52:53]
	v_pk_mul_f32 v[54:55], v[48:49], v[48:49]
	v_pk_mul_f32 v[58:59], v[50:51], v[50:51]
	v_max_f32_e32 v40, v40, v40
	v_max_f32_e32 v41, v41, v41
	v_lshl_add_u64 v[60:61], v[122:123], 0, s[46:47]
	v_cvt_pk_bf16_f32 v48, v52, v53
	v_cvt_pk_bf16_f32 v49, v54, v55
	v_cvt_pk_bf16_f32 v50, v56, v57
	v_cvt_pk_bf16_f32 v51, v58, v59
	v_max_f32_e32 v40, 0, v40
	v_max_f32_e32 v41, 0, v41
	global_store_dwordx4 v[60:61], v[48:51], off offset:256
	v_max_f32_e32 v44, v44, v44
	v_max_f32_e32 v45, v45, v45
	v_pk_mul_f32 v[48:49], v[40:41], v[40:41]
	v_max_f32_e32 v41, v42, v42
	v_max_f32_e32 v40, v46, v46
	v_max_f32_e32 v42, 0, v41
	v_max_f32_e32 v41, v47, v47
	v_max_f32_e32 v40, 0, v40
	v_max_f32_e32 v41, 0, v41
	v_max_f32_e32 v43, v43, v43
	v_max_f32_e32 v44, 0, v44
	v_max_f32_e32 v45, 0, v45
	v_max_f32_e32 v43, 0, v43
	v_pk_mul_f32 v[46:47], v[40:41], v[40:41]
	s_mov_b32 s1, 0x120000
	v_pk_mul_f32 v[44:45], v[44:45], v[44:45]
	v_pk_mul_f32 v[50:51], v[42:43], v[42:43]
	v_cvt_pk_bf16_f32 v41, v46, v47
	v_add_co_u32_e32 v46, vcc, s1, v122
	v_max_f32_e32 v32, v32, v32
	v_max_f32_e32 v33, v33, v33
	v_cvt_pk_bf16_f32 v40, v44, v45
	v_cvt_pk_bf16_f32 v42, v48, v49
	v_cvt_pk_bf16_f32 v43, v50, v51
	v_addc_co_u32_e32 v47, vcc, 0, v123, vcc
	v_max_f32_e32 v32, 0, v32
	v_max_f32_e32 v33, 0, v33
	global_store_dwordx4 v[46:47], v[40:43], off
	v_max_f32_e32 v36, v36, v36
	v_max_f32_e32 v37, v37, v37
	v_pk_mul_f32 v[40:41], v[32:33], v[32:33]
	v_max_f32_e32 v33, v34, v34
	v_max_f32_e32 v32, v38, v38
	v_max_f32_e32 v34, 0, v33
	v_max_f32_e32 v33, v39, v39
	v_max_f32_e32 v35, v35, v35
	v_max_f32_e32 v36, 0, v36
	v_max_f32_e32 v37, 0, v37
	v_max_f32_e32 v32, 0, v32
	v_max_f32_e32 v33, 0, v33
	v_max_f32_e32 v35, 0, v35
	s_mov_b64 s[46:47], 0x120000
	v_pk_mul_f32 v[36:37], v[36:37], v[36:37]
	v_pk_mul_f32 v[38:39], v[32:33], v[32:33]
	v_pk_mul_f32 v[42:43], v[34:35], v[34:35]
	v_max_f32_e32 v24, v24, v24
	v_max_f32_e32 v25, v25, v25
	v_lshl_add_u64 v[44:45], v[122:123], 0, s[46:47]
	v_cvt_pk_bf16_f32 v32, v36, v37
	v_cvt_pk_bf16_f32 v33, v38, v39
	v_cvt_pk_bf16_f32 v34, v40, v41
	v_cvt_pk_bf16_f32 v35, v42, v43
	v_max_f32_e32 v24, 0, v24
	v_max_f32_e32 v25, 0, v25
	global_store_dwordx4 v[44:45], v[32:35], off offset:256
	v_max_f32_e32 v28, v28, v28
	v_max_f32_e32 v29, v29, v29
; #define PG8_WAIT_V(n) asm volatile("s_waitcnt vmcnt(" #n ")" ::: "memory")
; #define PG8_BAR __builtin_amdgcn_s_barrier()
; template <class Epi, class Sched>
; __device__ __forceinline__ void gemm_phase(PG8_LAS unsigned char* lds, const Gemm g, const Sched& S, const Epi& E) {
;     ...
;         if (!has_next) break;
; #pragma unroll
;         for (int a = 0; a < 2; ++a)
; #pragma unroll
;             for (int b = 0; b < 2; ++b)
; #pragma unroll
;                 for (int m = 0; m < 4; ++m)
; #pragma unroll
;                     for (int n = 0; n < 2; ++n) acc[a][b][m][n] = (f32x4){0.f, 0.f, 0.f, 0.f};
;         cur = nxt; cA = nA; cB = nB; ++ui;
;     }
;     PG8_WAIT_V(0);
;     if (wr == 0) PG8_BAR;
;     PG8_BAR;
;   DEV void operator()(const f32x4 (&acc)[2][2][4][2], const pg8::Unit& u, int wr, int wc, int fr, int fq) const {
;     ...
;     for (int ai = 0; ai < 2; ++ai)
; #pragma unroll
;       for (int m = 0; m < 4; ++m) {
;         const int row = row0 + ai * 128 + m * 16;
; #pragma unroll
;         for (int bj = 0; bj < 2; ++bj) {
;           float v[8];
; #pragma unroll
;           for (int j = 0; j < 4; ++j) {
;             const float r0 = fmaxf(acc[ai][bj][m][0][j], 0.f), r1 = fmaxf(acc[ai][bj][m][1][j], 0.f);
;             v[j] = r0 * r0; v[4 + j] = r1 * r1;
;           }
;           u32x4 o;
;           o[0] = pk2(v[0], v[1]); o[1] = pk2(v[2], v[3]); o[2] = pk2(v[4], v[5]); o[3] = pk2(v[6], v[7]);
;           *(u32x4*)(HID + (size_t)row * 4096 + col0 + bj * 128) = o;
;         }
;       }
	v_pk_mul_f32 v[32:33], v[24:25], v[24:25]
	v_max_f32_e32 v25, v26, v26
	v_max_f32_e32 v24, v30, v30
	v_max_f32_e32 v26, 0, v25
	v_max_f32_e32 v25, v31, v31
	v_max_f32_e32 v24, 0, v24
	v_max_f32_e32 v25, 0, v25
	v_max_f32_e32 v27, v27, v27
	v_max_f32_e32 v28, 0, v28
	v_max_f32_e32 v29, 0, v29
	v_max_f32_e32 v27, 0, v27
	v_pk_mul_f32 v[30:31], v[24:25], v[24:25]
	s_mov_b32 s1, 0x140000
	v_pk_mul_f32 v[28:29], v[28:29], v[28:29]
	v_pk_mul_f32 v[34:35], v[26:27], v[26:27]
	v_cvt_pk_bf16_f32 v25, v30, v31
	v_add_co_u32_e32 v30, vcc, s1, v122
	v_max_f32_e32 v16, v16, v16
	v_max_f32_e32 v17, v17, v17
	v_cvt_pk_bf16_f32 v24, v28, v29
	v_cvt_pk_bf16_f32 v26, v32, v33
	v_cvt_pk_bf16_f32 v27, v34, v35
	v_addc_co_u32_e32 v31, vcc, 0, v123, vcc
	v_max_f32_e32 v16, 0, v16
	v_max_f32_e32 v17, 0, v17
	global_store_dwordx4 v[30:31], v[24:27], off
	v_max_f32_e32 v20, v20, v20
	v_max_f32_e32 v21, v21, v21
	v_pk_mul_f32 v[24:25], v[16:17], v[16:17]
	v_max_f32_e32 v17, v18, v18
	v_max_f32_e32 v16, v22, v22
	v_max_f32_e32 v18, 0, v17
	v_max_f32_e32 v17, v23, v23
	v_max_f32_e32 v19, v19, v19
	v_max_f32_e32 v20, 0, v20
	v_max_f32_e32 v21, 0, v21
	v_max_f32_e32 v16, 0, v16
	v_max_f32_e32 v17, 0, v17
	v_max_f32_e32 v19, 0, v19
	s_mov_b64 s[46:47], 0x140000
	v_pk_mul_f32 v[20:21], v[20:21], v[20:21]
	v_pk_mul_f32 v[22:23], v[16:17], v[16:17]
	v_pk_mul_f32 v[26:27], v[18:19], v[18:19]
	v_max_f32_e32 v8, v8, v8
	v_max_f32_e32 v9, v9, v9
	v_lshl_add_u64 v[28:29], v[122:123], 0, s[46:47]
	v_cvt_pk_bf16_f32 v16, v20, v21
	v_cvt_pk_bf16_f32 v17, v22, v23
	v_cvt_pk_bf16_f32 v18, v24, v25
	v_cvt_pk_bf16_f32 v19, v26, v27
	v_max_f32_e32 v8, 0, v8
	v_max_f32_e32 v9, 0, v9
	global_store_dwordx4 v[28:29], v[16:19], off offset:256
	v_max_f32_e32 v12, v12, v12
	v_max_f32_e32 v13, v13, v13
	v_pk_mul_f32 v[16:17], v[8:9], v[8:9]
	v_max_f32_e32 v9, v10, v10
	v_max_f32_e32 v8, v14, v14
	v_max_f32_e32 v10, 0, v9
	v_max_f32_e32 v9, v15, v15
	v_max_f32_e32 v8, 0, v8
	v_max_f32_e32 v9, 0, v9
	v_max_f32_e32 v11, v11, v11
	v_max_f32_e32 v12, 0, v12
	v_max_f32_e32 v13, 0, v13
	v_max_f32_e32 v11, 0, v11
	v_pk_mul_f32 v[14:15], v[8:9], v[8:9]
	s_mov_b32 s1, 0x160000
	v_pk_mul_f32 v[12:13], v[12:13], v[12:13]
	v_pk_mul_f32 v[18:19], v[10:11], v[10:11]
	v_cvt_pk_bf16_f32 v9, v14, v15
	v_add_co_u32_e32 v14, vcc, s1, v122
	v_max_f32_e32 v0, v0, v0
	v_max_f32_e32 v1, v1, v1
	v_cvt_pk_bf16_f32 v8, v12, v13
	v_cvt_pk_bf16_f32 v10, v16, v17
	v_cvt_pk_bf16_f32 v11, v18, v19
	v_addc_co_u32_e32 v15, vcc, 0, v123, vcc
	v_max_f32_e32 v0, 0, v0
	v_max_f32_e32 v1, 0, v1
	global_store_dwordx4 v[14:15], v[8:11], off
	v_max_f32_e32 v4, v4, v4
	v_max_f32_e32 v5, v5, v5
	v_pk_mul_f32 v[8:9], v[0:1], v[0:1]
	v_max_f32_e32 v1, v2, v2
	v_max_f32_e32 v0, v6, v6
	v_max_f32_e32 v2, 0, v1
	v_max_f32_e32 v1, v7, v7
	v_max_f32_e32 v3, v3, v3
	v_max_f32_e32 v4, 0, v4
	v_max_f32_e32 v5, 0, v5
	v_max_f32_e32 v0, 0, v0
	v_max_f32_e32 v1, 0, v1
	v_max_f32_e32 v3, 0, v3
	s_mov_b64 s[46:47], 0x160000
	v_pk_mul_f32 v[4:5], v[4:5], v[4:5]
	v_pk_mul_f32 v[6:7], v[0:1], v[0:1]
	v_pk_mul_f32 v[10:11], v[2:3], v[2:3]
	v_lshl_add_u64 v[12:13], v[122:123], 0, s[46:47]
	v_cvt_pk_bf16_f32 v0, v4, v5
	v_cvt_pk_bf16_f32 v1, v6, v7
	v_cvt_pk_bf16_f32 v2, v8, v9
	v_cvt_pk_bf16_f32 v3, v10, v11
	s_and_b64 vcc, exec, s[36:37]
	s_mov_b32 s65, s0
	s_mov_b32 s44, s30
	s_mov_b64 s[48:49], s[40:41]
	s_mov_b64 s[46:47], s[38:39]
	global_store_dwordx4 v[12:13], v[0:3], off offset:256
	s_cbranch_vccz .LBB0_62
	s_waitcnt vmcnt(0)
	v_readlane_b32 s64, v255, 38
	s_cmpk_gt_u32 s52, 0xff
	v_readlane_b32 s65, v255, 39
	s_cbranch_scc1 .LBB0_69
	s_barrier

; #define PG8_STAGE(bufoff, gbase, voff) do { _Pragma("unroll") for (int _i = 0; _i < 2; ++_i) \
;         __builtin_amdgcn_global_load_lds((const unsigned*)((const char*)(gbase) + (voff)[_i]), (PG8_LAS unsigned*)(lds + (bufoff) + ldsw + _i * 8192), 16, 0, 0); } while (0)
; #define PG8_LDA(dst, b, h) do { _Pragma("unroll") for (int m = 0; m < 4; ++m) _Pragma("unroll") for (int k = 0; k < 2; ++k) dst[m][k] = *(const PG8_LAS bf16x8*)(lds + PG8_SA(b, h) + aoff + m * 2048 + k * 1024); } while (0)
; #define PG8_LDB(dst, b, h) do { _Pragma("unroll") for (int n = 0; n < 2; ++n) _Pragma("unroll") for (int k = 0; k < 2; ++k) dst[n][k] = *(const PG8_LAS bf16x8*)(lds + PG8_SB(b, h) + boff + n * 2048 + k * 1024); } while (0)
; #define PG8_WAIT_V(n) asm volatile("s_waitcnt vmcnt(" #n ")" ::: "memory")
; #define PG8_WAIT_L(n) asm volatile("s_waitcnt lgkmcnt(" #n ")" ::: "memory")
; #define PG8_BAR __builtin_amdgcn_s_barrier()
; #define PG8_SCHED __builtin_amdgcn_sched_barrier(0)
; template <class Epi, class Sched>
; __device__ __forceinline__ void gemm_phase(PG8_LAS unsigned char* lds, const Gemm g, const Sched& S, const Epi& E) {
;     ...
;         for (int t = 0; t < nt; t += 2) {
;             const bool last = (t == nt - 2);
;             const char* a1 = cA + (size_t)(t + 1) * kstep;
;             const char* a2 = last ? nA : cA + (size_t)(t + 2) * kstep; const char* b2 = last ? nB : cB + (size_t)(t + 2) * kstep;
;             const char* a3 = a2 + kstep; const char* b3 = b2 + kstep;
;             if (last && has_next) S.a_ready(nxt);
;             PG8_LDB(B0, 0, 0); PG8_SCHED; PG8_LDA(At, 0, 0); PG8_STAGE(PG8_SA(1, 1), a1 + hstep, voffA);
;             PG8_WAIT_L(8); PG8_BAR; PG8_WAIT_L(0); PG8_MMA(0, 0, At, B0); PG8_BAR; PG8_SCHED;
;             PG8_LDB(B1, 0, 1); PG8_STAGE(PG8_SB(0, 0), b2, voffB);
;             PG8_BAR; PG8_WAIT_L(0); PG8_MMA(0, 1, At, B1); PG8_BAR;
;             PG8_LDA(At, 0, 1); PG8_STAGE(PG8_SA(0, 0), a2, voffA);
;             PG8_BAR; PG8_WAIT_L(0); PG8_MMA(1, 0, At, B0); PG8_BAR; PG8_SCHED;
;             PG8_STAGE(PG8_SB(0, 1), b2 + hstep, voffB);
;             PG8_WAIT_V(6); PG8_BAR; PG8_MMA(1, 1, At, B1); PG8_BAR;
;             PG8_LDB(B0, 1, 0); PG8_SCHED; PG8_LDA(At, 1, 0); PG8_STAGE(PG8_SA(0, 1), a2 + hstep, voffA);
;             PG8_WAIT_L(8); PG8_BAR; PG8_WAIT_L(0); PG8_MMA(0, 0, At, B0); PG8_BAR; PG8_SCHED;
.Lgp_4525:
.LBB0_87:
	s_add_u32 s40, s38, 0x100
	s_addc_u32 s41, s39, 0
	s_add_i32 s59, 0, 0x10000
	v_add_u32_e32 v102, s59, v240
	ds_read_b128 v[84:87], v102
	ds_read_b128 v[92:95], v102 offset:1024
	ds_read_b128 v[98:101], v102 offset:2048
	ds_read_b128 v[102:105], v102 offset:3072
	s_cmp_eq_u32 s60, 12
	s_cselect_b32 vcc_hi, s47, s41
	s_cselect_b32 vcc_lo, s94, s40
	s_cselect_b32 s53, s45, s57
	s_cselect_b32 s52, s97, s56
	v_lshl_add_u64 v[178:179], s[38:39], 0, v[210:211]
	s_add_i32 m0, s61, 0xc000
	ds_read_b128 v[146:149], v242
	ds_read_b128 v[154:157], v242 offset:2048
	ds_read_b128 v[162:165], v242 offset:4096
	ds_read_b128 v[170:173], v242 offset:6144
	ds_read_b128 v[150:153], v242 offset:1024
	ds_read_b128 v[158:161], v242 offset:3072
	ds_read_b128 v[166:169], v242 offset:5120
	ds_read_b128 v[174:177], v242 offset:7168
	global_load_lds_dwordx4 v[178:179], off
	v_lshl_add_u64 v[178:179], s[38:39], 0, v[212:213]
	s_add_i32 m0, s61, 0xe000
	s_nop 0
	global_load_lds_dwordx4 v[178:179], off
	s_waitcnt lgkmcnt(8)
	s_barrier
	s_waitcnt lgkmcnt(7)
	v_mfma_f32_16x16x32_bf16 v[142:145], v[84:87], v[146:149], v[142:145]
	v_mfma_f32_16x16x32_bf16 v[138:141], v[98:101], v[146:149], v[138:141]
	s_waitcnt lgkmcnt(6)
	v_mfma_f32_16x16x32_bf16 v[130:133], v[84:87], v[154:157], v[130:133]
	v_mfma_f32_16x16x32_bf16 v[122:125], v[98:101], v[154:157], v[122:125]
	s_waitcnt lgkmcnt(5)
	v_mfma_f32_16x16x32_bf16 v[114:117], v[84:87], v[162:165], v[114:117]
	v_mfma_f32_16x16x32_bf16 v[106:109], v[98:101], v[162:165], v[106:109]
	s_waitcnt lgkmcnt(4)
	v_mfma_f32_16x16x32_bf16 v[80:83], v[84:87], v[170:173], v[80:83]
	v_mfma_f32_16x16x32_bf16 v[72:75], v[98:101], v[170:173], v[72:75]
	s_waitcnt lgkmcnt(3)
	v_mfma_f32_16x16x32_bf16 v[142:145], v[92:95], v[150:153], v[142:145]
	v_mfma_f32_16x16x32_bf16 v[138:141], v[102:105], v[150:153], v[138:141]
	s_waitcnt lgkmcnt(2)
	v_mfma_f32_16x16x32_bf16 v[130:133], v[92:95], v[158:161], v[130:133]
	v_mfma_f32_16x16x32_bf16 v[122:125], v[102:105], v[158:161], v[122:125]
	s_waitcnt lgkmcnt(1)
	v_mfma_f32_16x16x32_bf16 v[114:117], v[92:95], v[166:169], v[114:117]
	v_mfma_f32_16x16x32_bf16 v[106:109], v[102:105], v[166:169], v[106:109]
	s_waitcnt lgkmcnt(0)
	v_mfma_f32_16x16x32_bf16 v[80:83], v[92:95], v[174:177], v[80:83]
	v_mfma_f32_16x16x32_bf16 v[72:75], v[102:105], v[174:177], v[72:75]
	s_barrier
	s_add_i32 s42, 0, 0x14000
	s_add_i32 s38, s59, s58
	v_add_u32_e32 v190, s42, v240
	v_lshl_add_u64 v[194:195], s[52:53], 0, v[96:97]
	s_mov_b32 m0, s38
	ds_read_b128 v[178:181], v190
	ds_read_b128 v[186:189], v190 offset:2048
	ds_read_b128 v[182:185], v190 offset:1024
	ds_read_b128 v[190:193], v190 offset:3072
	global_load_lds_dwordx4 v[194:195], off
	v_lshl_add_u64 v[196:197], s[52:53], 0, v[208:209]
	s_add_i32 m0, s38, 0x2000
	s_nop 0
	global_load_lds_dwordx4 v[196:197], off
	s_barrier
	s_waitcnt lgkmcnt(3)
	v_mfma_f32_16x16x32_bf16 v[134:137], v[178:181], v[146:149], v[134:137]
	s_waitcnt lgkmcnt(2)
	v_mfma_f32_16x16x32_bf16 v[126:129], v[186:189], v[146:149], v[126:129]
	v_mfma_f32_16x16x32_bf16 v[118:121], v[178:181], v[154:157], v[118:121]
	v_mfma_f32_16x16x32_bf16 v[110:113], v[186:189], v[154:157], v[110:113]
	v_mfma_f32_16x16x32_bf16 v[88:91], v[178:181], v[162:165], v[88:91]
	v_mfma_f32_16x16x32_bf16 v[76:79], v[186:189], v[162:165], v[76:79]
	v_mfma_f32_16x16x32_bf16 v[68:71], v[178:181], v[170:173], v[68:71]
	v_mfma_f32_16x16x32_bf16 v[64:67], v[186:189], v[170:173], v[64:67]
	s_waitcnt lgkmcnt(1)
	v_mfma_f32_16x16x32_bf16 v[134:137], v[182:185], v[150:153], v[134:137]
	s_waitcnt lgkmcnt(0)
	v_mfma_f32_16x16x32_bf16 v[126:129], v[190:193], v[150:153], v[126:129]
	v_mfma_f32_16x16x32_bf16 v[118:121], v[182:185], v[158:161], v[118:121]
	v_mfma_f32_16x16x32_bf16 v[110:113], v[190:193], v[158:161], v[110:113]
	v_mfma_f32_16x16x32_bf16 v[88:91], v[182:185], v[166:169], v[88:91]
	v_mfma_f32_16x16x32_bf16 v[76:79], v[190:193], v[166:169], v[76:79]
	v_mfma_f32_16x16x32_bf16 v[68:71], v[182:185], v[174:177], v[68:71]
	v_mfma_f32_16x16x32_bf16 v[64:67], v[190:193], v[174:177], v[64:67]
	s_mov_b32 m0, s61
	v_lshl_add_u64 v[198:199], vcc, 0, v[96:97]
	s_barrier
	ds_read_b128 v[146:149], v242 offset:16384
	ds_read_b128 v[154:157], v242 offset:18432
	ds_read_b128 v[162:165], v242 offset:20480
	ds_read_b128 v[170:173], v242 offset:22528
	ds_read_b128 v[150:153], v242 offset:17408
	ds_read_b128 v[158:161], v242 offset:19456
	ds_read_b128 v[166:169], v242 offset:21504
	ds_read_b128 v[174:177], v242 offset:23552
	global_load_lds_dwordx4 v[198:199], off
	v_lshl_add_u64 v[200:201], vcc, 0, v[208:209]
	s_mov_b32 m0, s62
	s_nop 0
	global_load_lds_dwordx4 v[200:201], off
	s_barrier
	s_waitcnt lgkmcnt(7)
	v_mfma_f32_16x16x32_bf16 v[60:63], v[84:87], v[146:149], v[60:63]
	v_mfma_f32_16x16x32_bf16 v[56:59], v[98:101], v[146:149], v[56:59]
	s_waitcnt lgkmcnt(6)
	v_mfma_f32_16x16x32_bf16 v[48:51], v[84:87], v[154:157], v[48:51]
	v_mfma_f32_16x16x32_bf16 v[40:43], v[98:101], v[154:157], v[40:43]
	s_waitcnt lgkmcnt(5)
	v_mfma_f32_16x16x32_bf16 v[32:35], v[84:87], v[162:165], v[32:35]
	v_mfma_f32_16x16x32_bf16 v[24:27], v[98:101], v[162:165], v[24:27]
	s_waitcnt lgkmcnt(4)
	v_mfma_f32_16x16x32_bf16 v[16:19], v[84:87], v[170:173], v[16:19]
	v_mfma_f32_16x16x32_bf16 v[8:11], v[98:101], v[170:173], v[8:11]
	s_waitcnt lgkmcnt(3)
	v_mfma_f32_16x16x32_bf16 v[60:63], v[92:95], v[150:153], v[60:63]
	v_mfma_f32_16x16x32_bf16 v[56:59], v[102:105], v[150:153], v[56:59]
	s_waitcnt lgkmcnt(2)
	v_mfma_f32_16x16x32_bf16 v[48:51], v[92:95], v[158:161], v[48:51]
	v_mfma_f32_16x16x32_bf16 v[40:43], v[102:105], v[158:161], v[40:43]
	s_waitcnt lgkmcnt(1)
	v_mfma_f32_16x16x32_bf16 v[32:35], v[92:95], v[166:169], v[32:35]
	v_mfma_f32_16x16x32_bf16 v[24:27], v[102:105], v[166:169], v[24:27]
	s_waitcnt lgkmcnt(0)
	v_mfma_f32_16x16x32_bf16 v[16:19], v[92:95], v[174:177], v[16:19]
	v_mfma_f32_16x16x32_bf16 v[8:11], v[102:105], v[174:177], v[8:11]
	s_barrier
; #define PG8_STAGE(bufoff, gbase, voff) do { _Pragma("unroll") for (int _i = 0; _i < 2; ++_i) \
;         __builtin_amdgcn_global_load_lds((const unsigned*)((const char*)(gbase) + (voff)[_i]), (PG8_LAS unsigned*)(lds + (bufoff) + ldsw + _i * 8192), 16, 0, 0); } while (0)
; #define PG8_LDA(dst, b, h) do { _Pragma("unroll") for (int m = 0; m < 4; ++m) _Pragma("unroll") for (int k = 0; k < 2; ++k) dst[m][k] = *(const PG8_LAS bf16x8*)(lds + PG8_SA(b, h) + aoff + m * 2048 + k * 1024); } while (0)
; #define PG8_LDB(dst, b, h) do { _Pragma("unroll") for (int n = 0; n < 2; ++n) _Pragma("unroll") for (int k = 0; k < 2; ++k) dst[n][k] = *(const PG8_LAS bf16x8*)(lds + PG8_SB(b, h) + boff + n * 2048 + k * 1024); } while (0)
; #define PG8_MMA(ai, bj, At, Bt) do { __builtin_amdgcn_s_setprio(1); _Pragma("unroll") for (int m = 0; m < 4; ++m) _Pragma("unroll") for (int n = 0; n < 2; ++n) _Pragma("unroll") for (int k = 0; k < 2; ++k) \
;         acc[ai][bj][m][n] = __builtin_amdgcn_mfma_f32_16x16x32_bf16(Bt[n][k], At[m][k], acc[ai][bj][m][n], 0, 0, 0); __builtin_amdgcn_s_setprio(0); } while (0)
; #define PG8_WAIT_V(n) asm volatile("s_waitcnt vmcnt(" #n ")" ::: "memory")
; #define PG8_WAIT_L(n) asm volatile("s_waitcnt lgkmcnt(" #n ")" ::: "memory")
; #define PG8_BAR __builtin_amdgcn_s_barrier()
; #define PG8_SCHED __builtin_amdgcn_sched_barrier(0)
; template <class Epi, class Sched>
; __device__ __forceinline__ void gemm_phase(PG8_LAS unsigned char* lds, const Gemm g, const Sched& S, const Epi& E) {
;     ...
;             PG8_WAIT_V(6); PG8_BAR; PG8_MMA(1, 1, At, B1); PG8_BAR;
;             PG8_LDB(B0, 1, 0); PG8_SCHED; PG8_LDA(At, 1, 0); PG8_STAGE(PG8_SA(0, 1), a2 + hstep, voffA);
;             PG8_WAIT_L(8); PG8_BAR; PG8_WAIT_L(0); PG8_MMA(0, 0, At, B0); PG8_BAR; PG8_SCHED;
;             PG8_LDB(B1, 1, 1); PG8_STAGE(PG8_SB(1, 0), b3, voffB);
;             PG8_BAR; PG8_WAIT_L(0); PG8_MMA(0, 1, At, B1); PG8_BAR;
;             PG8_LDA(At, 1, 1); PG8_STAGE(PG8_SA(1, 0), a3, voffA);
;             PG8_BAR; PG8_WAIT_L(0); PG8_MMA(1, 0, At, B0); PG8_BAR; PG8_SCHED;
;             PG8_STAGE(PG8_SB(1, 1), b3 + hstep, voffB);
	s_add_u32 s38, s52, 0x40000
	s_addc_u32 s39, s53, 0
	s_add_i32 s42, s42, s58
	v_lshl_add_u64 v[84:85], s[38:39], 0, v[96:97]
	s_mov_b32 m0, s42
	s_nop 0
	global_load_lds_dwordx4 v[84:85], off
	v_lshl_add_u64 v[84:85], s[38:39], 0, v[208:209]
	s_add_i32 m0, s42, 0x2000
	s_nop 0
	global_load_lds_dwordx4 v[84:85], off
	s_waitcnt vmcnt(6)
	s_barrier
	v_mfma_f32_16x16x32_bf16 v[52:55], v[178:181], v[146:149], v[52:55]
	v_mfma_f32_16x16x32_bf16 v[44:47], v[186:189], v[146:149], v[44:47]
	v_mfma_f32_16x16x32_bf16 v[36:39], v[178:181], v[154:157], v[36:39]
	v_mfma_f32_16x16x32_bf16 v[28:31], v[186:189], v[154:157], v[28:31]
	v_mfma_f32_16x16x32_bf16 v[20:23], v[178:181], v[162:165], v[20:23]
	v_mfma_f32_16x16x32_bf16 v[12:15], v[186:189], v[162:165], v[12:15]
	v_mfma_f32_16x16x32_bf16 v[4:7], v[178:181], v[170:173], v[4:7]
	v_mfma_f32_16x16x32_bf16 v[0:3], v[186:189], v[170:173], v[0:3]
	v_mfma_f32_16x16x32_bf16 v[52:55], v[182:185], v[150:153], v[52:55]
	v_mfma_f32_16x16x32_bf16 v[44:47], v[190:193], v[150:153], v[44:47]
	v_mfma_f32_16x16x32_bf16 v[36:39], v[182:185], v[158:161], v[36:39]
	v_mfma_f32_16x16x32_bf16 v[28:31], v[190:193], v[158:161], v[28:31]
	v_mfma_f32_16x16x32_bf16 v[20:23], v[182:185], v[166:169], v[20:23]
	v_mfma_f32_16x16x32_bf16 v[12:15], v[190:193], v[166:169], v[12:15]
	v_mfma_f32_16x16x32_bf16 v[4:7], v[182:185], v[174:177], v[4:7]
	v_mfma_f32_16x16x32_bf16 v[0:3], v[190:193], v[174:177], v[0:3]
	s_add_i32 s42, 0, 0x18000
	v_add_u32_e32 v102, s42, v240
	s_barrier
	ds_read_b128 v[84:87], v102
	ds_read_b128 v[92:95], v102 offset:1024
	ds_read_b128 v[98:101], v102 offset:2048
	ds_read_b128 v[102:105], v102 offset:3072
	s_add_u32 s38, vcc_lo, 0x40000
	s_addc_u32 s39, vcc_hi, 0
	s_mov_b32 m0, s63
	v_lshl_add_u64 v[178:179], s[38:39], 0, v[96:97]
	ds_read_b128 v[146:149], v242 offset:32768
	ds_read_b128 v[154:157], v242 offset:34816
	ds_read_b128 v[162:165], v242 offset:36864
	ds_read_b128 v[170:173], v242 offset:38912
	ds_read_b128 v[150:153], v242 offset:33792
	ds_read_b128 v[158:161], v242 offset:35840
	ds_read_b128 v[166:169], v242 offset:37888
	ds_read_b128 v[174:177], v242 offset:39936
	global_load_lds_dwordx4 v[178:179], off
	v_lshl_add_u64 v[178:179], s[38:39], 0, v[208:209]
	s_mov_b32 m0, s64
	s_nop 0
	global_load_lds_dwordx4 v[178:179], off
	s_waitcnt lgkmcnt(8)
	s_barrier
	s_waitcnt lgkmcnt(7)
	v_mfma_f32_16x16x32_bf16 v[142:145], v[84:87], v[146:149], v[142:145]
	v_mfma_f32_16x16x32_bf16 v[138:141], v[98:101], v[146:149], v[138:141]
	s_waitcnt lgkmcnt(6)
	v_mfma_f32_16x16x32_bf16 v[130:133], v[84:87], v[154:157], v[130:133]
	v_mfma_f32_16x16x32_bf16 v[122:125], v[98:101], v[154:157], v[122:125]
	s_waitcnt lgkmcnt(5)
	v_mfma_f32_16x16x32_bf16 v[114:117], v[84:87], v[162:165], v[114:117]
	v_mfma_f32_16x16x32_bf16 v[106:109], v[98:101], v[162:165], v[106:109]
	s_waitcnt lgkmcnt(4)
	v_mfma_f32_16x16x32_bf16 v[80:83], v[84:87], v[170:173], v[80:83]
	v_mfma_f32_16x16x32_bf16 v[72:75], v[98:101], v[170:173], v[72:75]
	s_waitcnt lgkmcnt(3)
	v_mfma_f32_16x16x32_bf16 v[142:145], v[92:95], v[150:153], v[142:145]
	v_mfma_f32_16x16x32_bf16 v[138:141], v[102:105], v[150:153], v[138:141]
	s_waitcnt lgkmcnt(2)
	v_mfma_f32_16x16x32_bf16 v[130:133], v[92:95], v[158:161], v[130:133]
	v_mfma_f32_16x16x32_bf16 v[122:125], v[102:105], v[158:161], v[122:125]
	s_waitcnt lgkmcnt(1)
	v_mfma_f32_16x16x32_bf16 v[114:117], v[92:95], v[166:169], v[114:117]
	v_mfma_f32_16x16x32_bf16 v[106:109], v[102:105], v[166:169], v[106:109]
	s_waitcnt lgkmcnt(0)
	v_mfma_f32_16x16x32_bf16 v[80:83], v[92:95], v[174:177], v[80:83]
	v_mfma_f32_16x16x32_bf16 v[72:75], v[102:105], v[174:177], v[72:75]
	s_barrier
	s_add_i32 s43, 0, 0x1c000
	s_add_i32 s38, s42, s58
	v_add_u32_e32 v190, s43, v240
	v_lshl_add_u64 v[194:195], v[194:195], 0, s[2:3]
	s_mov_b32 m0, s38
	ds_read_b128 v[178:181], v190
	ds_read_b128 v[186:189], v190 offset:2048
	ds_read_b128 v[182:185], v190 offset:1024
	ds_read_b128 v[190:193], v190 offset:3072
	global_load_lds_dwordx4 v[194:195], off
	v_lshl_add_u64 v[194:195], v[196:197], 0, s[2:3]
	s_add_i32 m0, s38, 0x2000
	s_nop 0
	global_load_lds_dwordx4 v[194:195], off
	s_barrier
	s_waitcnt lgkmcnt(3)
	v_mfma_f32_16x16x32_bf16 v[134:137], v[178:181], v[146:149], v[134:137]
	s_waitcnt lgkmcnt(2)
	v_mfma_f32_16x16x32_bf16 v[126:129], v[186:189], v[146:149], v[126:129]
	v_mfma_f32_16x16x32_bf16 v[118:121], v[178:181], v[154:157], v[118:121]
	v_mfma_f32_16x16x32_bf16 v[110:113], v[186:189], v[154:157], v[110:113]
	v_mfma_f32_16x16x32_bf16 v[88:91], v[178:181], v[162:165], v[88:91]
	v_mfma_f32_16x16x32_bf16 v[76:79], v[186:189], v[162:165], v[76:79]
	v_mfma_f32_16x16x32_bf16 v[68:71], v[178:181], v[170:173], v[68:71]
	v_mfma_f32_16x16x32_bf16 v[64:67], v[186:189], v[170:173], v[64:67]
	s_waitcnt lgkmcnt(1)
	v_mfma_f32_16x16x32_bf16 v[134:137], v[182:185], v[150:153], v[134:137]
	s_waitcnt lgkmcnt(0)
	v_mfma_f32_16x16x32_bf16 v[126:129], v[190:193], v[150:153], v[126:129]
	v_mfma_f32_16x16x32_bf16 v[118:121], v[182:185], v[158:161], v[118:121]
	v_mfma_f32_16x16x32_bf16 v[110:113], v[190:193], v[158:161], v[110:113]
	v_mfma_f32_16x16x32_bf16 v[88:91], v[182:185], v[166:169], v[88:91]
	v_mfma_f32_16x16x32_bf16 v[76:79], v[190:193], v[166:169], v[76:79]
	v_mfma_f32_16x16x32_bf16 v[68:71], v[182:185], v[174:177], v[68:71]
	v_mfma_f32_16x16x32_bf16 v[64:67], v[190:193], v[174:177], v[64:67]
	s_mov_b32 m0, s69
	v_lshl_add_u64 v[194:195], v[198:199], 0, s[2:3]
	s_barrier
; #define PG8_STAGE(bufoff, gbase, voff) do { _Pragma("unroll") for (int _i = 0; _i < 2; ++_i) \
;         __builtin_amdgcn_global_load_lds((const unsigned*)((const char*)(gbase) + (voff)[_i]), (PG8_LAS unsigned*)(lds + (bufoff) + ldsw + _i * 8192), 16, 0, 0); } while (0)
; #define PG8_LDA(dst, b, h) do { _Pragma("unroll") for (int m = 0; m < 4; ++m) _Pragma("unroll") for (int k = 0; k < 2; ++k) dst[m][k] = *(const PG8_LAS bf16x8*)(lds + PG8_SA(b, h) + aoff + m * 2048 + k * 1024); } while (0)
; #define PG8_MMA(ai, bj, At, Bt) do { __builtin_amdgcn_s_setprio(1); _Pragma("unroll") for (int m = 0; m < 4; ++m) _Pragma("unroll") for (int n = 0; n < 2; ++n) _Pragma("unroll") for (int k = 0; k < 2; ++k) \
;         acc[ai][bj][m][n] = __builtin_amdgcn_mfma_f32_16x16x32_bf16(Bt[n][k], At[m][k], acc[ai][bj][m][n], 0, 0, 0); __builtin_amdgcn_s_setprio(0); } while (0)
; #define PG8_WAIT_V(n) asm volatile("s_waitcnt vmcnt(" #n ")" ::: "memory")
; #define PG8_BAR __builtin_amdgcn_s_barrier()
; template <class Epi, class Sched>
; __device__ __forceinline__ void gemm_phase(PG8_LAS unsigned char* lds, const Gemm g, const Sched& S, const Epi& E) {
;     ...
;             PG8_LDA(At, 1, 1); PG8_STAGE(PG8_SA(1, 0), a3, voffA);
;             PG8_BAR; PG8_WAIT_L(0); PG8_MMA(1, 0, At, B0); PG8_BAR; PG8_SCHED;
;             PG8_STAGE(PG8_SB(1, 1), b3 + hstep, voffB);
;             PG8_WAIT_V(6); PG8_BAR; PG8_MMA(1, 1, At, B1); PG8_BAR;
;         }
;   DEV void operator()(const f32x4 (&acc)[2][2][4][2], const pg8::Unit& u, int wr, int wc, int fr, int fq) const {
;     const int row0 = u.pm * 256 + wr * 64 + fr, col0 = u.pn * 256 + wc * 32 + 4 * fq;
;     const float* gt = mod + (size_t)modrow(row0) * 6144;
;     f32x4 g4[2][2];
; #pragma unroll
;     for (int bj = 0; bj < 2; ++bj)
; #pragma unroll
;       for (int n = 0; n < 2; ++n) g4[bj][n] = *(const f32x4*)(gt + col0 + bj * 128 + n * 16);
; #pragma unroll
;     for (int ai = 0; ai < 2; ++ai) {
;       f32x4 xv[4][2][2];
; #pragma unroll
;       for (int m = 0; m < 4; ++m) {
;         const int row = row0 + ai * 128 + m * 16;
;         const float* xi = row < T_LAT ? rin_lat + (size_t)row * DM : rin_ctx + (size_t)(row - T_LAT) * DM;
; #pragma unroll
;         for (int bj = 0; bj < 2; ++bj)
; #pragma unroll
;           for (int n = 0; n < 2; ++n) xv[m][bj][n] = *(const f32x4*)(xi + col0 + bj * 128 + n * 16);
;       }
	ds_read_b128 v[146:149], v242 offset:49152
	ds_read_b128 v[154:157], v242 offset:51200
	ds_read_b128 v[162:165], v242 offset:53248
	ds_read_b128 v[170:173], v242 offset:55296
	ds_read_b128 v[150:153], v242 offset:50176
	ds_read_b128 v[158:161], v242 offset:52224
	ds_read_b128 v[166:169], v242 offset:54272
	ds_read_b128 v[174:177], v242 offset:56320
	global_load_lds_dwordx4 v[194:195], off
	v_lshl_add_u64 v[194:195], v[200:201], 0, s[2:3]
	s_mov_b32 m0, s70
	s_nop 0
	global_load_lds_dwordx4 v[194:195], off
	s_barrier
	s_waitcnt lgkmcnt(7)
	v_mfma_f32_16x16x32_bf16 v[60:63], v[84:87], v[146:149], v[60:63]
	v_mfma_f32_16x16x32_bf16 v[56:59], v[98:101], v[146:149], v[56:59]
	s_waitcnt lgkmcnt(6)
	v_mfma_f32_16x16x32_bf16 v[48:51], v[84:87], v[154:157], v[48:51]
	v_mfma_f32_16x16x32_bf16 v[40:43], v[98:101], v[154:157], v[40:43]
	s_waitcnt lgkmcnt(5)
	v_mfma_f32_16x16x32_bf16 v[32:35], v[84:87], v[162:165], v[32:35]
	v_mfma_f32_16x16x32_bf16 v[24:27], v[98:101], v[162:165], v[24:27]
	s_waitcnt lgkmcnt(4)
	v_mfma_f32_16x16x32_bf16 v[16:19], v[84:87], v[170:173], v[16:19]
	v_mfma_f32_16x16x32_bf16 v[8:11], v[98:101], v[170:173], v[8:11]
	s_waitcnt lgkmcnt(3)
	v_mfma_f32_16x16x32_bf16 v[60:63], v[92:95], v[150:153], v[60:63]
	v_mfma_f32_16x16x32_bf16 v[56:59], v[102:105], v[150:153], v[56:59]
	s_waitcnt lgkmcnt(2)
	v_mfma_f32_16x16x32_bf16 v[48:51], v[92:95], v[158:161], v[48:51]
	v_mfma_f32_16x16x32_bf16 v[40:43], v[102:105], v[158:161], v[40:43]
	s_waitcnt lgkmcnt(1)
	v_mfma_f32_16x16x32_bf16 v[32:35], v[92:95], v[166:169], v[32:35]
	v_mfma_f32_16x16x32_bf16 v[24:27], v[102:105], v[166:169], v[24:27]
	s_waitcnt lgkmcnt(0)
	v_mfma_f32_16x16x32_bf16 v[16:19], v[92:95], v[174:177], v[16:19]
	v_mfma_f32_16x16x32_bf16 v[8:11], v[102:105], v[174:177], v[8:11]
	s_barrier
	s_add_u32 s38, s52, 0x40080
	s_addc_u32 s39, s53, 0
	s_add_i32 s42, s43, s58
	v_lshl_add_u64 v[84:85], s[38:39], 0, v[96:97]
	s_mov_b32 m0, s42
	s_nop 0
	global_load_lds_dwordx4 v[84:85], off
	v_lshl_add_u64 v[84:85], s[38:39], 0, v[208:209]
	s_add_i32 m0, s42, 0x2000
	s_nop 0
	global_load_lds_dwordx4 v[84:85], off
	s_waitcnt vmcnt(6)
	s_barrier
	v_mfma_f32_16x16x32_bf16 v[52:55], v[178:181], v[146:149], v[52:55]
	v_mfma_f32_16x16x32_bf16 v[44:47], v[186:189], v[146:149], v[44:47]
	v_mfma_f32_16x16x32_bf16 v[36:39], v[178:181], v[154:157], v[36:39]
	v_mfma_f32_16x16x32_bf16 v[28:31], v[186:189], v[154:157], v[28:31]
	v_mfma_f32_16x16x32_bf16 v[20:23], v[178:181], v[162:165], v[20:23]
	v_mfma_f32_16x16x32_bf16 v[12:15], v[186:189], v[162:165], v[12:15]
	v_mfma_f32_16x16x32_bf16 v[4:7], v[178:181], v[170:173], v[4:7]
	v_mfma_f32_16x16x32_bf16 v[0:3], v[186:189], v[170:173], v[0:3]
	v_mfma_f32_16x16x32_bf16 v[52:55], v[182:185], v[150:153], v[52:55]
	v_mfma_f32_16x16x32_bf16 v[44:47], v[190:193], v[150:153], v[44:47]
	v_mfma_f32_16x16x32_bf16 v[36:39], v[182:185], v[158:161], v[36:39]
	v_mfma_f32_16x16x32_bf16 v[28:31], v[190:193], v[158:161], v[28:31]
	v_mfma_f32_16x16x32_bf16 v[20:23], v[182:185], v[166:169], v[20:23]
	v_mfma_f32_16x16x32_bf16 v[12:15], v[190:193], v[166:169], v[12:15]
	v_mfma_f32_16x16x32_bf16 v[4:7], v[182:185], v[174:177], v[4:7]
	v_mfma_f32_16x16x32_bf16 v[0:3], v[190:193], v[174:177], v[0:3]
	s_add_i32 s60, s60, 2
	s_add_u32 s56, s56, 0x100
	s_addc_u32 s57, s57, 0
	s_cmp_gt_u32 s60, 13
	s_mov_b64 s[38:39], s[40:41]
	s_barrier
	s_cbranch_scc0 .LBB0_87
	v_lshl_add_u32 v247, s0, 8, v239
	s_mov_b32 s42, 0x8000
	v_min_i32_e32 v85, 0x8000, v247
	v_cmp_gt_i32_e64 s[40:41], s42, v247
	v_add_u32_e32 v146, 0xffff8000, v247
	v_ashrrev_i32_e32 v147, 31, v247
	v_lshl_or_b32 v84, s1, 8, v241
	v_ashrrev_i32_e32 v85, 12, v85
	v_cndmask_b32_e64 v147, 0, v147, s[40:41]
	v_cndmask_b32_e64 v146, v146, v247, s[40:41]
	v_mov_b32_e32 v248, s67
	v_mov_b32_e32 v249, s65
	v_mov_b32_e32 v250, s68
	v_mov_b32_e32 v238, s66
	v_mul_hi_i32_i24_e32 v87, 0x6000, v85
	v_mul_i32_i24_e32 v86, 0x6000, v85
	v_ashrrev_i32_e32 v85, 31, v84
	v_cndmask_b32_e64 v149, v248, v249, s[40:41]
	v_cndmask_b32_e64 v148, v250, v238, s[40:41]
	v_lshlrev_b64 v[222:223], 12, v[146:147]
	v_lshlrev_b64 v[214:215], 2, v[84:85]
	v_lshl_add_u64 v[146:147], v[148:149], 0, v[222:223]
	v_lshl_add_u64 v[224:225], v[146:147], 0, v[214:215]
	v_or_b32_e32 v146, 16, v247
	v_cmp_gt_i32_e64 s[38:39], s42, v146
	v_ashrrev_i32_e32 v147, 31, v146
	v_add_u32_e32 v148, 0xffff8010, v247
	v_cndmask_b32_e64 v147, 0, v147, s[38:39]
	v_cndmask_b32_e64 v146, v148, v146, s[38:39]
	v_cndmask_b32_e64 v149, v248, v249, s[38:39]
	v_cndmask_b32_e64 v148, v250, v238, s[38:39]
	v_lshlrev_b64 v[220:221], 12, v[146:147]
	v_lshl_add_u64 v[86:87], s[30:31], 0, v[86:87]
	v_lshl_add_u64 v[146:147], v[148:149], 0, v[220:221]
	v_lshl_add_u64 v[84:85], v[86:87], 0, v[214:215]
	v_lshl_add_u64 v[146:147], v[146:147], 0, v[214:215]
	global_load_dwordx4 v[102:105], v[84:85], off
	global_load_dwordx4 v[98:101], v[84:85], off offset:64
	global_load_dwordx4 v[92:95], v[84:85], off offset:512
	s_nop 0
	global_load_dwordx4 v[84:87], v[84:85], off offset:576
	s_nop 0
	global_load_dwordx4 v[202:205], v[224:225], off offset:64
	global_load_dwordx4 v[198:201], v[224:225], off offset:512
	global_load_dwordx4 v[194:197], v[224:225], off offset:576
	global_load_dwordx4 v[190:193], v[146:147], off
	global_load_dwordx4 v[186:189], v[146:147], off offset:64
	global_load_dwordx4 v[182:185], v[146:147], off offset:512
	global_load_dwordx4 v[178:181], v[146:147], off offset:576
	v_or_b32_e32 v146, 32, v247
	v_cmp_gt_i32_e64 s[0:1], s42, v146
	v_ashrrev_i32_e32 v147, 31, v146
	v_add_u32_e32 v148, 0xffff8020, v247
	v_cndmask_b32_e64 v147, 0, v147, s[0:1]
	v_cndmask_b32_e64 v146, v148, v146, s[0:1]
;   DEV void operator()(const f32x4 (&acc)[2][2][4][2], const pg8::Unit& u, int wr, int wc, int fr, int fq) const {
;     const int row0 = u.pm * 256 + wr * 64 + fr, col0 = u.pn * 256 + wc * 32 + 4 * fq;
;     const float* gt = mod + (size_t)modrow(row0) * 6144;
;     f32x4 g4[2][2];
; #pragma unroll
;     for (int bj = 0; bj < 2; ++bj)
; #pragma unroll
;       for (int n = 0; n < 2; ++n) g4[bj][n] = *(const f32x4*)(gt + col0 + bj * 128 + n * 16);
; #pragma unroll
;     for (int ai = 0; ai < 2; ++ai) {
;       f32x4 xv[4][2][2];
; #pragma unroll
;       for (int m = 0; m < 4; ++m) {
;         const int row = row0 + ai * 128 + m * 16;
;         const float* xi = row < T_LAT ? rin_lat + (size_t)row * DM : rin_ctx + (size_t)(row - T_LAT) * DM;
; #pragma unroll
;         for (int bj = 0; bj < 2; ++bj)
; #pragma unroll
;           for (int n = 0; n < 2; ++n) xv[m][bj][n] = *(const f32x4*)(xi + col0 + bj * 128 + n * 16);
;       }
; #pragma unroll
;       for (int m = 0; m < 4; ++m) {
;         const int row = row0 + ai * 128 + m * 16;
;         float* xr = row < T_LAT ? out + (size_t)row * DM : xc + (size_t)(row - T_LAT) * DM;
; #pragma unroll
;         for (int bj = 0; bj < 2; ++bj)
; #pragma unroll
;           for (int n = 0; n < 2; ++n) {
;             const f32x4 r = xv[m][bj][n] + g4[bj][n] * acc[ai][bj][m][n];
;             if (store) *(f32x4*)(xr + col0 + bj * 128 + n * 16) = r;
;           }
;       }
;     }
;   }
	v_cndmask_b32_e64 v149, v248, v249, s[0:1]
	v_cndmask_b32_e64 v148, v250, v238, s[0:1]
	v_lshlrev_b64 v[218:219], 12, v[146:147]
	v_lshl_add_u64 v[146:147], v[148:149], 0, v[218:219]
	v_lshl_add_u64 v[146:147], v[146:147], 0, v[214:215]
	global_load_dwordx4 v[174:177], v[146:147], off
	global_load_dwordx4 v[170:173], v[146:147], off offset:64
	global_load_dwordx4 v[166:169], v[146:147], off offset:512
	global_load_dwordx4 v[162:165], v[146:147], off offset:576
	v_or_b32_e32 v146, 48, v247
	v_cmp_gt_i32_e32 vcc, s42, v146
	v_ashrrev_i32_e32 v147, 31, v146
	v_add_u32_e32 v148, 0xffff8030, v247
	v_cndmask_b32_e32 v147, 0, v147, vcc
	v_cndmask_b32_e32 v146, v148, v146, vcc
	v_readlane_b32 s42, v251, 52
	v_cndmask_b32_e32 v149, v248, v249, vcc
	v_cndmask_b32_e32 v148, v250, v238, vcc
	v_lshlrev_b64 v[216:217], 12, v[146:147]
	v_mov_b32_e32 v243, s42
	v_readlane_b32 s42, v251, 51
	v_lshl_add_u64 v[146:147], v[148:149], 0, v[216:217]
	v_mov_b32_e32 v244, s73
	v_mov_b32_e32 v245, s42
	v_mov_b32_e32 v246, s72
	v_lshl_add_u64 v[146:147], v[146:147], 0, v[214:215]
	v_cndmask_b32_e64 v229, v243, v244, s[40:41]
	v_cndmask_b32_e64 v228, v245, v246, s[40:41]
	global_load_dwordx4 v[158:161], v[146:147], off
	global_load_dwordx4 v[154:157], v[146:147], off offset:64
	global_load_dwordx4 v[150:153], v[146:147], off offset:512
	s_nop 0
	global_load_dwordx4 v[146:149], v[146:147], off offset:576
	v_lshl_add_u64 v[222:223], v[228:229], 0, v[222:223]
	global_load_dwordx4 v[228:231], v[224:225], off
	v_lshl_add_u64 v[222:223], v[222:223], 0, v[214:215]
	s_movk_i32 s42, 0x7f50
	s_waitcnt vmcnt(0)
	v_pk_fma_f32 v[140:141], v[140:141], v[100:101], v[204:205]
	v_pk_fma_f32 v[136:137], v[136:137], v[94:95], v[200:201]
	v_pk_fma_f32 v[128:129], v[128:129], v[86:87], v[196:197]
	v_pk_fma_f32 v[126:127], v[126:127], v[84:85], v[194:195]
	global_store_dwordx4 v[222:223], v[126:129], off offset:576
	v_pk_fma_f32 v[134:135], v[134:135], v[92:93], v[198:199]
	v_pk_fma_f32 v[138:139], v[138:139], v[98:99], v[202:203]
	v_cndmask_b32_e64 v127, v243, v244, s[38:39]
	v_cndmask_b32_e64 v126, v245, v246, s[38:39]
	v_lshl_add_u64 v[126:127], v[126:127], 0, v[220:221]
	global_store_dwordx4 v[222:223], v[134:137], off offset:512
	v_pk_fma_f32 v[112:113], v[112:113], v[86:87], v[180:181]
	v_pk_fma_f32 v[110:111], v[110:111], v[84:85], v[178:179]
	v_lshl_add_u64 v[134:135], v[126:127], 0, v[214:215]
	global_store_dwordx4 v[222:223], v[138:141], off offset:64
	v_pk_fma_f32 v[120:121], v[120:121], v[94:95], v[184:185]
	v_pk_fma_f32 v[118:119], v[118:119], v[92:93], v[182:183]
	v_pk_fma_f32 v[128:129], v[132:133], v[104:105], v[192:193]
	v_pk_fma_f32 v[126:127], v[130:131], v[102:103], v[190:191]
	v_pk_fma_f32 v[124:125], v[124:125], v[100:101], v[188:189]
	v_pk_fma_f32 v[122:123], v[122:123], v[98:99], v[186:187]
	v_pk_fma_f32 v[78:79], v[78:79], v[86:87], v[164:165]
	v_pk_fma_f32 v[76:77], v[76:77], v[84:85], v[162:163]
	v_pk_fma_f32 v[90:91], v[90:91], v[94:95], v[168:169]
	v_pk_fma_f32 v[88:89], v[88:89], v[92:93], v[166:167]
	v_pk_fma_f32 v[108:109], v[108:109], v[100:101], v[172:173]
	v_pk_fma_f32 v[106:107], v[106:107], v[98:99], v[170:171]
	v_pk_fma_f32 v[74:75], v[74:75], v[100:101], v[156:157]
	v_pk_fma_f32 v[68:69], v[68:69], v[92:93], v[150:151]
	v_pk_fma_f32 v[66:67], v[66:67], v[86:87], v[148:149]
	v_pk_fma_f32 v[64:65], v[64:65], v[84:85], v[146:147]
	v_pk_fma_f32 v[144:145], v[144:145], v[104:105], v[230:231]
	v_pk_fma_f32 v[142:143], v[142:143], v[102:103], v[228:229]
	global_store_dwordx4 v[222:223], v[142:145], off
	global_store_dwordx4 v[134:135], v[110:113], off offset:576
	global_store_dwordx4 v[134:135], v[118:121], off offset:512
	global_store_dwordx4 v[134:135], v[126:129], off
	v_cndmask_b32_e64 v111, v243, v244, s[0:1]
	v_cndmask_b32_e64 v110, v245, v246, s[0:1]
	v_lshl_add_u64 v[110:111], v[110:111], 0, v[218:219]
	v_lshl_add_u64 v[118:119], v[110:111], 0, v[214:215]
	global_store_dwordx4 v[134:135], v[122:125], off offset:64
	global_store_dwordx4 v[118:119], v[76:79], off offset:576
	v_pk_fma_f32 v[112:113], v[116:117], v[104:105], v[176:177]
	v_pk_fma_f32 v[110:111], v[114:115], v[102:103], v[174:175]
	v_cndmask_b32_e32 v77, v243, v244, vcc
	v_cndmask_b32_e32 v76, v245, v246, vcc
	v_lshl_add_u64 v[76:77], v[76:77], 0, v[216:217]
	global_store_dwordx4 v[118:119], v[88:91], off offset:512
	global_store_dwordx4 v[118:119], v[110:113], off
	global_store_dwordx4 v[118:119], v[106:109], off offset:64
	v_lshl_add_u64 v[88:89], v[76:77], 0, v[214:215]
	global_store_dwordx4 v[88:89], v[64:67], off offset:576
	s_movk_i32 s0, 0x7f80
	v_cmp_gt_i32_e64 s[40:41], s0, v247
	v_add_u32_e32 v64, 0x80, v247
	v_ashrrev_i32_e32 v65, 31, v64
	v_add_u32_e32 v66, 0xffff8080, v247
	v_cndmask_b32_e64 v65, 0, v65, s[40:41]
	v_cndmask_b32_e64 v64, v66, v64, s[40:41]
	v_cndmask_b32_e64 v67, v248, v249, s[40:41]
	v_cndmask_b32_e64 v66, v250, v238, s[40:41]
	v_lshlrev_b64 v[148:149], 12, v[64:65]
	v_lshl_add_u64 v[64:65], v[66:67], 0, v[148:149]
	v_lshl_add_u64 v[150:151], v[64:65], 0, v[214:215]
	v_add_u32_e32 v64, 0x90, v247
	s_movk_i32 s0, 0x7f70
	v_cmp_gt_i32_e64 s[38:39], s0, v247
	v_ashrrev_i32_e32 v65, 31, v64
	v_add_u32_e32 v66, 0xffff8090, v247
	v_cndmask_b32_e64 v65, 0, v65, s[38:39]
	v_cndmask_b32_e64 v64, v66, v64, s[38:39]
	v_cndmask_b32_e64 v67, v248, v249, s[38:39]
	v_cndmask_b32_e64 v66, v250, v238, s[38:39]
	v_lshlrev_b64 v[146:147], 12, v[64:65]
	v_pk_fma_f32 v[78:79], v[82:83], v[104:105], v[160:161]
	v_pk_fma_f32 v[76:77], v[80:81], v[102:103], v[158:159]
	v_pk_fma_f32 v[72:73], v[72:73], v[98:99], v[154:155]
	v_pk_fma_f32 v[70:71], v[70:71], v[94:95], v[152:153]
;   DEV void operator()(const f32x4 (&acc)[2][2][4][2], const pg8::Unit& u, int wr, int wc, int fr, int fq) const {
;     ...
;     for (int ai = 0; ai < 2; ++ai) {
;       f32x4 xv[4][2][2];
; #pragma unroll
;       for (int m = 0; m < 4; ++m) {
;         const int row = row0 + ai * 128 + m * 16;
;         const float* xi = row < T_LAT ? rin_lat + (size_t)row * DM : rin_ctx + (size_t)(row - T_LAT) * DM;
; #pragma unroll
;         for (int bj = 0; bj < 2; ++bj)
; #pragma unroll
;           for (int n = 0; n < 2; ++n) xv[m][bj][n] = *(const f32x4*)(xi + col0 + bj * 128 + n * 16);
;       }
; #pragma unroll
;       for (int m = 0; m < 4; ++m) {
;         const int row = row0 + ai * 128 + m * 16;
;         float* xr = row < T_LAT ? out + (size_t)row * DM : xc + (size_t)(row - T_LAT) * DM;
; #pragma unroll
;         for (int bj = 0; bj < 2; ++bj)
; #pragma unroll
;           for (int n = 0; n < 2; ++n) {
;             const f32x4 r = xv[m][bj][n] + g4[bj][n] * acc[ai][bj][m][n];
;             if (store) *(f32x4*)(xr + col0 + bj * 128 + n * 16) = r;
;           }
;       }
;     }
;   }
	v_lshl_add_u64 v[64:65], v[66:67], 0, v[146:147]
	global_store_dwordx4 v[88:89], v[76:79], off
	global_store_dwordx4 v[88:89], v[72:75], off offset:64
	global_store_dwordx4 v[88:89], v[68:71], off offset:512
	v_lshl_add_u64 v[64:65], v[64:65], 0, v[214:215]
	global_load_dwordx4 v[138:141], v[150:151], off offset:64
	global_load_dwordx4 v[134:137], v[150:151], off offset:512
	global_load_dwordx4 v[130:133], v[150:151], off offset:576
	global_load_dwordx4 v[126:129], v[64:65], off
	global_load_dwordx4 v[122:125], v[64:65], off offset:64
	global_load_dwordx4 v[118:121], v[64:65], off offset:512
	global_load_dwordx4 v[114:117], v[64:65], off offset:576
	v_add_u32_e32 v64, 0xa0, v247
	s_movk_i32 s0, 0x7f60
	v_cmp_gt_i32_e64 s[0:1], s0, v247
	v_ashrrev_i32_e32 v65, 31, v64
	v_add_u32_e32 v66, 0xffff80a0, v247
	v_cndmask_b32_e64 v65, 0, v65, s[0:1]
	v_cndmask_b32_e64 v64, v66, v64, s[0:1]
	v_cndmask_b32_e64 v67, v248, v249, s[0:1]
	v_cndmask_b32_e64 v66, v250, v238, s[0:1]
	v_lshlrev_b64 v[144:145], 12, v[64:65]
	v_lshl_add_u64 v[64:65], v[66:67], 0, v[144:145]
	v_lshl_add_u64 v[64:65], v[64:65], 0, v[214:215]
	global_load_dwordx4 v[110:113], v[64:65], off
	global_load_dwordx4 v[106:109], v[64:65], off offset:64
	global_load_dwordx4 v[88:91], v[64:65], off offset:512
	global_load_dwordx4 v[80:83], v[64:65], off offset:576
	v_add_u32_e32 v64, 0xb0, v247
	v_cmp_gt_i32_e32 vcc, s42, v247
	v_ashrrev_i32_e32 v65, 31, v64
	v_add_u32_e32 v66, 0xffff80b0, v247
	v_cndmask_b32_e32 v65, 0, v65, vcc
	v_cndmask_b32_e32 v64, v66, v64, vcc
	v_cndmask_b32_e32 v67, v248, v249, vcc
	v_cndmask_b32_e32 v66, v250, v238, vcc
	v_lshlrev_b64 v[142:143], 12, v[64:65]
	v_lshl_add_u64 v[64:65], v[66:67], 0, v[142:143]
	v_lshl_add_u64 v[64:65], v[64:65], 0, v[214:215]
	v_cndmask_b32_e64 v153, v243, v244, s[40:41]
	v_cndmask_b32_e64 v152, v245, v246, s[40:41]
	global_load_dwordx4 v[76:79], v[64:65], off
	global_load_dwordx4 v[72:75], v[64:65], off offset:64
	global_load_dwordx4 v[68:71], v[64:65], off offset:512
	s_nop 0
	global_load_dwordx4 v[64:67], v[64:65], off offset:576
	v_lshl_add_u64 v[148:149], v[152:153], 0, v[148:149]
	global_load_dwordx4 v[150:153], v[150:151], off
	v_lshl_add_u64 v[148:149], v[148:149], 0, v[214:215]
	s_mov_b64 s[40:41], s[50:51]
	s_waitcnt vmcnt(0)
	v_pk_fma_f32 v[58:59], v[58:59], v[100:101], v[140:141]
	v_pk_fma_f32 v[54:55], v[54:55], v[94:95], v[136:137]
	v_pk_fma_f32 v[46:47], v[46:47], v[86:87], v[132:133]
	v_pk_fma_f32 v[44:45], v[44:45], v[84:85], v[130:131]
	global_store_dwordx4 v[148:149], v[44:47], off offset:576
	v_pk_fma_f32 v[52:53], v[52:53], v[92:93], v[134:135]
	v_pk_fma_f32 v[56:57], v[56:57], v[98:99], v[138:139]
	v_cndmask_b32_e64 v45, v243, v244, s[38:39]
	v_cndmask_b32_e64 v44, v245, v246, s[38:39]
	v_lshl_add_u64 v[44:45], v[44:45], 0, v[146:147]
	global_store_dwordx4 v[148:149], v[52:55], off offset:512
	v_pk_fma_f32 v[30:31], v[30:31], v[86:87], v[116:117]
	v_pk_fma_f32 v[28:29], v[28:29], v[84:85], v[114:115]
	v_lshl_add_u64 v[52:53], v[44:45], 0, v[214:215]
	global_store_dwordx4 v[148:149], v[56:59], off offset:64
	v_pk_fma_f32 v[38:39], v[38:39], v[94:95], v[120:121]
	v_pk_fma_f32 v[36:37], v[36:37], v[92:93], v[118:119]
	v_pk_fma_f32 v[46:47], v[50:51], v[104:105], v[128:129]
	v_pk_fma_f32 v[44:45], v[48:49], v[102:103], v[126:127]
	v_pk_fma_f32 v[42:43], v[42:43], v[100:101], v[124:125]
	v_pk_fma_f32 v[40:41], v[40:41], v[98:99], v[122:123]
	v_pk_fma_f32 v[14:15], v[14:15], v[86:87], v[82:83]
	v_pk_fma_f32 v[12:13], v[12:13], v[84:85], v[80:81]
	v_pk_fma_f32 v[22:23], v[22:23], v[94:95], v[90:91]
	v_pk_fma_f32 v[20:21], v[20:21], v[92:93], v[88:89]
	v_pk_fma_f32 v[26:27], v[26:27], v[100:101], v[108:109]
	v_pk_fma_f32 v[24:25], v[24:25], v[98:99], v[106:107]
	s_mov_b64 s[38:39], s[48:49]
	v_pk_fma_f32 v[10:11], v[10:11], v[100:101], v[74:75]
	v_pk_fma_f32 v[8:9], v[8:9], v[98:99], v[72:73]
	v_pk_fma_f32 v[6:7], v[6:7], v[94:95], v[70:71]
	v_pk_fma_f32 v[4:5], v[4:5], v[92:93], v[68:69]
	v_pk_fma_f32 v[62:63], v[62:63], v[104:105], v[152:153]
	v_pk_fma_f32 v[60:61], v[60:61], v[102:103], v[150:151]
	global_store_dwordx4 v[148:149], v[60:63], off
	global_store_dwordx4 v[52:53], v[28:31], off offset:576
	global_store_dwordx4 v[52:53], v[36:39], off offset:512
	global_store_dwordx4 v[52:53], v[44:47], off
	v_cndmask_b32_e64 v29, v243, v244, s[0:1]
	v_cndmask_b32_e64 v28, v245, v246, s[0:1]
	v_lshl_add_u64 v[28:29], v[28:29], 0, v[144:145]
	v_lshl_add_u64 v[36:37], v[28:29], 0, v[214:215]
	global_store_dwordx4 v[52:53], v[40:43], off offset:64
	global_store_dwordx4 v[36:37], v[12:15], off offset:576
	v_pk_fma_f32 v[30:31], v[34:35], v[104:105], v[112:113]
	v_pk_fma_f32 v[28:29], v[32:33], v[102:103], v[110:111]
	v_cndmask_b32_e32 v13, v243, v244, vcc
	v_cndmask_b32_e32 v12, v245, v246, vcc
	v_lshl_add_u64 v[12:13], v[12:13], 0, v[142:143]
	global_store_dwordx4 v[36:37], v[20:23], off offset:512
	v_pk_fma_f32 v[14:15], v[18:19], v[104:105], v[78:79]
	v_pk_fma_f32 v[2:3], v[2:3], v[86:87], v[66:67]
	v_lshl_add_u64 v[20:21], v[12:13], 0, v[214:215]
	v_pk_fma_f32 v[12:13], v[16:17], v[102:103], v[76:77]
	v_pk_fma_f32 v[0:1], v[0:1], v[84:85], v[64:65]
	s_and_b64 vcc, exec, s[36:37]
	s_mov_b32 s1, s44
	s_mov_b32 s0, s46
	global_store_dwordx4 v[36:37], v[28:31], off
	global_store_dwordx4 v[36:37], v[24:27], off offset:64
	global_store_dwordx4 v[20:21], v[12:15], off
	global_store_dwordx4 v[20:21], v[8:11], off offset:64
	global_store_dwordx4 v[20:21], v[4:7], off offset:512
	global_store_dwordx4 v[20:21], v[0:3], off offset:576
	s_cbranch_vccz .LBB0_84
	s_waitcnt vmcnt(0)
	v_readlane_b32 s0, v255, 48
	v_readlane_b32 s66, v255, 34
	v_readlane_b32 s68, v255, 36
	s_cmpk_gt_u32 s0, 0xff
	v_readlane_b32 s67, v255, 35
	v_readlane_b32 s69, v255, 37
	v_readlane_b32 s70, v255, 41
	s_mov_b64 s[78:79], 0
	s_cbranch_scc1 .LBB0_91
	s_barrier

; #define PG8_STAGE(bufoff, gbase, voff) do { _Pragma("unroll") for (int _i = 0; _i < 2; ++_i) \
;         __builtin_amdgcn_global_load_lds((const unsigned*)((const char*)(gbase) + (voff)[_i]), (PG8_LAS unsigned*)(lds + (bufoff) + ldsw + _i * 8192), 16, 0, 0); } while (0)
; #define PG8_LDA(dst, b, h) do { _Pragma("unroll") for (int m = 0; m < 4; ++m) _Pragma("unroll") for (int k = 0; k < 2; ++k) dst[m][k] = *(const PG8_LAS bf16x8*)(lds + PG8_SA(b, h) + aoff + m * 2048 + k * 1024); } while (0)
; #define PG8_LDB(dst, b, h) do { _Pragma("unroll") for (int n = 0; n < 2; ++n) _Pragma("unroll") for (int k = 0; k < 2; ++k) dst[n][k] = *(const PG8_LAS bf16x8*)(lds + PG8_SB(b, h) + boff + n * 2048 + k * 1024); } while (0)
; #define PG8_WAIT_V(n) asm volatile("s_waitcnt vmcnt(" #n ")" ::: "memory")
; #define PG8_WAIT_L(n) asm volatile("s_waitcnt lgkmcnt(" #n ")" ::: "memory")
; #define PG8_BAR __builtin_amdgcn_s_barrier()
; #define PG8_SCHED __builtin_amdgcn_sched_barrier(0)
; template <class Epi, class Sched>
; __device__ __forceinline__ void gemm_phase(PG8_LAS unsigned char* lds, const Gemm g, const Sched& S, const Epi& E) {
;     ...
;         for (int t = 0; t < nt; t += 2) {
;             const bool last = (t == nt - 2);
;             const char* a1 = cA + (size_t)(t + 1) * kstep;
;             const char* a2 = last ? nA : cA + (size_t)(t + 2) * kstep; const char* b2 = last ? nB : cB + (size_t)(t + 2) * kstep;
;             const char* a3 = a2 + kstep; const char* b3 = b2 + kstep;
;             if (last && has_next) S.a_ready(nxt);
;             PG8_LDB(B0, 0, 0); PG8_SCHED; PG8_LDA(At, 0, 0); PG8_STAGE(PG8_SA(1, 1), a1 + hstep, voffA);
;             PG8_WAIT_L(8); PG8_BAR; PG8_WAIT_L(0); PG8_MMA(0, 0, At, B0); PG8_BAR; PG8_SCHED;
;             PG8_LDB(B1, 0, 1); PG8_STAGE(PG8_SB(0, 0), b2, voffB);
;             PG8_BAR; PG8_WAIT_L(0); PG8_MMA(0, 1, At, B1); PG8_BAR;
;             PG8_LDA(At, 0, 1); PG8_STAGE(PG8_SA(0, 0), a2, voffA);
;             PG8_BAR; PG8_WAIT_L(0); PG8_MMA(1, 0, At, B0); PG8_BAR; PG8_SCHED;
;             PG8_STAGE(PG8_SB(0, 1), b2 + hstep, voffB);
;             PG8_WAIT_V(6); PG8_BAR; PG8_MMA(1, 1, At, B1); PG8_BAR;
;             PG8_LDB(B0, 1, 0); PG8_SCHED; PG8_LDA(At, 1, 0); PG8_STAGE(PG8_SA(0, 1), a2 + hstep, voffA);
;             PG8_WAIT_L(8); PG8_BAR; PG8_WAIT_L(0); PG8_MMA(0, 0, At, B0); PG8_BAR; PG8_SCHED;
.Lgp_5880:
.LBB0_105:
	s_add_u32 s50, s48, 0xfffe0080
	s_addc_u32 s51, s49, -1
	s_add_i32 s70, 0, 0x10000
	v_add_u32_e32 v96, s70, v221
	ds_read_b128 v[130:133], v96
	ds_read_b128 v[134:137], v96 offset:1024
	ds_read_b128 v[138:141], v96 offset:2048
	ds_read_b128 v[142:145], v96 offset:3072
	s_cmp_eq_u32 s69, 4
	s_cselect_b32 s53, s1, s51
	s_cselect_b32 s52, s39, s50
	s_cselect_b32 s51, s31, s68
	s_cselect_b32 s50, s47, s67
	v_lshl_add_u64 v[178:179], s[48:49], 0, v[204:205]
	s_add_i32 m0, s59, 0xc000
	ds_read_b128 v[146:149], v223
	ds_read_b128 v[154:157], v223 offset:2048
	ds_read_b128 v[162:165], v223 offset:4096
	ds_read_b128 v[170:173], v223 offset:6144
	ds_read_b128 v[150:153], v223 offset:1024
	ds_read_b128 v[158:161], v223 offset:3072
	ds_read_b128 v[166:169], v223 offset:5120
	ds_read_b128 v[174:177], v223 offset:7168
	global_load_lds_dwordx4 v[178:179], off
	v_lshl_add_u64 v[178:179], s[48:49], 0, v[208:209]
	s_add_i32 m0, s59, 0xe000
	s_nop 0
	global_load_lds_dwordx4 v[178:179], off
	s_waitcnt lgkmcnt(8)
	s_barrier
	s_waitcnt lgkmcnt(7)
	v_mfma_f32_16x16x32_bf16 v[126:129], v[130:133], v[146:149], v[126:129]
	v_mfma_f32_16x16x32_bf16 v[122:125], v[138:141], v[146:149], v[122:125]
	s_waitcnt lgkmcnt(6)
	v_mfma_f32_16x16x32_bf16 v[110:113], v[130:133], v[154:157], v[110:113]
	v_mfma_f32_16x16x32_bf16 v[106:109], v[138:141], v[154:157], v[106:109]
	s_waitcnt lgkmcnt(5)
	v_mfma_f32_16x16x32_bf16 v[92:95], v[130:133], v[162:165], v[92:95]
	v_mfma_f32_16x16x32_bf16 v[88:91], v[138:141], v[162:165], v[88:91]
	s_waitcnt lgkmcnt(4)
	v_mfma_f32_16x16x32_bf16 v[76:79], v[130:133], v[170:173], v[76:79]
	v_mfma_f32_16x16x32_bf16 v[72:75], v[138:141], v[170:173], v[72:75]
	s_waitcnt lgkmcnt(3)
	v_mfma_f32_16x16x32_bf16 v[126:129], v[134:137], v[150:153], v[126:129]
	v_mfma_f32_16x16x32_bf16 v[122:125], v[142:145], v[150:153], v[122:125]
	s_waitcnt lgkmcnt(2)
	v_mfma_f32_16x16x32_bf16 v[110:113], v[134:137], v[158:161], v[110:113]
	v_mfma_f32_16x16x32_bf16 v[106:109], v[142:145], v[158:161], v[106:109]
	s_waitcnt lgkmcnt(1)
	v_mfma_f32_16x16x32_bf16 v[92:95], v[134:137], v[166:169], v[92:95]
	v_mfma_f32_16x16x32_bf16 v[88:91], v[142:145], v[166:169], v[88:91]
	s_waitcnt lgkmcnt(0)
	v_mfma_f32_16x16x32_bf16 v[76:79], v[134:137], v[174:177], v[76:79]
	v_mfma_f32_16x16x32_bf16 v[72:75], v[142:145], v[174:177], v[72:75]
	s_barrier
	s_add_i32 s94, 0, 0x14000
	s_add_i32 s70, s70, s58
	v_add_u32_e32 v96, s94, v221
	v_lshl_add_u64 v[194:195], s[50:51], 0, v[198:199]
	s_mov_b32 m0, s70
	ds_read_b128 v[178:181], v96
	ds_read_b128 v[186:189], v96 offset:2048
	ds_read_b128 v[182:185], v96 offset:1024
	ds_read_b128 v[190:193], v96 offset:3072
	global_load_lds_dwordx4 v[194:195], off
	v_lshl_add_u64 v[210:211], s[50:51], 0, v[202:203]
	s_add_i32 m0, s70, 0x2000
	s_nop 0
	global_load_lds_dwordx4 v[210:211], off
	s_barrier
	s_waitcnt lgkmcnt(3)
	v_mfma_f32_16x16x32_bf16 v[118:121], v[178:181], v[146:149], v[118:121]
	s_waitcnt lgkmcnt(2)
	v_mfma_f32_16x16x32_bf16 v[114:117], v[186:189], v[146:149], v[114:117]
	v_mfma_f32_16x16x32_bf16 v[102:105], v[178:181], v[154:157], v[102:105]
	v_mfma_f32_16x16x32_bf16 v[98:101], v[186:189], v[154:157], v[98:101]
	v_mfma_f32_16x16x32_bf16 v[84:87], v[178:181], v[162:165], v[84:87]
	v_mfma_f32_16x16x32_bf16 v[80:83], v[186:189], v[162:165], v[80:83]
	v_mfma_f32_16x16x32_bf16 v[68:71], v[178:181], v[170:173], v[68:71]
	v_mfma_f32_16x16x32_bf16 v[64:67], v[186:189], v[170:173], v[64:67]
	s_waitcnt lgkmcnt(1)
	v_mfma_f32_16x16x32_bf16 v[118:121], v[182:185], v[150:153], v[118:121]
	s_waitcnt lgkmcnt(0)
	v_mfma_f32_16x16x32_bf16 v[114:117], v[190:193], v[150:153], v[114:117]
	v_mfma_f32_16x16x32_bf16 v[102:105], v[182:185], v[158:161], v[102:105]
	v_mfma_f32_16x16x32_bf16 v[98:101], v[190:193], v[158:161], v[98:101]
	v_mfma_f32_16x16x32_bf16 v[84:87], v[182:185], v[166:169], v[84:87]
	v_mfma_f32_16x16x32_bf16 v[80:83], v[190:193], v[166:169], v[80:83]
	v_mfma_f32_16x16x32_bf16 v[68:71], v[182:185], v[174:177], v[68:71]
	v_mfma_f32_16x16x32_bf16 v[64:67], v[190:193], v[174:177], v[64:67]
	s_mov_b32 m0, s59
	v_lshl_add_u64 v[212:213], s[52:53], 0, v[196:197]
	s_barrier
	ds_read_b128 v[146:149], v223 offset:16384
	ds_read_b128 v[154:157], v223 offset:18432
	ds_read_b128 v[162:165], v223 offset:20480
	ds_read_b128 v[170:173], v223 offset:22528
	ds_read_b128 v[150:153], v223 offset:17408
	ds_read_b128 v[158:161], v223 offset:19456
	ds_read_b128 v[166:169], v223 offset:21504
	ds_read_b128 v[174:177], v223 offset:23552
	global_load_lds_dwordx4 v[212:213], off
	v_lshl_add_u64 v[214:215], s[52:53], 0, v[200:201]
	s_mov_b32 m0, s60
	s_nop 0
	global_load_lds_dwordx4 v[214:215], off
	s_barrier
	s_waitcnt lgkmcnt(7)
	v_mfma_f32_16x16x32_bf16 v[60:63], v[130:133], v[146:149], v[60:63]
	v_mfma_f32_16x16x32_bf16 v[56:59], v[138:141], v[146:149], v[56:59]
	s_waitcnt lgkmcnt(6)
	v_mfma_f32_16x16x32_bf16 v[44:47], v[130:133], v[154:157], v[44:47]
	v_mfma_f32_16x16x32_bf16 v[40:43], v[138:141], v[154:157], v[40:43]
	s_waitcnt lgkmcnt(5)
	v_mfma_f32_16x16x32_bf16 v[28:31], v[130:133], v[162:165], v[28:31]
	v_mfma_f32_16x16x32_bf16 v[24:27], v[138:141], v[162:165], v[24:27]
	s_waitcnt lgkmcnt(4)
	v_mfma_f32_16x16x32_bf16 v[12:15], v[130:133], v[170:173], v[12:15]
	v_mfma_f32_16x16x32_bf16 v[8:11], v[138:141], v[170:173], v[8:11]
	s_waitcnt lgkmcnt(3)
	v_mfma_f32_16x16x32_bf16 v[60:63], v[134:137], v[150:153], v[60:63]
	v_mfma_f32_16x16x32_bf16 v[56:59], v[142:145], v[150:153], v[56:59]
	s_waitcnt lgkmcnt(2)
	v_mfma_f32_16x16x32_bf16 v[44:47], v[134:137], v[158:161], v[44:47]
	v_mfma_f32_16x16x32_bf16 v[40:43], v[142:145], v[158:161], v[40:43]
	s_waitcnt lgkmcnt(1)
	v_mfma_f32_16x16x32_bf16 v[28:31], v[134:137], v[166:169], v[28:31]
	v_mfma_f32_16x16x32_bf16 v[24:27], v[142:145], v[166:169], v[24:27]
	s_waitcnt lgkmcnt(0)
	v_mfma_f32_16x16x32_bf16 v[12:15], v[134:137], v[174:177], v[12:15]
	v_mfma_f32_16x16x32_bf16 v[8:11], v[142:145], v[174:177], v[8:11]
	s_barrier
; #define PG8_STAGE(bufoff, gbase, voff) do { _Pragma("unroll") for (int _i = 0; _i < 2; ++_i) \
;         __builtin_amdgcn_global_load_lds((const unsigned*)((const char*)(gbase) + (voff)[_i]), (PG8_LAS unsigned*)(lds + (bufoff) + ldsw + _i * 8192), 16, 0, 0); } while (0)
; #define PG8_LDA(dst, b, h) do { _Pragma("unroll") for (int m = 0; m < 4; ++m) _Pragma("unroll") for (int k = 0; k < 2; ++k) dst[m][k] = *(const PG8_LAS bf16x8*)(lds + PG8_SA(b, h) + aoff + m * 2048 + k * 1024); } while (0)
; #define PG8_LDB(dst, b, h) do { _Pragma("unroll") for (int n = 0; n < 2; ++n) _Pragma("unroll") for (int k = 0; k < 2; ++k) dst[n][k] = *(const PG8_LAS bf16x8*)(lds + PG8_SB(b, h) + boff + n * 2048 + k * 1024); } while (0)
; #define PG8_MMA(ai, bj, At, Bt) do { __builtin_amdgcn_s_setprio(1); _Pragma("unroll") for (int m = 0; m < 4; ++m) _Pragma("unroll") for (int n = 0; n < 2; ++n) _Pragma("unroll") for (int k = 0; k < 2; ++k) \
;         acc[ai][bj][m][n] = __builtin_amdgcn_mfma_f32_16x16x32_bf16(Bt[n][k], At[m][k], acc[ai][bj][m][n], 0, 0, 0); __builtin_amdgcn_s_setprio(0); } while (0)
; #define PG8_WAIT_V(n) asm volatile("s_waitcnt vmcnt(" #n ")" ::: "memory")
; #define PG8_WAIT_L(n) asm volatile("s_waitcnt lgkmcnt(" #n ")" ::: "memory")
; #define PG8_BAR __builtin_amdgcn_s_barrier()
; #define PG8_SCHED __builtin_amdgcn_sched_barrier(0)
; template <class Epi, class Sched>
; __device__ __forceinline__ void gemm_phase(PG8_LAS unsigned char* lds, const Gemm g, const Sched& S, const Epi& E) {
;     ...
;             PG8_WAIT_V(6); PG8_BAR; PG8_MMA(1, 1, At, B1); PG8_BAR;
;             PG8_LDB(B0, 1, 0); PG8_SCHED; PG8_LDA(At, 1, 0); PG8_STAGE(PG8_SA(0, 1), a2 + hstep, voffA);
;             PG8_WAIT_L(8); PG8_BAR; PG8_WAIT_L(0); PG8_MMA(0, 0, At, B0); PG8_BAR; PG8_SCHED;
;             PG8_LDB(B1, 1, 1); PG8_STAGE(PG8_SB(1, 0), b3, voffB);
;             PG8_BAR; PG8_WAIT_L(0); PG8_MMA(0, 1, At, B1); PG8_BAR;
;             PG8_LDA(At, 1, 1); PG8_STAGE(PG8_SA(1, 0), a3, voffA);
;             PG8_BAR; PG8_WAIT_L(0); PG8_MMA(1, 0, At, B0); PG8_BAR; PG8_SCHED;
;             PG8_STAGE(PG8_SB(1, 1), b3 + hstep, voffB);
	s_add_u32 s70, s50, 0x20000
	s_addc_u32 s71, s51, 0
	s_add_i32 s94, s94, s58
	v_lshl_add_u64 v[130:131], s[70:71], 0, v[198:199]
	s_mov_b32 m0, s94
	s_nop 0
	global_load_lds_dwordx4 v[130:131], off
	v_lshl_add_u64 v[130:131], s[70:71], 0, v[202:203]
	s_add_i32 m0, s94, 0x2000
	s_nop 0
	global_load_lds_dwordx4 v[130:131], off
	s_waitcnt vmcnt(6)
	s_barrier
	v_mfma_f32_16x16x32_bf16 v[52:55], v[178:181], v[146:149], v[52:55]
	v_mfma_f32_16x16x32_bf16 v[48:51], v[186:189], v[146:149], v[48:51]
	v_mfma_f32_16x16x32_bf16 v[36:39], v[178:181], v[154:157], v[36:39]
	v_mfma_f32_16x16x32_bf16 v[32:35], v[186:189], v[154:157], v[32:35]
	v_mfma_f32_16x16x32_bf16 v[20:23], v[178:181], v[162:165], v[20:23]
	v_mfma_f32_16x16x32_bf16 v[16:19], v[186:189], v[162:165], v[16:19]
	v_mfma_f32_16x16x32_bf16 v[4:7], v[178:181], v[170:173], v[4:7]
	v_mfma_f32_16x16x32_bf16 v[0:3], v[186:189], v[170:173], v[0:3]
	v_mfma_f32_16x16x32_bf16 v[52:55], v[182:185], v[150:153], v[52:55]
	v_mfma_f32_16x16x32_bf16 v[48:51], v[190:193], v[150:153], v[48:51]
	v_mfma_f32_16x16x32_bf16 v[36:39], v[182:185], v[158:161], v[36:39]
	v_mfma_f32_16x16x32_bf16 v[32:35], v[190:193], v[158:161], v[32:35]
	v_mfma_f32_16x16x32_bf16 v[20:23], v[182:185], v[166:169], v[20:23]
	v_mfma_f32_16x16x32_bf16 v[16:19], v[190:193], v[166:169], v[16:19]
	v_mfma_f32_16x16x32_bf16 v[4:7], v[182:185], v[174:177], v[4:7]
	v_mfma_f32_16x16x32_bf16 v[0:3], v[190:193], v[174:177], v[0:3]
	s_add_i32 s70, 0, 0x18000
	v_add_u32_e32 v96, s70, v221
	s_barrier
	ds_read_b128 v[130:133], v96
	ds_read_b128 v[134:137], v96 offset:1024
	ds_read_b128 v[138:141], v96 offset:2048
	ds_read_b128 v[142:145], v96 offset:3072
	s_add_u32 s52, s52, 0x20000
	s_addc_u32 s53, s53, 0
	s_mov_b32 m0, s61
	v_lshl_add_u64 v[178:179], s[52:53], 0, v[196:197]
	ds_read_b128 v[146:149], v223 offset:32768
	ds_read_b128 v[154:157], v223 offset:34816
	ds_read_b128 v[162:165], v223 offset:36864
	ds_read_b128 v[170:173], v223 offset:38912
	ds_read_b128 v[150:153], v223 offset:33792
	ds_read_b128 v[158:161], v223 offset:35840
	ds_read_b128 v[166:169], v223 offset:37888
	ds_read_b128 v[174:177], v223 offset:39936
	global_load_lds_dwordx4 v[178:179], off
	v_lshl_add_u64 v[178:179], s[52:53], 0, v[200:201]
	s_mov_b32 m0, s62
	s_nop 0
	global_load_lds_dwordx4 v[178:179], off
	s_waitcnt lgkmcnt(8)
	s_barrier
	s_waitcnt lgkmcnt(7)
	v_mfma_f32_16x16x32_bf16 v[126:129], v[130:133], v[146:149], v[126:129]
	v_mfma_f32_16x16x32_bf16 v[122:125], v[138:141], v[146:149], v[122:125]
	s_waitcnt lgkmcnt(6)
	v_mfma_f32_16x16x32_bf16 v[110:113], v[130:133], v[154:157], v[110:113]
	v_mfma_f32_16x16x32_bf16 v[106:109], v[138:141], v[154:157], v[106:109]
	s_waitcnt lgkmcnt(5)
	v_mfma_f32_16x16x32_bf16 v[92:95], v[130:133], v[162:165], v[92:95]
	v_mfma_f32_16x16x32_bf16 v[88:91], v[138:141], v[162:165], v[88:91]
	s_waitcnt lgkmcnt(4)
	v_mfma_f32_16x16x32_bf16 v[76:79], v[130:133], v[170:173], v[76:79]
	v_mfma_f32_16x16x32_bf16 v[72:75], v[138:141], v[170:173], v[72:75]
	s_waitcnt lgkmcnt(3)
	v_mfma_f32_16x16x32_bf16 v[126:129], v[134:137], v[150:153], v[126:129]
	v_mfma_f32_16x16x32_bf16 v[122:125], v[142:145], v[150:153], v[122:125]
	s_waitcnt lgkmcnt(2)
	v_mfma_f32_16x16x32_bf16 v[110:113], v[134:137], v[158:161], v[110:113]
	v_mfma_f32_16x16x32_bf16 v[106:109], v[142:145], v[158:161], v[106:109]
	s_waitcnt lgkmcnt(1)
	v_mfma_f32_16x16x32_bf16 v[92:95], v[134:137], v[166:169], v[92:95]
	v_mfma_f32_16x16x32_bf16 v[88:91], v[142:145], v[166:169], v[88:91]
	s_waitcnt lgkmcnt(0)
	v_mfma_f32_16x16x32_bf16 v[76:79], v[134:137], v[174:177], v[76:79]
	v_mfma_f32_16x16x32_bf16 v[72:75], v[142:145], v[174:177], v[72:75]
	s_barrier
	s_add_i32 s52, 0, 0x1c000
	s_add_i32 s53, s70, s58
	v_add_u32_e32 v96, s52, v221
	v_lshl_add_u64 v[194:195], v[194:195], 0, s[2:3]
	s_mov_b32 m0, s53
	ds_read_b128 v[178:181], v96
	ds_read_b128 v[186:189], v96 offset:2048
	ds_read_b128 v[182:185], v96 offset:1024
	ds_read_b128 v[190:193], v96 offset:3072
	global_load_lds_dwordx4 v[194:195], off
	v_lshl_add_u64 v[194:195], v[210:211], 0, s[2:3]
	s_add_i32 m0, s53, 0x2000
	s_nop 0
	global_load_lds_dwordx4 v[194:195], off
	s_barrier
	s_waitcnt lgkmcnt(3)
	v_mfma_f32_16x16x32_bf16 v[118:121], v[178:181], v[146:149], v[118:121]
	s_waitcnt lgkmcnt(2)
	v_mfma_f32_16x16x32_bf16 v[114:117], v[186:189], v[146:149], v[114:117]
	v_mfma_f32_16x16x32_bf16 v[102:105], v[178:181], v[154:157], v[102:105]
	v_mfma_f32_16x16x32_bf16 v[98:101], v[186:189], v[154:157], v[98:101]
	v_mfma_f32_16x16x32_bf16 v[84:87], v[178:181], v[162:165], v[84:87]
	v_mfma_f32_16x16x32_bf16 v[80:83], v[186:189], v[162:165], v[80:83]
	v_mfma_f32_16x16x32_bf16 v[68:71], v[178:181], v[170:173], v[68:71]
	v_mfma_f32_16x16x32_bf16 v[64:67], v[186:189], v[170:173], v[64:67]
	s_waitcnt lgkmcnt(1)
	v_mfma_f32_16x16x32_bf16 v[118:121], v[182:185], v[150:153], v[118:121]
	s_waitcnt lgkmcnt(0)
	v_mfma_f32_16x16x32_bf16 v[114:117], v[190:193], v[150:153], v[114:117]
	v_mfma_f32_16x16x32_bf16 v[102:105], v[182:185], v[158:161], v[102:105]
	v_mfma_f32_16x16x32_bf16 v[98:101], v[190:193], v[158:161], v[98:101]
	v_mfma_f32_16x16x32_bf16 v[84:87], v[182:185], v[166:169], v[84:87]
	v_mfma_f32_16x16x32_bf16 v[80:83], v[190:193], v[166:169], v[80:83]
	v_mfma_f32_16x16x32_bf16 v[68:71], v[182:185], v[174:177], v[68:71]
	v_mfma_f32_16x16x32_bf16 v[64:67], v[190:193], v[174:177], v[64:67]
	s_mov_b32 m0, s63
	v_lshl_add_u64 v[194:195], v[212:213], 0, s[2:3]
	s_barrier
; #define PG8_STAGE(bufoff, gbase, voff) do { _Pragma("unroll") for (int _i = 0; _i < 2; ++_i) \
;         __builtin_amdgcn_global_load_lds((const unsigned*)((const char*)(gbase) + (voff)[_i]), (PG8_LAS unsigned*)(lds + (bufoff) + ldsw + _i * 8192), 16, 0, 0); } while (0)
; #define PG8_LDA(dst, b, h) do { _Pragma("unroll") for (int m = 0; m < 4; ++m) _Pragma("unroll") for (int k = 0; k < 2; ++k) dst[m][k] = *(const PG8_LAS bf16x8*)(lds + PG8_SA(b, h) + aoff + m * 2048 + k * 1024); } while (0)
; #define PG8_LDB(dst, b, h) do { _Pragma("unroll") for (int n = 0; n < 2; ++n) _Pragma("unroll") for (int k = 0; k < 2; ++k) dst[n][k] = *(const PG8_LAS bf16x8*)(lds + PG8_SB(b, h) + boff + n * 2048 + k * 1024); } while (0)
; template <class Epi, class Sched>
; __device__ __forceinline__ void gemm_phase(PG8_LAS unsigned char* lds, const Gemm g, const Sched& S, const Epi& E) {
;     ...
;             PG8_LDB(B0, 1, 0); PG8_SCHED; PG8_LDA(At, 1, 0); PG8_STAGE(PG8_SA(0, 1), a2 + hstep, voffA);
;             PG8_WAIT_L(8); PG8_BAR; PG8_WAIT_L(0); PG8_MMA(0, 0, At, B0); PG8_BAR; PG8_SCHED;
;             PG8_LDB(B1, 1, 1); PG8_STAGE(PG8_SB(1, 0), b3, voffB);
;             PG8_BAR; PG8_WAIT_L(0); PG8_MMA(0, 1, At, B1); PG8_BAR;
;             PG8_LDA(At, 1, 1); PG8_STAGE(PG8_SA(1, 0), a3, voffA);
;             PG8_BAR; PG8_WAIT_L(0); PG8_MMA(1, 0, At, B0); PG8_BAR; PG8_SCHED;
;             PG8_STAGE(PG8_SB(1, 1), b3 + hstep, voffB);
;             PG8_WAIT_V(6); PG8_BAR; PG8_MMA(1, 1, At, B1); PG8_BAR;
;   DEV void operator()(const f32x4 (&acc)[2][2][4][2], const pg8::Unit& u, int wr, int wc, int fr, int fq) const {
;     const int b = u.pn >> 2, pn = u.pn & 3, pm = u.pm - 136 * (b == 0 ? 11 : (b == 1 ? 12 : 6));
;     const bf16_t* G = (const bf16_t*)(ws + (b == 0 ? O_G1 : (b == 1 ? O_G2 : O_G3)));
;     bf16_t* M = (bf16_t*)(ws + O_M);
;     const int row0 = pm * 256 + wr * 64 + fr, col0 = pn * 256 + wc * 32 + 8 * fq;
; #pragma unroll
;     for (int ai = 0; ai < 2; ++ai) {
;       u32x4 gv[4][2], mv[4][2];
; #pragma unroll
;       for (int m = 0; m < 4; ++m)
; #pragma unroll
;         for (int bj = 0; bj < 2; ++bj) {
;           const size_t off = (size_t)(row0 + ai * 128 + m * 16) * DM + col0 + bj * 128;
;           gv[m][bj] = *(const u32x4*)(G + off);
;           mv[m][bj] = (u32x4){0u, 0u, 0u, 0u};
;           if (b > 0) mv[m][bj] = *(const u32x4*)(M + off);
	ds_read_b128 v[146:149], v223 offset:49152
	ds_read_b128 v[154:157], v223 offset:51200
	ds_read_b128 v[162:165], v223 offset:53248
	ds_read_b128 v[170:173], v223 offset:55296
	ds_read_b128 v[150:153], v223 offset:50176
	ds_read_b128 v[158:161], v223 offset:52224
	ds_read_b128 v[166:169], v223 offset:54272
	ds_read_b128 v[174:177], v223 offset:56320
	global_load_lds_dwordx4 v[194:195], off
	v_lshl_add_u64 v[194:195], v[214:215], 0, s[2:3]
	s_mov_b32 m0, s64
	s_nop 0
	global_load_lds_dwordx4 v[194:195], off
	s_barrier
	s_waitcnt lgkmcnt(7)
	v_mfma_f32_16x16x32_bf16 v[60:63], v[130:133], v[146:149], v[60:63]
	v_mfma_f32_16x16x32_bf16 v[56:59], v[138:141], v[146:149], v[56:59]
	s_waitcnt lgkmcnt(6)
	v_mfma_f32_16x16x32_bf16 v[44:47], v[130:133], v[154:157], v[44:47]
	v_mfma_f32_16x16x32_bf16 v[40:43], v[138:141], v[154:157], v[40:43]
	s_waitcnt lgkmcnt(5)
	v_mfma_f32_16x16x32_bf16 v[28:31], v[130:133], v[162:165], v[28:31]
	v_mfma_f32_16x16x32_bf16 v[24:27], v[138:141], v[162:165], v[24:27]
	s_waitcnt lgkmcnt(4)
	v_mfma_f32_16x16x32_bf16 v[12:15], v[130:133], v[170:173], v[12:15]
	v_mfma_f32_16x16x32_bf16 v[8:11], v[138:141], v[170:173], v[8:11]
	s_waitcnt lgkmcnt(3)
	v_mfma_f32_16x16x32_bf16 v[60:63], v[134:137], v[150:153], v[60:63]
	v_mfma_f32_16x16x32_bf16 v[56:59], v[142:145], v[150:153], v[56:59]
	s_waitcnt lgkmcnt(2)
	v_mfma_f32_16x16x32_bf16 v[44:47], v[134:137], v[158:161], v[44:47]
	v_mfma_f32_16x16x32_bf16 v[40:43], v[142:145], v[158:161], v[40:43]
	s_waitcnt lgkmcnt(1)
	v_mfma_f32_16x16x32_bf16 v[28:31], v[134:137], v[166:169], v[28:31]
	v_mfma_f32_16x16x32_bf16 v[24:27], v[142:145], v[166:169], v[24:27]
	s_waitcnt lgkmcnt(0)
	v_mfma_f32_16x16x32_bf16 v[12:15], v[134:137], v[174:177], v[12:15]
	v_mfma_f32_16x16x32_bf16 v[8:11], v[142:145], v[174:177], v[8:11]
	s_barrier
	s_add_u32 s50, s50, 0x20080
	s_addc_u32 s51, s51, 0
	s_add_i32 s52, s52, s58
	v_lshl_add_u64 v[130:131], s[50:51], 0, v[198:199]
	s_mov_b32 m0, s52
	s_nop 0
	global_load_lds_dwordx4 v[130:131], off
	v_lshl_add_u64 v[130:131], s[50:51], 0, v[202:203]
	s_add_i32 m0, s52, 0x2000
	s_nop 0
	global_load_lds_dwordx4 v[130:131], off
	s_waitcnt vmcnt(6)
	s_barrier
	v_mfma_f32_16x16x32_bf16 v[52:55], v[178:181], v[146:149], v[52:55]
	v_mfma_f32_16x16x32_bf16 v[48:51], v[186:189], v[146:149], v[48:51]
	v_mfma_f32_16x16x32_bf16 v[36:39], v[178:181], v[154:157], v[36:39]
	v_mfma_f32_16x16x32_bf16 v[32:35], v[186:189], v[154:157], v[32:35]
	v_mfma_f32_16x16x32_bf16 v[20:23], v[178:181], v[162:165], v[20:23]
	v_mfma_f32_16x16x32_bf16 v[16:19], v[186:189], v[162:165], v[16:19]
	v_mfma_f32_16x16x32_bf16 v[4:7], v[178:181], v[170:173], v[4:7]
	v_mfma_f32_16x16x32_bf16 v[0:3], v[186:189], v[170:173], v[0:3]
	v_mfma_f32_16x16x32_bf16 v[52:55], v[182:185], v[150:153], v[52:55]
	v_mfma_f32_16x16x32_bf16 v[48:51], v[190:193], v[150:153], v[48:51]
	v_mfma_f32_16x16x32_bf16 v[36:39], v[182:185], v[158:161], v[36:39]
	v_mfma_f32_16x16x32_bf16 v[32:35], v[190:193], v[158:161], v[32:35]
	v_mfma_f32_16x16x32_bf16 v[20:23], v[182:185], v[166:169], v[20:23]
	v_mfma_f32_16x16x32_bf16 v[16:19], v[190:193], v[166:169], v[16:19]
	v_mfma_f32_16x16x32_bf16 v[4:7], v[182:185], v[174:177], v[4:7]
	v_mfma_f32_16x16x32_bf16 v[0:3], v[190:193], v[174:177], v[0:3]
	s_add_i32 s69, s69, 2
	s_add_u32 s48, s48, 0x100
	s_addc_u32 s49, s49, 0
	s_add_u32 s67, s67, 0x100
	s_addc_u32 s68, s68, 0
	s_cmp_gt_u32 s69, 5
	s_barrier
	s_cbranch_scc0 .LBB0_105
	s_ashr_i32 s1, s0, 2
	s_cmp_eq_u32 s1, 1
	s_movk_i32 s31, 0xf9a0
	s_mov_b32 s39, 0xee00000
	s_cselect_b32 s31, s31, 0xfffffcd0
	s_cselect_b32 s39, s39, 0x13200000
	s_cmp_lt_u32 s0, 4
	s_cselect_b32 s31, 0xfffffa28, s31
	s_cselect_b32 s39, 0x6600000, s39
	s_add_i32 s31, s31, s46
	s_add_u32 s46, s74, s39
	s_addc_u32 s47, s75, 0
	v_lshl_add_u32 v212, s31, 8, v220
	s_lshl_b32 s0, s0, 8
	s_and_b32 s0, s0, 0x300
	v_ashrrev_i32_e32 v213, 31, v212
	v_or_b32_e32 v224, s0, v222
	v_lshlrev_b64 v[130:131], 10, v[212:213]
	v_or_b32_e32 v130, v130, v224
	v_lshl_add_u64 v[132:133], v[130:131], 1, s[46:47]
	global_load_dwordx4 v[188:191], v[132:133], off
	s_cmp_gt_i32 s1, 0
	s_cselect_b64 s[48:49], -1, 0
	s_cmp_lt_i32 s1, 1
	v_lshl_add_u64 v[130:131], v[130:131], 1, s[74:75]
	s_cbranch_scc1 .LBB0_108
	global_load_dwordx4 v[192:195], v[130:131], off
	s_branch .LBB0_109

; #define PG8_STAGE(bufoff, gbase, voff) do { _Pragma("unroll") for (int _i = 0; _i < 2; ++_i) \
;         __builtin_amdgcn_global_load_lds((const unsigned*)((const char*)(gbase) + (voff)[_i]), (PG8_LAS unsigned*)(lds + (bufoff) + ldsw + _i * 8192), 16, 0, 0); } while (0)
; #define PG8_LDA(dst, b, h) do { _Pragma("unroll") for (int m = 0; m < 4; ++m) _Pragma("unroll") for (int k = 0; k < 2; ++k) dst[m][k] = *(const PG8_LAS bf16x8*)(lds + PG8_SA(b, h) + aoff + m * 2048 + k * 1024); } while (0)
; #define PG8_LDB(dst, b, h) do { _Pragma("unroll") for (int n = 0; n < 2; ++n) _Pragma("unroll") for (int k = 0; k < 2; ++k) dst[n][k] = *(const PG8_LAS bf16x8*)(lds + PG8_SB(b, h) + boff + n * 2048 + k * 1024); } while (0)
; #define PG8_MMA(ai, bj, At, Bt) do { __builtin_amdgcn_s_setprio(1); _Pragma("unroll") for (int m = 0; m < 4; ++m) _Pragma("unroll") for (int n = 0; n < 2; ++n) _Pragma("unroll") for (int k = 0; k < 2; ++k) \
;         acc[ai][bj][m][n] = __builtin_amdgcn_mfma_f32_16x16x32_bf16(Bt[n][k], At[m][k], acc[ai][bj][m][n], 0, 0, 0); __builtin_amdgcn_s_setprio(0); } while (0)
; #define PG8_WAIT_V(n) asm volatile("s_waitcnt vmcnt(" #n ")" ::: "memory")
; #define PG8_WAIT_L(n) asm volatile("s_waitcnt lgkmcnt(" #n ")" ::: "memory")
; #define PG8_BAR __builtin_amdgcn_s_barrier()
; #define PG8_SCHED __builtin_amdgcn_sched_barrier(0)
; template <class Epi, class Sched>
; __device__ __forceinline__ void gemm_phase(PG8_LAS unsigned char* lds, const Gemm g, const Sched& S, const Epi& E) {
;     ...
;             PG8_LDB(B0, 0, 0); PG8_SCHED; PG8_LDA(At, 0, 0); PG8_STAGE(PG8_SA(1, 1), a1 + hstep, voffA);
;             PG8_WAIT_L(8); PG8_BAR; PG8_WAIT_L(0); PG8_MMA(0, 0, At, B0); PG8_BAR; PG8_SCHED;
;             PG8_LDB(B1, 0, 1); PG8_STAGE(PG8_SB(0, 0), b2, voffB);
;             PG8_BAR; PG8_WAIT_L(0); PG8_MMA(0, 1, At, B1); PG8_BAR;
;             PG8_LDA(At, 0, 1); PG8_STAGE(PG8_SA(0, 0), a2, voffA);
;             PG8_BAR; PG8_WAIT_L(0); PG8_MMA(1, 0, At, B0); PG8_BAR; PG8_SCHED;
;             PG8_STAGE(PG8_SB(0, 1), b2 + hstep, voffB);
;             PG8_WAIT_V(6); PG8_BAR; PG8_MMA(1, 1, At, B1); PG8_BAR;
.Lgp_7151:
.LBB0_152:
	s_add_u32 s48, s46, 0xfffc0080
	s_addc_u32 s49, s47, -1
	s_add_i32 s71, 0, 0x10000
	v_add_u32_e32 v96, s71, v147
	ds_read_b128 v[142:145], v96
	ds_read_b128 v[150:153], v96 offset:1024
	ds_read_b128 v[154:157], v96 offset:2048
	ds_read_b128 v[158:161], v96 offset:3072
	s_cmp_eq_u32 s70, 12
	s_cselect_b32 s51, s31, s49
	s_cselect_b32 s50, s66, s48
	s_cselect_b32 s49, s1, s69
	s_cselect_b32 s48, s67, s68
	v_lshl_add_u64 v[194:195], s[46:47], 0, v[138:139]
	s_add_i32 m0, s45, 0xc000
	ds_read_b128 v[162:165], v149
	ds_read_b128 v[170:173], v149 offset:2048
	ds_read_b128 v[178:181], v149 offset:4096
	ds_read_b128 v[186:189], v149 offset:6144
	ds_read_b128 v[166:169], v149 offset:1024
	ds_read_b128 v[174:177], v149 offset:3072
	ds_read_b128 v[182:185], v149 offset:5120
	ds_read_b128 v[190:193], v149 offset:7168
	global_load_lds_dwordx4 v[194:195], off
	v_lshl_add_u64 v[194:195], s[46:47], 0, v[140:141]
	s_add_i32 m0, s45, 0xe000
	s_nop 0
	global_load_lds_dwordx4 v[194:195], off
	s_waitcnt lgkmcnt(8)
	s_barrier
	s_waitcnt lgkmcnt(7)
	v_mfma_f32_16x16x32_bf16 v[126:129], v[142:145], v[162:165], v[126:129]
	v_mfma_f32_16x16x32_bf16 v[122:125], v[154:157], v[162:165], v[122:125]
	s_waitcnt lgkmcnt(6)
	v_mfma_f32_16x16x32_bf16 v[110:113], v[142:145], v[170:173], v[110:113]
	v_mfma_f32_16x16x32_bf16 v[106:109], v[154:157], v[170:173], v[106:109]
	s_waitcnt lgkmcnt(5)
	v_mfma_f32_16x16x32_bf16 v[92:95], v[142:145], v[178:181], v[92:95]
	v_mfma_f32_16x16x32_bf16 v[88:91], v[154:157], v[178:181], v[88:91]
	s_waitcnt lgkmcnt(4)
	v_mfma_f32_16x16x32_bf16 v[76:79], v[142:145], v[186:189], v[76:79]
	v_mfma_f32_16x16x32_bf16 v[72:75], v[154:157], v[186:189], v[72:75]
	s_waitcnt lgkmcnt(3)
	v_mfma_f32_16x16x32_bf16 v[126:129], v[150:153], v[166:169], v[126:129]
	v_mfma_f32_16x16x32_bf16 v[122:125], v[158:161], v[166:169], v[122:125]
	s_waitcnt lgkmcnt(2)
	v_mfma_f32_16x16x32_bf16 v[110:113], v[150:153], v[174:177], v[110:113]
	v_mfma_f32_16x16x32_bf16 v[106:109], v[158:161], v[174:177], v[106:109]
	s_waitcnt lgkmcnt(1)
	v_mfma_f32_16x16x32_bf16 v[92:95], v[150:153], v[182:185], v[92:95]
	v_mfma_f32_16x16x32_bf16 v[88:91], v[158:161], v[182:185], v[88:91]
	s_waitcnt lgkmcnt(0)
	v_mfma_f32_16x16x32_bf16 v[76:79], v[150:153], v[190:193], v[76:79]
	v_mfma_f32_16x16x32_bf16 v[72:75], v[158:161], v[190:193], v[72:75]
	s_barrier
	s_add_i32 s94, 0, 0x14000
	s_add_i32 s71, s71, s56
	v_add_u32_e32 v96, s94, v147
	v_lshl_add_u64 v[212:213], s[48:49], 0, v[134:135]
	s_mov_b32 m0, s71
	ds_read_b128 v[194:197], v96
	ds_read_b128 v[202:205], v96 offset:2048
	ds_read_b128 v[198:201], v96 offset:1024
	ds_read_b128 v[208:211], v96 offset:3072
	global_load_lds_dwordx4 v[212:213], off
	v_lshl_add_u64 v[214:215], s[48:49], 0, v[130:131]
	s_add_i32 m0, s71, 0x2000
	s_nop 0
	global_load_lds_dwordx4 v[214:215], off
	s_barrier
	s_waitcnt lgkmcnt(3)
	v_mfma_f32_16x16x32_bf16 v[118:121], v[194:197], v[162:165], v[118:121]
	s_waitcnt lgkmcnt(2)
	v_mfma_f32_16x16x32_bf16 v[114:117], v[202:205], v[162:165], v[114:117]
	v_mfma_f32_16x16x32_bf16 v[102:105], v[194:197], v[170:173], v[102:105]
	v_mfma_f32_16x16x32_bf16 v[98:101], v[202:205], v[170:173], v[98:101]
	v_mfma_f32_16x16x32_bf16 v[84:87], v[194:197], v[178:181], v[84:87]
	v_mfma_f32_16x16x32_bf16 v[80:83], v[202:205], v[178:181], v[80:83]
	v_mfma_f32_16x16x32_bf16 v[68:71], v[194:197], v[186:189], v[68:71]
	v_mfma_f32_16x16x32_bf16 v[64:67], v[202:205], v[186:189], v[64:67]
	s_waitcnt lgkmcnt(1)
	v_mfma_f32_16x16x32_bf16 v[118:121], v[198:201], v[166:169], v[118:121]
	s_waitcnt lgkmcnt(0)
	v_mfma_f32_16x16x32_bf16 v[114:117], v[208:211], v[166:169], v[114:117]
	v_mfma_f32_16x16x32_bf16 v[102:105], v[198:201], v[174:177], v[102:105]
	v_mfma_f32_16x16x32_bf16 v[98:101], v[208:211], v[174:177], v[98:101]
	v_mfma_f32_16x16x32_bf16 v[84:87], v[198:201], v[182:185], v[84:87]
	v_mfma_f32_16x16x32_bf16 v[80:83], v[208:211], v[182:185], v[80:83]
	v_mfma_f32_16x16x32_bf16 v[68:71], v[198:201], v[190:193], v[68:71]
	v_mfma_f32_16x16x32_bf16 v[64:67], v[208:211], v[190:193], v[64:67]
	s_mov_b32 m0, s45
	v_lshl_add_u64 v[216:217], s[50:51], 0, v[136:137]
	s_barrier
	ds_read_b128 v[162:165], v149 offset:16384
	ds_read_b128 v[170:173], v149 offset:18432
	ds_read_b128 v[178:181], v149 offset:20480
	ds_read_b128 v[186:189], v149 offset:22528
	ds_read_b128 v[166:169], v149 offset:17408
	ds_read_b128 v[174:177], v149 offset:19456
	ds_read_b128 v[182:185], v149 offset:21504
	ds_read_b128 v[190:193], v149 offset:23552
	global_load_lds_dwordx4 v[216:217], off
	v_lshl_add_u64 v[218:219], s[50:51], 0, v[132:133]
	s_mov_b32 m0, s59
	s_nop 0
	global_load_lds_dwordx4 v[218:219], off
	s_barrier
	s_waitcnt lgkmcnt(7)
	v_mfma_f32_16x16x32_bf16 v[60:63], v[142:145], v[162:165], v[60:63]
	v_mfma_f32_16x16x32_bf16 v[56:59], v[154:157], v[162:165], v[56:59]
	s_waitcnt lgkmcnt(6)
	v_mfma_f32_16x16x32_bf16 v[44:47], v[142:145], v[170:173], v[44:47]
	v_mfma_f32_16x16x32_bf16 v[40:43], v[154:157], v[170:173], v[40:43]
	s_waitcnt lgkmcnt(5)
	v_mfma_f32_16x16x32_bf16 v[28:31], v[142:145], v[178:181], v[28:31]
	v_mfma_f32_16x16x32_bf16 v[24:27], v[154:157], v[178:181], v[24:27]
	s_waitcnt lgkmcnt(4)
	v_mfma_f32_16x16x32_bf16 v[12:15], v[142:145], v[186:189], v[12:15]
	v_mfma_f32_16x16x32_bf16 v[8:11], v[154:157], v[186:189], v[8:11]
	s_waitcnt lgkmcnt(3)
	v_mfma_f32_16x16x32_bf16 v[60:63], v[150:153], v[166:169], v[60:63]
	v_mfma_f32_16x16x32_bf16 v[56:59], v[158:161], v[166:169], v[56:59]
	s_waitcnt lgkmcnt(2)
	v_mfma_f32_16x16x32_bf16 v[44:47], v[150:153], v[174:177], v[44:47]
	v_mfma_f32_16x16x32_bf16 v[40:43], v[158:161], v[174:177], v[40:43]
	s_waitcnt lgkmcnt(1)
	v_mfma_f32_16x16x32_bf16 v[28:31], v[150:153], v[182:185], v[28:31]
	v_mfma_f32_16x16x32_bf16 v[24:27], v[158:161], v[182:185], v[24:27]
	s_waitcnt lgkmcnt(0)
	v_mfma_f32_16x16x32_bf16 v[12:15], v[150:153], v[190:193], v[12:15]
	v_mfma_f32_16x16x32_bf16 v[8:11], v[158:161], v[190:193], v[8:11]
	s_barrier
; #define PG8_STAGE(bufoff, gbase, voff) do { _Pragma("unroll") for (int _i = 0; _i < 2; ++_i) \
;         __builtin_amdgcn_global_load_lds((const unsigned*)((const char*)(gbase) + (voff)[_i]), (PG8_LAS unsigned*)(lds + (bufoff) + ldsw + _i * 8192), 16, 0, 0); } while (0)
; #define PG8_LDA(dst, b, h) do { _Pragma("unroll") for (int m = 0; m < 4; ++m) _Pragma("unroll") for (int k = 0; k < 2; ++k) dst[m][k] = *(const PG8_LAS bf16x8*)(lds + PG8_SA(b, h) + aoff + m * 2048 + k * 1024); } while (0)
; #define PG8_LDB(dst, b, h) do { _Pragma("unroll") for (int n = 0; n < 2; ++n) _Pragma("unroll") for (int k = 0; k < 2; ++k) dst[n][k] = *(const PG8_LAS bf16x8*)(lds + PG8_SB(b, h) + boff + n * 2048 + k * 1024); } while (0)
; #define PG8_MMA(ai, bj, At, Bt) do { __builtin_amdgcn_s_setprio(1); _Pragma("unroll") for (int m = 0; m < 4; ++m) _Pragma("unroll") for (int n = 0; n < 2; ++n) _Pragma("unroll") for (int k = 0; k < 2; ++k) \
;         acc[ai][bj][m][n] = __builtin_amdgcn_mfma_f32_16x16x32_bf16(Bt[n][k], At[m][k], acc[ai][bj][m][n], 0, 0, 0); __builtin_amdgcn_s_setprio(0); } while (0)
; #define PG8_WAIT_V(n) asm volatile("s_waitcnt vmcnt(" #n ")" ::: "memory")
; #define PG8_WAIT_L(n) asm volatile("s_waitcnt lgkmcnt(" #n ")" ::: "memory")
; #define PG8_BAR __builtin_amdgcn_s_barrier()
; #define PG8_SCHED __builtin_amdgcn_sched_barrier(0)
; template <class Epi, class Sched>
; __device__ __forceinline__ void gemm_phase(PG8_LAS unsigned char* lds, const Gemm g, const Sched& S, const Epi& E) {
;     ...
;             PG8_STAGE(PG8_SB(0, 1), b2 + hstep, voffB);
;             PG8_WAIT_V(6); PG8_BAR; PG8_MMA(1, 1, At, B1); PG8_BAR;
;             PG8_LDB(B0, 1, 0); PG8_SCHED; PG8_LDA(At, 1, 0); PG8_STAGE(PG8_SA(0, 1), a2 + hstep, voffA);
;             PG8_WAIT_L(8); PG8_BAR; PG8_WAIT_L(0); PG8_MMA(0, 0, At, B0); PG8_BAR; PG8_SCHED;
;             PG8_LDB(B1, 1, 1); PG8_STAGE(PG8_SB(1, 0), b3, voffB);
;             PG8_BAR; PG8_WAIT_L(0); PG8_MMA(0, 1, At, B1); PG8_BAR;
;             PG8_LDA(At, 1, 1); PG8_STAGE(PG8_SA(1, 0), a3, voffA);
;             PG8_BAR; PG8_WAIT_L(0); PG8_MMA(1, 0, At, B0); PG8_BAR; PG8_SCHED;
	s_add_u32 vcc_lo, s48, 0x40000
	s_addc_u32 vcc_hi, s49, 0
	s_add_i32 s71, s94, s56
	v_lshl_add_u64 v[142:143], vcc, 0, v[134:135]
	s_mov_b32 m0, s71
	s_nop 0
	global_load_lds_dwordx4 v[142:143], off
	v_lshl_add_u64 v[142:143], vcc, 0, v[130:131]
	s_add_i32 m0, s71, 0x2000
	s_nop 0
	global_load_lds_dwordx4 v[142:143], off
	s_waitcnt vmcnt(6)
	s_barrier
	v_mfma_f32_16x16x32_bf16 v[52:55], v[194:197], v[162:165], v[52:55]
	v_mfma_f32_16x16x32_bf16 v[48:51], v[202:205], v[162:165], v[48:51]
	v_mfma_f32_16x16x32_bf16 v[36:39], v[194:197], v[170:173], v[36:39]
	v_mfma_f32_16x16x32_bf16 v[32:35], v[202:205], v[170:173], v[32:35]
	v_mfma_f32_16x16x32_bf16 v[20:23], v[194:197], v[178:181], v[20:23]
	v_mfma_f32_16x16x32_bf16 v[16:19], v[202:205], v[178:181], v[16:19]
	v_mfma_f32_16x16x32_bf16 v[4:7], v[194:197], v[186:189], v[4:7]
	v_mfma_f32_16x16x32_bf16 v[0:3], v[202:205], v[186:189], v[0:3]
	v_mfma_f32_16x16x32_bf16 v[52:55], v[198:201], v[166:169], v[52:55]
	v_mfma_f32_16x16x32_bf16 v[48:51], v[208:211], v[166:169], v[48:51]
	v_mfma_f32_16x16x32_bf16 v[36:39], v[198:201], v[174:177], v[36:39]
	v_mfma_f32_16x16x32_bf16 v[32:35], v[208:211], v[174:177], v[32:35]
	v_mfma_f32_16x16x32_bf16 v[20:23], v[198:201], v[182:185], v[20:23]
	v_mfma_f32_16x16x32_bf16 v[16:19], v[208:211], v[182:185], v[16:19]
	v_mfma_f32_16x16x32_bf16 v[4:7], v[198:201], v[190:193], v[4:7]
	v_mfma_f32_16x16x32_bf16 v[0:3], v[208:211], v[190:193], v[0:3]
	s_add_i32 s71, 0, 0x18000
	v_add_u32_e32 v96, s71, v147
	s_barrier
	ds_read_b128 v[142:145], v96
	ds_read_b128 v[150:153], v96 offset:1024
	ds_read_b128 v[154:157], v96 offset:2048
	ds_read_b128 v[158:161], v96 offset:3072
	s_add_u32 s50, s50, 0x40000
	s_addc_u32 s51, s51, 0
	s_mov_b32 m0, s60
	v_lshl_add_u64 v[194:195], s[50:51], 0, v[136:137]
	ds_read_b128 v[162:165], v149 offset:32768
	ds_read_b128 v[170:173], v149 offset:34816
	ds_read_b128 v[178:181], v149 offset:36864
	ds_read_b128 v[186:189], v149 offset:38912
	ds_read_b128 v[166:169], v149 offset:33792
	ds_read_b128 v[174:177], v149 offset:35840
	ds_read_b128 v[182:185], v149 offset:37888
	ds_read_b128 v[190:193], v149 offset:39936
	global_load_lds_dwordx4 v[194:195], off
	v_lshl_add_u64 v[194:195], s[50:51], 0, v[132:133]
	s_mov_b32 m0, s61
	s_nop 0
	global_load_lds_dwordx4 v[194:195], off
	s_waitcnt lgkmcnt(8)
	s_barrier
	s_waitcnt lgkmcnt(7)
	v_mfma_f32_16x16x32_bf16 v[126:129], v[142:145], v[162:165], v[126:129]
	v_mfma_f32_16x16x32_bf16 v[122:125], v[154:157], v[162:165], v[122:125]
	s_waitcnt lgkmcnt(6)
	v_mfma_f32_16x16x32_bf16 v[110:113], v[142:145], v[170:173], v[110:113]
	v_mfma_f32_16x16x32_bf16 v[106:109], v[154:157], v[170:173], v[106:109]
	s_waitcnt lgkmcnt(5)
	v_mfma_f32_16x16x32_bf16 v[92:95], v[142:145], v[178:181], v[92:95]
	v_mfma_f32_16x16x32_bf16 v[88:91], v[154:157], v[178:181], v[88:91]
	s_waitcnt lgkmcnt(4)
	v_mfma_f32_16x16x32_bf16 v[76:79], v[142:145], v[186:189], v[76:79]
	v_mfma_f32_16x16x32_bf16 v[72:75], v[154:157], v[186:189], v[72:75]
	s_waitcnt lgkmcnt(3)
	v_mfma_f32_16x16x32_bf16 v[126:129], v[150:153], v[166:169], v[126:129]
	v_mfma_f32_16x16x32_bf16 v[122:125], v[158:161], v[166:169], v[122:125]
	s_waitcnt lgkmcnt(2)
	v_mfma_f32_16x16x32_bf16 v[110:113], v[150:153], v[174:177], v[110:113]
	v_mfma_f32_16x16x32_bf16 v[106:109], v[158:161], v[174:177], v[106:109]
	s_waitcnt lgkmcnt(1)
	v_mfma_f32_16x16x32_bf16 v[92:95], v[150:153], v[182:185], v[92:95]
	v_mfma_f32_16x16x32_bf16 v[88:91], v[158:161], v[182:185], v[88:91]
	s_waitcnt lgkmcnt(0)
	v_mfma_f32_16x16x32_bf16 v[76:79], v[150:153], v[190:193], v[76:79]
	v_mfma_f32_16x16x32_bf16 v[72:75], v[158:161], v[190:193], v[72:75]
	s_barrier
	s_add_i32 s50, 0, 0x1c000
	s_add_i32 s51, s71, s56
	v_add_u32_e32 v96, s50, v147
	v_lshl_add_u64 v[212:213], v[212:213], 0, s[2:3]
	s_mov_b32 m0, s51
	ds_read_b128 v[194:197], v96
	ds_read_b128 v[202:205], v96 offset:2048
	ds_read_b128 v[198:201], v96 offset:1024
	ds_read_b128 v[208:211], v96 offset:3072
	global_load_lds_dwordx4 v[212:213], off
	v_lshl_add_u64 v[212:213], v[214:215], 0, s[2:3]
	s_add_i32 m0, s51, 0x2000
	s_nop 0
	global_load_lds_dwordx4 v[212:213], off
	s_barrier
	s_waitcnt lgkmcnt(3)
	v_mfma_f32_16x16x32_bf16 v[118:121], v[194:197], v[162:165], v[118:121]
	s_waitcnt lgkmcnt(2)
	v_mfma_f32_16x16x32_bf16 v[114:117], v[202:205], v[162:165], v[114:117]
	v_mfma_f32_16x16x32_bf16 v[102:105], v[194:197], v[170:173], v[102:105]
	v_mfma_f32_16x16x32_bf16 v[98:101], v[202:205], v[170:173], v[98:101]
	v_mfma_f32_16x16x32_bf16 v[84:87], v[194:197], v[178:181], v[84:87]
	v_mfma_f32_16x16x32_bf16 v[80:83], v[202:205], v[178:181], v[80:83]
	v_mfma_f32_16x16x32_bf16 v[68:71], v[194:197], v[186:189], v[68:71]
	v_mfma_f32_16x16x32_bf16 v[64:67], v[202:205], v[186:189], v[64:67]
	s_waitcnt lgkmcnt(1)
	v_mfma_f32_16x16x32_bf16 v[118:121], v[198:201], v[166:169], v[118:121]
	s_waitcnt lgkmcnt(0)
	v_mfma_f32_16x16x32_bf16 v[114:117], v[208:211], v[166:169], v[114:117]
	v_mfma_f32_16x16x32_bf16 v[102:105], v[198:201], v[174:177], v[102:105]
	v_mfma_f32_16x16x32_bf16 v[98:101], v[208:211], v[174:177], v[98:101]
	v_mfma_f32_16x16x32_bf16 v[84:87], v[198:201], v[182:185], v[84:87]
	v_mfma_f32_16x16x32_bf16 v[80:83], v[208:211], v[182:185], v[80:83]
	v_mfma_f32_16x16x32_bf16 v[68:71], v[198:201], v[190:193], v[68:71]
	v_mfma_f32_16x16x32_bf16 v[64:67], v[208:211], v[190:193], v[64:67]
	s_mov_b32 m0, s62
	v_lshl_add_u64 v[212:213], v[216:217], 0, s[2:3]
	s_barrier
; DEV float sigmoidf_(float x) { return __builtin_amdgcn_rcpf(1.f + __expf(-x)); }
; #define PG8_STAGE(bufoff, gbase, voff) do { _Pragma("unroll") for (int _i = 0; _i < 2; ++_i) \
;         __builtin_amdgcn_global_load_lds((const unsigned*)((const char*)(gbase) + (voff)[_i]), (PG8_LAS unsigned*)(lds + (bufoff) + ldsw + _i * 8192), 16, 0, 0); } while (0)
; #define PG8_LDA(dst, b, h) do { _Pragma("unroll") for (int m = 0; m < 4; ++m) _Pragma("unroll") for (int k = 0; k < 2; ++k) dst[m][k] = *(const PG8_LAS bf16x8*)(lds + PG8_SA(b, h) + aoff + m * 2048 + k * 1024); } while (0)
; #define PG8_MMA(ai, bj, At, Bt) do { __builtin_amdgcn_s_setprio(1); _Pragma("unroll") for (int m = 0; m < 4; ++m) _Pragma("unroll") for (int n = 0; n < 2; ++n) _Pragma("unroll") for (int k = 0; k < 2; ++k) \
;         acc[ai][bj][m][n] = __builtin_amdgcn_mfma_f32_16x16x32_bf16(Bt[n][k], At[m][k], acc[ai][bj][m][n], 0, 0, 0); __builtin_amdgcn_s_setprio(0); } while (0)
; #define PG8_WAIT_V(n) asm volatile("s_waitcnt vmcnt(" #n ")" ::: "memory")
; template <class Epi, class Sched>
; __device__ __forceinline__ void gemm_phase(PG8_LAS unsigned char* lds, const Gemm g, const Sched& S, const Epi& E) {
;     ...
;             PG8_LDA(At, 1, 1); PG8_STAGE(PG8_SA(1, 0), a3, voffA);
;             PG8_BAR; PG8_WAIT_L(0); PG8_MMA(1, 0, At, B0); PG8_BAR; PG8_SCHED;
;             PG8_STAGE(PG8_SB(1, 1), b3 + hstep, voffB);
;             PG8_WAIT_V(6); PG8_BAR; PG8_MMA(1, 1, At, B1); PG8_BAR;
;   DEV void operator()(const f32x4 (&acc)[2][2][4][2], const pg8::Unit& u, int wr, int wc, int fr, int fq) const {
;     const int b = u.pn >> 2, pn = u.pn & 3;
;     bf16_t* G = (bf16_t*)(ws + (b == 0 ? O_G1 : (b == 1 ? O_G2 : O_G3)));
;     const int row0 = u.pm * 256 + wr * 64 + fr, col0 = pn * 256 + wc * 32 + 8 * fq;
; #pragma unroll
;     for (int ai = 0; ai < 2; ++ai)
; #pragma unroll
;       for (int m = 0; m < 4; ++m) {
;         const int row = row0 + ai * 128 + m * 16;
; #pragma unroll
;         for (int bj = 0; bj < 2; ++bj) {
;           const f32x4 a0 = acc[ai][bj][m][0], a1 = acc[ai][bj][m][1];
;           u32x4 o;
;           o[0] = pk2(sigmoidf_(a0[0]), sigmoidf_(a0[1])); o[1] = pk2(sigmoidf_(a0[2]), sigmoidf_(a0[3]));
;           o[2] = pk2(sigmoidf_(a1[0]), sigmoidf_(a1[1])); o[3] = pk2(sigmoidf_(a1[2]), sigmoidf_(a1[3]));
;           *(u32x4*)(G + (size_t)row * DM + col0 + bj * 128) = o;
	ds_read_b128 v[162:165], v149 offset:49152
	ds_read_b128 v[170:173], v149 offset:51200
	ds_read_b128 v[178:181], v149 offset:53248
	ds_read_b128 v[186:189], v149 offset:55296
	ds_read_b128 v[166:169], v149 offset:50176
	ds_read_b128 v[174:177], v149 offset:52224
	ds_read_b128 v[182:185], v149 offset:54272
	ds_read_b128 v[190:193], v149 offset:56320
	global_load_lds_dwordx4 v[212:213], off
	v_lshl_add_u64 v[212:213], v[218:219], 0, s[2:3]
	s_mov_b32 m0, s63
	s_nop 0
	global_load_lds_dwordx4 v[212:213], off
	s_barrier
	s_waitcnt lgkmcnt(7)
	v_mfma_f32_16x16x32_bf16 v[60:63], v[142:145], v[162:165], v[60:63]
	v_mfma_f32_16x16x32_bf16 v[56:59], v[154:157], v[162:165], v[56:59]
	s_waitcnt lgkmcnt(6)
	v_mfma_f32_16x16x32_bf16 v[44:47], v[142:145], v[170:173], v[44:47]
	v_mfma_f32_16x16x32_bf16 v[40:43], v[154:157], v[170:173], v[40:43]
	s_waitcnt lgkmcnt(5)
	v_mfma_f32_16x16x32_bf16 v[28:31], v[142:145], v[178:181], v[28:31]
	v_mfma_f32_16x16x32_bf16 v[24:27], v[154:157], v[178:181], v[24:27]
	s_waitcnt lgkmcnt(4)
	v_mfma_f32_16x16x32_bf16 v[12:15], v[142:145], v[186:189], v[12:15]
	v_mfma_f32_16x16x32_bf16 v[8:11], v[154:157], v[186:189], v[8:11]
	s_waitcnt lgkmcnt(3)
	v_mfma_f32_16x16x32_bf16 v[60:63], v[150:153], v[166:169], v[60:63]
	v_mfma_f32_16x16x32_bf16 v[56:59], v[158:161], v[166:169], v[56:59]
	s_waitcnt lgkmcnt(2)
	v_mfma_f32_16x16x32_bf16 v[44:47], v[150:153], v[174:177], v[44:47]
	v_mfma_f32_16x16x32_bf16 v[40:43], v[158:161], v[174:177], v[40:43]
	s_waitcnt lgkmcnt(1)
	v_mfma_f32_16x16x32_bf16 v[28:31], v[150:153], v[182:185], v[28:31]
	v_mfma_f32_16x16x32_bf16 v[24:27], v[158:161], v[182:185], v[24:27]
	s_waitcnt lgkmcnt(0)
	v_mfma_f32_16x16x32_bf16 v[12:15], v[150:153], v[190:193], v[12:15]
	v_mfma_f32_16x16x32_bf16 v[8:11], v[158:161], v[190:193], v[8:11]
	s_barrier
	s_add_u32 s48, s48, 0x40080
	s_addc_u32 s49, s49, 0
	s_add_i32 s50, s50, s56
	v_lshl_add_u64 v[142:143], s[48:49], 0, v[134:135]
	s_mov_b32 m0, s50
	s_nop 0
	global_load_lds_dwordx4 v[142:143], off
	v_lshl_add_u64 v[142:143], s[48:49], 0, v[130:131]
	s_add_i32 m0, s50, 0x2000
	s_nop 0
	global_load_lds_dwordx4 v[142:143], off
	s_waitcnt vmcnt(6)
	s_barrier
	v_mfma_f32_16x16x32_bf16 v[52:55], v[194:197], v[162:165], v[52:55]
	v_mfma_f32_16x16x32_bf16 v[48:51], v[202:205], v[162:165], v[48:51]
	v_mfma_f32_16x16x32_bf16 v[36:39], v[194:197], v[170:173], v[36:39]
	v_mfma_f32_16x16x32_bf16 v[32:35], v[202:205], v[170:173], v[32:35]
	v_mfma_f32_16x16x32_bf16 v[20:23], v[194:197], v[178:181], v[20:23]
	v_mfma_f32_16x16x32_bf16 v[16:19], v[202:205], v[178:181], v[16:19]
	v_mfma_f32_16x16x32_bf16 v[4:7], v[194:197], v[186:189], v[4:7]
	v_mfma_f32_16x16x32_bf16 v[0:3], v[202:205], v[186:189], v[0:3]
	v_mfma_f32_16x16x32_bf16 v[52:55], v[198:201], v[166:169], v[52:55]
	v_mfma_f32_16x16x32_bf16 v[48:51], v[208:211], v[166:169], v[48:51]
	v_mfma_f32_16x16x32_bf16 v[36:39], v[198:201], v[174:177], v[36:39]
	v_mfma_f32_16x16x32_bf16 v[32:35], v[208:211], v[174:177], v[32:35]
	v_mfma_f32_16x16x32_bf16 v[20:23], v[198:201], v[182:185], v[20:23]
	v_mfma_f32_16x16x32_bf16 v[16:19], v[208:211], v[182:185], v[16:19]
	v_mfma_f32_16x16x32_bf16 v[4:7], v[198:201], v[190:193], v[4:7]
	v_mfma_f32_16x16x32_bf16 v[0:3], v[208:211], v[190:193], v[0:3]
	s_add_i32 s70, s70, 2
	s_add_u32 s46, s46, 0x100
	s_addc_u32 s47, s47, 0
	s_add_u32 s68, s68, 0x100
	s_addc_u32 s69, s69, 0
	s_cmp_gt_u32 s70, 13
	s_barrier
	s_cbranch_scc0 .LBB0_152
	s_and_b32 s1, s65, -4
	s_cmp_eq_u32 s1, 4
	s_mov_b32 s1, 0xee00000
	s_cselect_b32 s1, s1, 0x13200000
	s_cmp_gt_u32 s65, 3
	s_cselect_b32 s1, s1, 0x6600000
	s_add_u32 s46, s74, s1
	s_addc_u32 s47, s75, 0
	s_lshl_b32 s1, s65, 8
	s_and_b32 s1, s1, 0x300
	v_mul_f32_e32 v122, 0xbfb8aa3b, v122
	v_or_b32_e32 v96, s1, v148
	v_exp_f32_e32 v122, v122
	v_mul_f32_e32 v123, 0xbfb8aa3b, v123
	v_lshl_add_u32 v144, s44, 8, v146
	v_lshlrev_b32_e32 v96, 1, v96
	v_exp_f32_e32 v123, v123
	v_lshl_add_u64 v[142:143], s[46:47], 0, v[96:97]
	v_ashrrev_i32_e32 v145, 31, v144
	v_mul_f32_e32 v96, 0xbfb8aa3b, v126
	v_mul_f32_e32 v126, 0xbfb8aa3b, v127
	v_lshlrev_b64 v[150:151], 11, v[144:145]
	v_exp_f32_e32 v96, v96
	v_exp_f32_e32 v145, v126
	v_add_f32_e32 v122, 1.0, v122
	v_lshl_add_u64 v[126:127], v[142:143], 0, v[150:151]
	v_rcp_f32_e32 v150, v122
	v_add_f32_e32 v122, 1.0, v123
	v_mul_f32_e32 v123, 0xbfb8aa3b, v124
	v_exp_f32_e32 v123, v123
	v_mul_f32_e32 v124, 0xbfb8aa3b, v125
	v_mul_f32_e32 v114, 0xbfb8aa3b, v114
	v_add_f32_e32 v96, 1.0, v96
	v_add_f32_e32 v145, 1.0, v145
	v_mul_f32_e32 v128, 0xbfb8aa3b, v128
	v_mul_f32_e32 v129, 0xbfb8aa3b, v129
	v_exp_f32_e32 v124, v124
	v_exp_f32_e32 v114, v114
	v_mul_f32_e32 v115, 0xbfb8aa3b, v115
	v_rcp_f32_e32 v96, v96
	v_exp_f32_e32 v128, v128
	v_exp_f32_e32 v129, v129
	v_rcp_f32_e32 v145, v145
	v_exp_f32_e32 v115, v115
	v_rcp_f32_e32 v125, v122
	v_add_f32_e32 v122, 1.0, v123
	v_rcp_f32_e32 v151, v122
	v_add_f32_e32 v122, 1.0, v124
	v_add_f32_e32 v114, 1.0, v114
	v_add_f32_e32 v128, 1.0, v128
	v_add_f32_e32 v129, 1.0, v129
	v_rcp_f32_e32 v152, v122
	v_cvt_pk_bf16_f32 v122, v96, v145
	v_mul_f32_e32 v96, 0xbfb8aa3b, v118
	v_mul_f32_e32 v118, 0xbfb8aa3b, v119
	v_mul_f32_e32 v119, 0xbfb8aa3b, v120
	v_mul_f32_e32 v120, 0xbfb8aa3b, v121
	v_rcp_f32_e32 v121, v114
	v_add_f32_e32 v114, 1.0, v115
	v_mul_f32_e32 v115, 0xbfb8aa3b, v116
	v_rcp_f32_e32 v128, v128
	v_rcp_f32_e32 v129, v129
	v_exp_f32_e32 v115, v115
	v_mul_f32_e32 v116, 0xbfb8aa3b, v117
	v_exp_f32_e32 v96, v96
	v_exp_f32_e32 v118, v118
	v_exp_f32_e32 v119, v119
	v_exp_f32_e32 v120, v120
	v_exp_f32_e32 v116, v116
	v_cvt_pk_bf16_f32 v123, v128, v129
	v_cvt_pk_bf16_f32 v124, v150, v125
; DEV float sigmoidf_(float x) { return __builtin_amdgcn_rcpf(1.f + __expf(-x)); }
;   DEV void operator()(const f32x4 (&acc)[2][2][4][2], const pg8::Unit& u, int wr, int wc, int fr, int fq) const {
;     const int b = u.pn >> 2, pn = u.pn & 3;
;     bf16_t* G = (bf16_t*)(ws + (b == 0 ? O_G1 : (b == 1 ? O_G2 : O_G3)));
;     const int row0 = u.pm * 256 + wr * 64 + fr, col0 = pn * 256 + wc * 32 + 8 * fq;
; #pragma unroll
;     for (int ai = 0; ai < 2; ++ai)
; #pragma unroll
;       for (int m = 0; m < 4; ++m) {
;         const int row = row0 + ai * 128 + m * 16;
; #pragma unroll
;         for (int bj = 0; bj < 2; ++bj) {
;           const f32x4 a0 = acc[ai][bj][m][0], a1 = acc[ai][bj][m][1];
;           u32x4 o;
;           o[0] = pk2(sigmoidf_(a0[0]), sigmoidf_(a0[1])); o[1] = pk2(sigmoidf_(a0[2]), sigmoidf_(a0[3]));
;           o[2] = pk2(sigmoidf_(a1[0]), sigmoidf_(a1[1])); o[3] = pk2(sigmoidf_(a1[2]), sigmoidf_(a1[3]));
;           *(u32x4*)(G + (size_t)row * DM + col0 + bj * 128) = o;
;         }
;       }
;   }
	v_cvt_pk_bf16_f32 v125, v151, v152
	v_rcp_f32_e32 v117, v114
	v_add_f32_e32 v114, 1.0, v115
	global_store_dwordx4 v[126:127], v[122:125], off
	v_add_f32_e32 v96, 1.0, v96
	v_add_f32_e32 v118, 1.0, v118
	v_add_f32_e32 v119, 1.0, v119
	v_add_f32_e32 v120, 1.0, v120
	v_rcp_f32_e32 v122, v114
	v_add_f32_e32 v114, 1.0, v116
	v_rcp_f32_e32 v96, v96
	v_rcp_f32_e32 v118, v118
	v_rcp_f32_e32 v119, v119
	v_rcp_f32_e32 v120, v120
	v_rcp_f32_e32 v123, v114
	v_mul_f32_e32 v106, 0xbfb8aa3b, v106
	v_exp_f32_e32 v106, v106
	v_mul_f32_e32 v107, 0xbfb8aa3b, v107
	v_cvt_pk_bf16_f32 v114, v96, v118
	v_cvt_pk_bf16_f32 v115, v119, v120
	v_cvt_pk_bf16_f32 v116, v121, v117
	v_cvt_pk_bf16_f32 v117, v122, v123
	v_exp_f32_e32 v107, v107
	global_store_dwordx4 v[126:127], v[114:117], off offset:256
	v_mul_f32_e32 v96, 0xbfb8aa3b, v110
	v_mul_f32_e32 v110, 0xbfb8aa3b, v111
	v_or_b32_e32 v114, 16, v144
	v_ashrrev_i32_e32 v115, 31, v114
	v_exp_f32_e32 v96, v96
	v_exp_f32_e32 v116, v110
	v_lshlrev_b64 v[114:115], 11, v[114:115]
	v_add_f32_e32 v106, 1.0, v106
	v_lshl_add_u64 v[110:111], v[142:143], 0, v[114:115]
	v_rcp_f32_e32 v115, v106
	v_add_f32_e32 v106, 1.0, v107
	v_mul_f32_e32 v107, 0xbfb8aa3b, v108
	v_exp_f32_e32 v107, v107
	v_mul_f32_e32 v108, 0xbfb8aa3b, v109
	v_mul_f32_e32 v98, 0xbfb8aa3b, v98
	v_add_f32_e32 v96, 1.0, v96
	v_add_f32_e32 v114, 1.0, v116
	v_mul_f32_e32 v112, 0xbfb8aa3b, v112
	v_mul_f32_e32 v113, 0xbfb8aa3b, v113
	v_exp_f32_e32 v108, v108
	v_exp_f32_e32 v98, v98
	v_mul_f32_e32 v99, 0xbfb8aa3b, v99
	v_rcp_f32_e32 v96, v96
	v_exp_f32_e32 v112, v112
	v_exp_f32_e32 v113, v113
	v_rcp_f32_e32 v114, v114
	v_exp_f32_e32 v99, v99
	v_rcp_f32_e32 v109, v106
	v_add_f32_e32 v106, 1.0, v107
	v_rcp_f32_e32 v116, v106
	v_add_f32_e32 v106, 1.0, v108
	v_add_f32_e32 v98, 1.0, v98
	v_add_f32_e32 v112, 1.0, v112
	v_add_f32_e32 v113, 1.0, v113
	v_rcp_f32_e32 v117, v106
	v_cvt_pk_bf16_f32 v106, v96, v114
	v_mul_f32_e32 v96, 0xbfb8aa3b, v102
	v_mul_f32_e32 v102, 0xbfb8aa3b, v103
	v_mul_f32_e32 v103, 0xbfb8aa3b, v104
	v_mul_f32_e32 v104, 0xbfb8aa3b, v105
	v_rcp_f32_e32 v105, v98
	v_add_f32_e32 v98, 1.0, v99
	v_mul_f32_e32 v99, 0xbfb8aa3b, v100
	v_rcp_f32_e32 v112, v112
	v_rcp_f32_e32 v113, v113
	v_exp_f32_e32 v99, v99
	v_mul_f32_e32 v100, 0xbfb8aa3b, v101
	v_exp_f32_e32 v96, v96
	v_exp_f32_e32 v102, v102
	v_exp_f32_e32 v103, v103
	v_exp_f32_e32 v104, v104
	v_exp_f32_e32 v100, v100
	v_cvt_pk_bf16_f32 v107, v112, v113
	v_cvt_pk_bf16_f32 v108, v115, v109
	v_cvt_pk_bf16_f32 v109, v116, v117
	v_rcp_f32_e32 v101, v98
	v_add_f32_e32 v98, 1.0, v99
	global_store_dwordx4 v[110:111], v[106:109], off
	v_add_f32_e32 v96, 1.0, v96
	v_add_f32_e32 v102, 1.0, v102
	v_add_f32_e32 v103, 1.0, v103
	v_add_f32_e32 v104, 1.0, v104
	v_rcp_f32_e32 v106, v98
	v_add_f32_e32 v98, 1.0, v100
	v_rcp_f32_e32 v96, v96
	v_rcp_f32_e32 v102, v102
	v_rcp_f32_e32 v103, v103
	v_rcp_f32_e32 v104, v104
	v_rcp_f32_e32 v107, v98
	v_mul_f32_e32 v88, 0xbfb8aa3b, v88
	v_exp_f32_e32 v88, v88
	v_mul_f32_e32 v89, 0xbfb8aa3b, v89
	v_cvt_pk_bf16_f32 v98, v96, v102
	v_cvt_pk_bf16_f32 v99, v103, v104
	v_cvt_pk_bf16_f32 v100, v105, v101
	v_cvt_pk_bf16_f32 v101, v106, v107
	v_exp_f32_e32 v89, v89
	global_store_dwordx4 v[110:111], v[98:101], off offset:256
	v_mul_f32_e32 v92, 0xbfb8aa3b, v92
	v_exp_f32_e32 v96, v92
	v_or_b32_e32 v98, 32, v144
	v_ashrrev_i32_e32 v99, 31, v98
	v_lshlrev_b64 v[98:99], 11, v[98:99]
	v_mul_f32_e32 v92, 0xbfb8aa3b, v93
	v_add_f32_e32 v88, 1.0, v88
	v_exp_f32_e32 v100, v92
	v_lshl_add_u64 v[92:93], v[142:143], 0, v[98:99]
	v_rcp_f32_e32 v99, v88
	v_add_f32_e32 v88, 1.0, v89
	v_mul_f32_e32 v89, 0xbfb8aa3b, v90
	v_mul_f32_e32 v94, 0xbfb8aa3b, v94
	v_mul_f32_e32 v95, 0xbfb8aa3b, v95
	v_exp_f32_e32 v89, v89
	v_mul_f32_e32 v90, 0xbfb8aa3b, v91
	v_exp_f32_e32 v94, v94
	v_exp_f32_e32 v95, v95
	v_exp_f32_e32 v90, v90
	v_rcp_f32_e32 v91, v88
	v_add_f32_e32 v88, 1.0, v89
	v_add_f32_e32 v96, 1.0, v96
	v_add_f32_e32 v98, 1.0, v100
	v_add_f32_e32 v94, 1.0, v94
	v_add_f32_e32 v95, 1.0, v95
	v_rcp_f32_e32 v100, v88
	v_add_f32_e32 v88, 1.0, v90
	v_mul_f32_e32 v80, 0xbfb8aa3b, v80
	v_rcp_f32_e32 v96, v96
	v_rcp_f32_e32 v98, v98
	v_rcp_f32_e32 v94, v94
	v_rcp_f32_e32 v95, v95
	v_rcp_f32_e32 v101, v88
	v_exp_f32_e32 v80, v80
	v_mul_f32_e32 v81, 0xbfb8aa3b, v81
	v_exp_f32_e32 v81, v81
	v_cvt_pk_bf16_f32 v88, v96, v98
	v_cvt_pk_bf16_f32 v89, v94, v95
	v_cvt_pk_bf16_f32 v90, v99, v91
	v_cvt_pk_bf16_f32 v91, v100, v101
	v_add_f32_e32 v80, 1.0, v80
	global_store_dwordx4 v[92:93], v[88:91], off
	v_mul_f32_e32 v84, 0xbfb8aa3b, v84
	v_mul_f32_e32 v85, 0xbfb8aa3b, v85
	v_rcp_f32_e32 v88, v80
	v_add_f32_e32 v80, 1.0, v81
	v_mul_f32_e32 v81, 0xbfb8aa3b, v82
	v_mul_f32_e32 v86, 0xbfb8aa3b, v86
	v_mul_f32_e32 v87, 0xbfb8aa3b, v87
	v_exp_f32_e32 v81, v81
	v_mul_f32_e32 v82, 0xbfb8aa3b, v83
	v_exp_f32_e32 v84, v84
	v_exp_f32_e32 v85, v85
	v_exp_f32_e32 v86, v86
	v_exp_f32_e32 v87, v87
	v_exp_f32_e32 v82, v82
	v_rcp_f32_e32 v83, v80
	v_add_f32_e32 v80, 1.0, v81
	v_add_f32_e32 v84, 1.0, v84
	v_add_f32_e32 v85, 1.0, v85
	v_add_f32_e32 v86, 1.0, v86
	v_add_f32_e32 v87, 1.0, v87
	v_rcp_f32_e32 v89, v80
	v_add_f32_e32 v80, 1.0, v82
	v_rcp_f32_e32 v84, v84
	v_rcp_f32_e32 v85, v85
	v_rcp_f32_e32 v86, v86
	v_rcp_f32_e32 v87, v87
	v_rcp_f32_e32 v90, v80
	v_mul_f32_e32 v72, 0xbfb8aa3b, v72
	v_cvt_pk_bf16_f32 v80, v84, v85
	v_cvt_pk_bf16_f32 v81, v86, v87
	v_cvt_pk_bf16_f32 v82, v88, v83
	v_cvt_pk_bf16_f32 v83, v89, v90
	v_mul_f32_e32 v76, 0xbfb8aa3b, v76
	v_exp_f32_e32 v72, v72
	v_mul_f32_e32 v73, 0xbfb8aa3b, v73
	global_store_dwordx4 v[92:93], v[80:83], off offset:256
	v_exp_f32_e32 v73, v73
	v_add_f32_e32 v72, 1.0, v72
	v_exp_f32_e32 v82, v76
; DEV float sigmoidf_(float x) { return __builtin_amdgcn_rcpf(1.f + __expf(-x)); }
;   DEV void operator()(const f32x4 (&acc)[2][2][4][2], const pg8::Unit& u, int wr, int wc, int fr, int fq) const {
;     ...
; #pragma unroll
;     for (int ai = 0; ai < 2; ++ai)
; #pragma unroll
;       for (int m = 0; m < 4; ++m) {
;         const int row = row0 + ai * 128 + m * 16;
; #pragma unroll
;         for (int bj = 0; bj < 2; ++bj) {
;           const f32x4 a0 = acc[ai][bj][m][0], a1 = acc[ai][bj][m][1];
;           u32x4 o;
;           o[0] = pk2(sigmoidf_(a0[0]), sigmoidf_(a0[1])); o[1] = pk2(sigmoidf_(a0[2]), sigmoidf_(a0[3]));
;           o[2] = pk2(sigmoidf_(a1[0]), sigmoidf_(a1[1])); o[3] = pk2(sigmoidf_(a1[2]), sigmoidf_(a1[3]));
;           *(u32x4*)(G + (size_t)row * DM + col0 + bj * 128) = o;
;         }
;       }
;   }
	v_or_b32_e32 v80, 48, v144
	v_ashrrev_i32_e32 v81, 31, v80
	v_lshlrev_b64 v[80:81], 11, v[80:81]
	v_mul_f32_e32 v76, 0xbfb8aa3b, v77
	v_exp_f32_e32 v83, v76
	v_lshl_add_u64 v[76:77], v[142:143], 0, v[80:81]
	v_add_f32_e32 v80, 1.0, v82
	v_rcp_f32_e32 v82, v72
	v_add_f32_e32 v72, 1.0, v73
	v_mul_f32_e32 v73, 0xbfb8aa3b, v74
	v_mul_f32_e32 v78, 0xbfb8aa3b, v78
	v_mul_f32_e32 v79, 0xbfb8aa3b, v79
	v_exp_f32_e32 v73, v73
	v_mul_f32_e32 v74, 0xbfb8aa3b, v75
	v_exp_f32_e32 v78, v78
	v_exp_f32_e32 v79, v79
	v_exp_f32_e32 v74, v74
	v_rcp_f32_e32 v75, v72
	v_add_f32_e32 v72, 1.0, v73
	v_add_f32_e32 v81, 1.0, v83
	v_add_f32_e32 v78, 1.0, v78
	v_add_f32_e32 v79, 1.0, v79
	v_rcp_f32_e32 v83, v72
	v_add_f32_e32 v72, 1.0, v74
	v_mul_f32_e32 v64, 0xbfb8aa3b, v64
	v_rcp_f32_e32 v80, v80
	v_rcp_f32_e32 v81, v81
	v_rcp_f32_e32 v78, v78
	v_rcp_f32_e32 v79, v79
	v_rcp_f32_e32 v84, v72
	v_exp_f32_e32 v64, v64
	v_mul_f32_e32 v65, 0xbfb8aa3b, v65
	v_exp_f32_e32 v65, v65
	v_cvt_pk_bf16_f32 v72, v80, v81
	v_cvt_pk_bf16_f32 v73, v78, v79
	v_cvt_pk_bf16_f32 v74, v82, v75
	v_cvt_pk_bf16_f32 v75, v83, v84
	v_add_f32_e32 v64, 1.0, v64
	global_store_dwordx4 v[76:77], v[72:75], off
	v_mul_f32_e32 v68, 0xbfb8aa3b, v68
	v_mul_f32_e32 v69, 0xbfb8aa3b, v69
	v_rcp_f32_e32 v72, v64
	v_add_f32_e32 v64, 1.0, v65
	v_mul_f32_e32 v65, 0xbfb8aa3b, v66
	v_mul_f32_e32 v70, 0xbfb8aa3b, v70
	v_mul_f32_e32 v71, 0xbfb8aa3b, v71
	v_exp_f32_e32 v65, v65
	v_mul_f32_e32 v66, 0xbfb8aa3b, v67
	v_exp_f32_e32 v68, v68
	v_exp_f32_e32 v69, v69
	v_exp_f32_e32 v70, v70
	v_exp_f32_e32 v71, v71
	v_exp_f32_e32 v66, v66
	v_rcp_f32_e32 v67, v64
	v_add_f32_e32 v64, 1.0, v65
	v_add_f32_e32 v68, 1.0, v68
	v_add_f32_e32 v69, 1.0, v69
	v_add_f32_e32 v70, 1.0, v70
	v_add_f32_e32 v71, 1.0, v71
	v_rcp_f32_e32 v73, v64
	v_add_f32_e32 v64, 1.0, v66
	v_mul_f32_e32 v56, 0xbfb8aa3b, v56
	v_rcp_f32_e32 v68, v68
	v_rcp_f32_e32 v69, v69
	v_rcp_f32_e32 v70, v70
	v_rcp_f32_e32 v71, v71
	v_rcp_f32_e32 v74, v64
	v_exp_f32_e32 v56, v56
	v_mul_f32_e32 v57, 0xbfb8aa3b, v57
	v_exp_f32_e32 v57, v57
	v_cvt_pk_bf16_f32 v64, v68, v69
	v_cvt_pk_bf16_f32 v65, v70, v71
	v_cvt_pk_bf16_f32 v66, v72, v67
	v_cvt_pk_bf16_f32 v67, v73, v74
	v_add_f32_e32 v56, 1.0, v56
	global_store_dwordx4 v[76:77], v[64:67], off offset:256
	v_mul_f32_e32 v60, 0xbfb8aa3b, v60
	v_mul_f32_e32 v62, 0xbfb8aa3b, v62
	v_mul_f32_e32 v63, 0xbfb8aa3b, v63
	v_rcp_f32_e32 v66, v56
	v_add_f32_e32 v56, 1.0, v57
	v_mul_f32_e32 v57, 0xbfb8aa3b, v58
	v_exp_f32_e32 v64, v60
	v_mul_f32_e32 v60, 0xbfb8aa3b, v61
	v_exp_f32_e32 v62, v62
	v_exp_f32_e32 v63, v63
	v_exp_f32_e32 v57, v57
	v_mul_f32_e32 v58, 0xbfb8aa3b, v59
	v_exp_f32_e32 v65, v60
	v_exp_f32_e32 v58, v58
	v_add_f32_e32 v62, 1.0, v62
	v_add_f32_e32 v63, 1.0, v63
	v_rcp_f32_e32 v59, v56
	v_add_f32_e32 v56, 1.0, v57
	v_add_f32_e32 v64, 1.0, v64
	v_add_f32_e32 v65, 1.0, v65
	v_rcp_f32_e32 v62, v62
	v_rcp_f32_e32 v63, v63
	v_rcp_f32_e32 v67, v56
	v_add_f32_e32 v56, 1.0, v58
	v_mul_f32_e32 v48, 0xbfb8aa3b, v48
	v_rcp_f32_e32 v64, v64
	v_rcp_f32_e32 v65, v65
	v_rcp_f32_e32 v68, v56
	v_exp_f32_e32 v48, v48
	v_mul_f32_e32 v49, 0xbfb8aa3b, v49
	v_exp_f32_e32 v49, v49
	s_mov_b32 s1, 0x40000
	v_cvt_pk_bf16_f32 v57, v62, v63
	v_add_co_u32_e32 v62, vcc, s1, v126
	v_cvt_pk_bf16_f32 v56, v64, v65
	v_cvt_pk_bf16_f32 v58, v66, v59
	v_cvt_pk_bf16_f32 v59, v67, v68
	v_addc_co_u32_e32 v63, vcc, 0, v127, vcc
	v_add_f32_e32 v48, 1.0, v48
	global_store_dwordx4 v[62:63], v[56:59], off
	v_mul_f32_e32 v52, 0xbfb8aa3b, v52
	v_mul_f32_e32 v53, 0xbfb8aa3b, v53
	v_rcp_f32_e32 v56, v48
	v_add_f32_e32 v48, 1.0, v49
	v_mul_f32_e32 v49, 0xbfb8aa3b, v50
	v_mul_f32_e32 v54, 0xbfb8aa3b, v54
	v_mul_f32_e32 v55, 0xbfb8aa3b, v55
	v_exp_f32_e32 v49, v49
	v_mul_f32_e32 v50, 0xbfb8aa3b, v51
	v_exp_f32_e32 v52, v52
	v_exp_f32_e32 v53, v53
	v_exp_f32_e32 v54, v54
	v_exp_f32_e32 v55, v55
	v_exp_f32_e32 v50, v50
	v_rcp_f32_e32 v51, v48
	v_add_f32_e32 v48, 1.0, v49
	v_add_f32_e32 v52, 1.0, v52
	v_add_f32_e32 v53, 1.0, v53
	v_add_f32_e32 v54, 1.0, v54
	v_add_f32_e32 v55, 1.0, v55
	v_rcp_f32_e32 v57, v48
	v_add_f32_e32 v48, 1.0, v50
	v_mul_f32_e32 v40, 0xbfb8aa3b, v40
	v_rcp_f32_e32 v52, v52
	v_rcp_f32_e32 v53, v53
	v_rcp_f32_e32 v54, v54
	v_rcp_f32_e32 v55, v55
	v_rcp_f32_e32 v58, v48
	v_exp_f32_e32 v40, v40
	v_mul_f32_e32 v41, 0xbfb8aa3b, v41
	v_exp_f32_e32 v41, v41
	s_mov_b64 s[46:47], 0x40000
	v_lshl_add_u64 v[60:61], v[126:127], 0, s[46:47]
	v_cvt_pk_bf16_f32 v48, v52, v53
	v_cvt_pk_bf16_f32 v49, v54, v55
	v_cvt_pk_bf16_f32 v50, v56, v51
	v_cvt_pk_bf16_f32 v51, v57, v58
	v_add_f32_e32 v40, 1.0, v40
	global_store_dwordx4 v[60:61], v[48:51], off offset:256
	v_mul_f32_e32 v44, 0xbfb8aa3b, v44
	v_mul_f32_e32 v46, 0xbfb8aa3b, v46
	v_mul_f32_e32 v47, 0xbfb8aa3b, v47
	v_rcp_f32_e32 v50, v40
	v_add_f32_e32 v40, 1.0, v41
	v_mul_f32_e32 v41, 0xbfb8aa3b, v42
	v_exp_f32_e32 v48, v44
	v_mul_f32_e32 v44, 0xbfb8aa3b, v45
	v_exp_f32_e32 v46, v46
	v_exp_f32_e32 v47, v47
	v_exp_f32_e32 v41, v41
	v_mul_f32_e32 v42, 0xbfb8aa3b, v43
	v_exp_f32_e32 v49, v44
	v_exp_f32_e32 v42, v42
	v_add_f32_e32 v46, 1.0, v46
	v_add_f32_e32 v47, 1.0, v47
	v_rcp_f32_e32 v43, v40
	v_add_f32_e32 v40, 1.0, v41
	v_add_f32_e32 v48, 1.0, v48
	v_add_f32_e32 v49, 1.0, v49
	v_rcp_f32_e32 v46, v46
	v_rcp_f32_e32 v47, v47
	v_rcp_f32_e32 v51, v40
	v_add_f32_e32 v40, 1.0, v42
	v_mul_f32_e32 v32, 0xbfb8aa3b, v32
	v_rcp_f32_e32 v48, v48
	v_rcp_f32_e32 v49, v49
	v_rcp_f32_e32 v52, v40
	v_exp_f32_e32 v32, v32
	v_mul_f32_e32 v33, 0xbfb8aa3b, v33
	v_exp_f32_e32 v33, v33
	s_mov_b32 s1, 0x48000
	v_cvt_pk_bf16_f32 v41, v46, v47
	v_add_co_u32_e32 v46, vcc, s1, v126
	v_cvt_pk_bf16_f32 v40, v48, v49
	v_cvt_pk_bf16_f32 v42, v50, v43
; DEV float sigmoidf_(float x) { return __builtin_amdgcn_rcpf(1.f + __expf(-x)); }
; template <class Epi, class Sched>
; __device__ __forceinline__ void gemm_phase(PG8_LAS unsigned char* lds, const Gemm g, const Sched& S, const Epi& E) {
;     ...
;         if constexpr (!Epi::AFTER_DRAIN) { E(acc, cur, wr, wc, fr, fq); S.done(cur); }
;         if (!has_next) break;
;   DEV void operator()(const f32x4 (&acc)[2][2][4][2], const pg8::Unit& u, int wr, int wc, int fr, int fq) const {
;     ...
; #pragma unroll
;     for (int ai = 0; ai < 2; ++ai)
; #pragma unroll
;       for (int m = 0; m < 4; ++m) {
;         const int row = row0 + ai * 128 + m * 16;
; #pragma unroll
;         for (int bj = 0; bj < 2; ++bj) {
;           const f32x4 a0 = acc[ai][bj][m][0], a1 = acc[ai][bj][m][1];
;           u32x4 o;
;           o[0] = pk2(sigmoidf_(a0[0]), sigmoidf_(a0[1])); o[1] = pk2(sigmoidf_(a0[2]), sigmoidf_(a0[3]));
;           o[2] = pk2(sigmoidf_(a1[0]), sigmoidf_(a1[1])); o[3] = pk2(sigmoidf_(a1[2]), sigmoidf_(a1[3]));
;           *(u32x4*)(G + (size_t)row * DM + col0 + bj * 128) = o;
;         }
;       }
;   }
	v_cvt_pk_bf16_f32 v43, v51, v52
	v_addc_co_u32_e32 v47, vcc, 0, v127, vcc
	v_add_f32_e32 v32, 1.0, v32
	global_store_dwordx4 v[46:47], v[40:43], off
	v_mul_f32_e32 v36, 0xbfb8aa3b, v36
	v_mul_f32_e32 v37, 0xbfb8aa3b, v37
	v_rcp_f32_e32 v40, v32
	v_add_f32_e32 v32, 1.0, v33
	v_mul_f32_e32 v33, 0xbfb8aa3b, v34
	v_mul_f32_e32 v38, 0xbfb8aa3b, v38
	v_mul_f32_e32 v39, 0xbfb8aa3b, v39
	v_exp_f32_e32 v33, v33
	v_mul_f32_e32 v34, 0xbfb8aa3b, v35
	v_exp_f32_e32 v36, v36
	v_exp_f32_e32 v37, v37
	v_exp_f32_e32 v38, v38
	v_exp_f32_e32 v39, v39
	v_exp_f32_e32 v34, v34
	v_rcp_f32_e32 v35, v32
	v_add_f32_e32 v32, 1.0, v33
	v_add_f32_e32 v36, 1.0, v36
	v_add_f32_e32 v37, 1.0, v37
	v_add_f32_e32 v38, 1.0, v38
	v_add_f32_e32 v39, 1.0, v39
	v_rcp_f32_e32 v41, v32
	v_add_f32_e32 v32, 1.0, v34
	v_mul_f32_e32 v24, 0xbfb8aa3b, v24
	v_rcp_f32_e32 v36, v36
	v_rcp_f32_e32 v37, v37
	v_rcp_f32_e32 v38, v38
	v_rcp_f32_e32 v39, v39
	v_rcp_f32_e32 v42, v32
	v_exp_f32_e32 v24, v24
	v_mul_f32_e32 v25, 0xbfb8aa3b, v25
	v_exp_f32_e32 v25, v25
	s_mov_b64 s[46:47], 0x48000
	v_lshl_add_u64 v[44:45], v[126:127], 0, s[46:47]
	v_cvt_pk_bf16_f32 v32, v36, v37
	v_cvt_pk_bf16_f32 v33, v38, v39
	v_cvt_pk_bf16_f32 v34, v40, v35
	v_cvt_pk_bf16_f32 v35, v41, v42
	v_add_f32_e32 v24, 1.0, v24
	global_store_dwordx4 v[44:45], v[32:35], off offset:256
	v_mul_f32_e32 v28, 0xbfb8aa3b, v28
	v_mul_f32_e32 v30, 0xbfb8aa3b, v30
	v_mul_f32_e32 v31, 0xbfb8aa3b, v31
	v_rcp_f32_e32 v34, v24
	v_add_f32_e32 v24, 1.0, v25
	v_mul_f32_e32 v25, 0xbfb8aa3b, v26
	v_exp_f32_e32 v32, v28
	v_mul_f32_e32 v28, 0xbfb8aa3b, v29
	v_exp_f32_e32 v30, v30
	v_exp_f32_e32 v31, v31
	v_exp_f32_e32 v25, v25
	v_mul_f32_e32 v26, 0xbfb8aa3b, v27
	v_exp_f32_e32 v33, v28
	v_exp_f32_e32 v26, v26
	v_add_f32_e32 v30, 1.0, v30
	v_add_f32_e32 v31, 1.0, v31
	v_rcp_f32_e32 v27, v24
	v_add_f32_e32 v24, 1.0, v25
	v_add_f32_e32 v32, 1.0, v32
	v_add_f32_e32 v33, 1.0, v33
	v_rcp_f32_e32 v30, v30
	v_rcp_f32_e32 v31, v31
	v_rcp_f32_e32 v35, v24
	v_add_f32_e32 v24, 1.0, v26
	v_mul_f32_e32 v16, 0xbfb8aa3b, v16
	v_rcp_f32_e32 v32, v32
	v_rcp_f32_e32 v33, v33
	v_rcp_f32_e32 v36, v24
	v_exp_f32_e32 v16, v16
	v_mul_f32_e32 v17, 0xbfb8aa3b, v17
	v_exp_f32_e32 v17, v17
	s_mov_b32 s1, 0x50000
	v_cvt_pk_bf16_f32 v25, v30, v31
	v_add_co_u32_e32 v30, vcc, s1, v126
	v_cvt_pk_bf16_f32 v24, v32, v33
	v_cvt_pk_bf16_f32 v26, v34, v27
	v_cvt_pk_bf16_f32 v27, v35, v36
	v_addc_co_u32_e32 v31, vcc, 0, v127, vcc
	v_add_f32_e32 v16, 1.0, v16
	global_store_dwordx4 v[30:31], v[24:27], off
	v_mul_f32_e32 v20, 0xbfb8aa3b, v20
	v_mul_f32_e32 v21, 0xbfb8aa3b, v21
	v_rcp_f32_e32 v24, v16
	v_add_f32_e32 v16, 1.0, v17
	v_mul_f32_e32 v17, 0xbfb8aa3b, v18
	v_mul_f32_e32 v22, 0xbfb8aa3b, v22
	v_mul_f32_e32 v23, 0xbfb8aa3b, v23
	v_exp_f32_e32 v17, v17
	v_mul_f32_e32 v18, 0xbfb8aa3b, v19
	v_exp_f32_e32 v20, v20
	v_exp_f32_e32 v21, v21
	v_exp_f32_e32 v22, v22
	v_exp_f32_e32 v23, v23
	v_exp_f32_e32 v18, v18
	v_rcp_f32_e32 v19, v16
	v_add_f32_e32 v16, 1.0, v17
	v_add_f32_e32 v20, 1.0, v20
	v_add_f32_e32 v21, 1.0, v21
	v_add_f32_e32 v22, 1.0, v22
	v_add_f32_e32 v23, 1.0, v23
	v_rcp_f32_e32 v25, v16
	v_add_f32_e32 v16, 1.0, v18
	v_mul_f32_e32 v8, 0xbfb8aa3b, v8
	v_rcp_f32_e32 v20, v20
	v_rcp_f32_e32 v21, v21
	v_rcp_f32_e32 v22, v22
	v_rcp_f32_e32 v23, v23
	v_rcp_f32_e32 v26, v16
	v_exp_f32_e32 v8, v8
	v_mul_f32_e32 v9, 0xbfb8aa3b, v9
	v_exp_f32_e32 v9, v9
	s_mov_b64 s[46:47], 0x50000
	v_lshl_add_u64 v[28:29], v[126:127], 0, s[46:47]
	v_cvt_pk_bf16_f32 v16, v20, v21
	v_cvt_pk_bf16_f32 v17, v22, v23
	v_cvt_pk_bf16_f32 v18, v24, v19
	v_cvt_pk_bf16_f32 v19, v25, v26
	v_add_f32_e32 v8, 1.0, v8
	global_store_dwordx4 v[28:29], v[16:19], off offset:256
	v_mul_f32_e32 v12, 0xbfb8aa3b, v12
	v_mul_f32_e32 v14, 0xbfb8aa3b, v14
	v_mul_f32_e32 v15, 0xbfb8aa3b, v15
	v_rcp_f32_e32 v18, v8
	v_add_f32_e32 v8, 1.0, v9
	v_mul_f32_e32 v9, 0xbfb8aa3b, v10
	v_exp_f32_e32 v16, v12
	v_mul_f32_e32 v12, 0xbfb8aa3b, v13
	v_exp_f32_e32 v14, v14
	v_exp_f32_e32 v15, v15
	v_exp_f32_e32 v9, v9
	v_mul_f32_e32 v10, 0xbfb8aa3b, v11
	v_exp_f32_e32 v17, v12
	v_exp_f32_e32 v10, v10
	v_add_f32_e32 v14, 1.0, v14
	v_add_f32_e32 v15, 1.0, v15
	v_rcp_f32_e32 v11, v8
	v_add_f32_e32 v8, 1.0, v9
	v_add_f32_e32 v16, 1.0, v16
	v_add_f32_e32 v17, 1.0, v17
	v_rcp_f32_e32 v14, v14
	v_rcp_f32_e32 v15, v15
	v_rcp_f32_e32 v19, v8
	v_add_f32_e32 v8, 1.0, v10
	v_mul_f32_e32 v0, 0xbfb8aa3b, v0
	v_rcp_f32_e32 v16, v16
	v_rcp_f32_e32 v17, v17
	v_rcp_f32_e32 v20, v8
	v_exp_f32_e32 v0, v0
	v_mul_f32_e32 v1, 0xbfb8aa3b, v1
	v_exp_f32_e32 v1, v1
	s_mov_b32 s1, 0x58000
	v_cvt_pk_bf16_f32 v9, v14, v15
	v_add_co_u32_e32 v14, vcc, s1, v126
	v_cvt_pk_bf16_f32 v8, v16, v17
	v_cvt_pk_bf16_f32 v10, v18, v11
	v_cvt_pk_bf16_f32 v11, v19, v20
	v_addc_co_u32_e32 v15, vcc, 0, v127, vcc
	v_add_f32_e32 v0, 1.0, v0
	global_store_dwordx4 v[14:15], v[8:11], off
	v_mul_f32_e32 v4, 0xbfb8aa3b, v4
	v_mul_f32_e32 v5, 0xbfb8aa3b, v5
	v_rcp_f32_e32 v8, v0
	v_add_f32_e32 v0, 1.0, v1
	v_mul_f32_e32 v1, 0xbfb8aa3b, v2
	v_mul_f32_e32 v6, 0xbfb8aa3b, v6
	v_mul_f32_e32 v7, 0xbfb8aa3b, v7
	v_exp_f32_e32 v1, v1
	v_mul_f32_e32 v2, 0xbfb8aa3b, v3
	v_exp_f32_e32 v4, v4
	v_exp_f32_e32 v5, v5
	v_exp_f32_e32 v6, v6
	v_exp_f32_e32 v7, v7
	v_exp_f32_e32 v2, v2
	v_rcp_f32_e32 v3, v0
	v_add_f32_e32 v0, 1.0, v1
	v_add_f32_e32 v4, 1.0, v4
	v_add_f32_e32 v5, 1.0, v5
	v_add_f32_e32 v6, 1.0, v6
	v_add_f32_e32 v7, 1.0, v7
	v_rcp_f32_e32 v9, v0
	v_add_f32_e32 v0, 1.0, v2
	v_rcp_f32_e32 v4, v4
	v_rcp_f32_e32 v5, v5
	v_rcp_f32_e32 v6, v6
	v_rcp_f32_e32 v7, v7
	v_rcp_f32_e32 v10, v0
	s_mov_b64 s[46:47], 0x58000
	v_lshl_add_u64 v[12:13], v[126:127], 0, s[46:47]
	v_cvt_pk_bf16_f32 v0, v4, v5
	v_cvt_pk_bf16_f32 v1, v6, v7
	v_cvt_pk_bf16_f32 v2, v8, v3
	v_cvt_pk_bf16_f32 v3, v9, v10
	s_and_b64 vcc, exec, s[36:37]
	s_mov_b32 s65, s0
	s_mov_b32 s44, s30
	s_mov_b64 s[48:49], s[40:41]
	s_mov_b64 s[46:47], s[38:39]
	global_store_dwordx4 v[12:13], v[0:3], off offset:256
	s_cbranch_vccz .LBB0_149
	s_waitcnt vmcnt(0)
	v_readlane_b32 s64, v255, 38
	s_cmpk_gt_u32 s53, 0xff
	v_readlane_b32 s65, v255, 39
	s_cbranch_scc1 .LBB0_156
	s_barrier

; #define PG8_STAGE(bufoff, gbase, voff) do { _Pragma("unroll") for (int _i = 0; _i < 2; ++_i) \
;         __builtin_amdgcn_global_load_lds((const unsigned*)((const char*)(gbase) + (voff)[_i]), (PG8_LAS unsigned*)(lds + (bufoff) + ldsw + _i * 8192), 16, 0, 0); } while (0)
; #define PG8_LDA(dst, b, h) do { _Pragma("unroll") for (int m = 0; m < 4; ++m) _Pragma("unroll") for (int k = 0; k < 2; ++k) dst[m][k] = *(const PG8_LAS bf16x8*)(lds + PG8_SA(b, h) + aoff + m * 2048 + k * 1024); } while (0)
; #define PG8_LDB(dst, b, h) do { _Pragma("unroll") for (int n = 0; n < 2; ++n) _Pragma("unroll") for (int k = 0; k < 2; ++k) dst[n][k] = *(const PG8_LAS bf16x8*)(lds + PG8_SB(b, h) + boff + n * 2048 + k * 1024); } while (0)
; #define PG8_MMA(ai, bj, At, Bt) do { __builtin_amdgcn_s_setprio(1); _Pragma("unroll") for (int m = 0; m < 4; ++m) _Pragma("unroll") for (int n = 0; n < 2; ++n) _Pragma("unroll") for (int k = 0; k < 2; ++k) \
;         acc[ai][bj][m][n] = __builtin_amdgcn_mfma_f32_16x16x32_bf16(Bt[n][k], At[m][k], acc[ai][bj][m][n], 0, 0, 0); __builtin_amdgcn_s_setprio(0); } while (0)
; #define PG8_WAIT_V(n) asm volatile("s_waitcnt vmcnt(" #n ")" ::: "memory")
; #define PG8_WAIT_L(n) asm volatile("s_waitcnt lgkmcnt(" #n ")" ::: "memory")
; #define PG8_BAR __builtin_amdgcn_s_barrier()
; #define PG8_SCHED __builtin_amdgcn_sched_barrier(0)
; template <class Epi, class Sched>
; __device__ __forceinline__ void gemm_phase(PG8_LAS unsigned char* lds, const Gemm g, const Sched& S, const Epi& E) {
;     ...
;             PG8_LDB(B0, 0, 0); PG8_SCHED; PG8_LDA(At, 0, 0); PG8_STAGE(PG8_SA(1, 1), a1 + hstep, voffA);
;             PG8_WAIT_L(8); PG8_BAR; PG8_WAIT_L(0); PG8_MMA(0, 0, At, B0); PG8_BAR; PG8_SCHED;
;             PG8_LDB(B1, 0, 1); PG8_STAGE(PG8_SB(0, 0), b2, voffB);
;             PG8_BAR; PG8_WAIT_L(0); PG8_MMA(0, 1, At, B1); PG8_BAR;
;             PG8_LDA(At, 0, 1); PG8_STAGE(PG8_SA(0, 0), a2, voffA);
;             PG8_BAR; PG8_WAIT_L(0); PG8_MMA(1, 0, At, B0); PG8_BAR; PG8_SCHED;
;             PG8_STAGE(PG8_SB(0, 1), b2 + hstep, voffB);
;             PG8_WAIT_V(6); PG8_BAR; PG8_MMA(1, 1, At, B1); PG8_BAR;
.Lgp_21593:
.LBB0_654:
	s_add_u32 s30, s0, 0xfffc0080
	s_addc_u32 s31, s1, -1
	s_add_i32 s62, 0, 0x10000
	v_add_u32_e32 v96, s62, v162
	ds_read_b128 v[144:147], v96
	ds_read_b128 v[148:151], v96 offset:1024
	ds_read_b128 v[152:155], v96 offset:2048
	ds_read_b128 v[156:159], v96 offset:3072
	s_cmp_eq_u32 s61, 12
	s_cselect_b32 s49, s43, s31
	s_cselect_b32 s48, s57, s30
	s_cselect_b32 s31, s41, s60
	s_cselect_b32 s30, s58, s59
	v_lshl_add_u64 v[160:161], s[0:1], 0, v[140:141]
	s_add_i32 m0, s52, 0xc000
	ds_read_b128 v[170:173], v168
	ds_read_b128 v[178:181], v168 offset:2048
	ds_read_b128 v[186:189], v168 offset:4096
	ds_read_b128 v[194:197], v168 offset:6144
	ds_read_b128 v[174:177], v168 offset:1024
	ds_read_b128 v[182:185], v168 offset:3072
	ds_read_b128 v[190:193], v168 offset:5120
	ds_read_b128 v[198:201], v168 offset:7168
	global_load_lds_dwordx4 v[160:161], off
	v_lshl_add_u64 v[160:161], s[0:1], 0, v[142:143]
	s_add_i32 m0, s52, 0xe000
	s_nop 0
	global_load_lds_dwordx4 v[160:161], off
	s_waitcnt lgkmcnt(8)
	s_barrier
	s_waitcnt lgkmcnt(7)
	v_mfma_f32_16x16x32_bf16 v[126:129], v[144:147], v[170:173], v[126:129]
	v_mfma_f32_16x16x32_bf16 v[118:121], v[152:155], v[170:173], v[118:121]
	s_waitcnt lgkmcnt(6)
	v_mfma_f32_16x16x32_bf16 v[110:113], v[144:147], v[178:181], v[110:113]
	v_mfma_f32_16x16x32_bf16 v[102:105], v[152:155], v[178:181], v[102:105]
	s_waitcnt lgkmcnt(5)
	v_mfma_f32_16x16x32_bf16 v[92:95], v[144:147], v[186:189], v[92:95]
	v_mfma_f32_16x16x32_bf16 v[84:87], v[152:155], v[186:189], v[84:87]
	s_waitcnt lgkmcnt(4)
	v_mfma_f32_16x16x32_bf16 v[76:79], v[144:147], v[194:197], v[76:79]
	v_mfma_f32_16x16x32_bf16 v[68:71], v[152:155], v[194:197], v[68:71]
	s_waitcnt lgkmcnt(3)
	v_mfma_f32_16x16x32_bf16 v[126:129], v[148:151], v[174:177], v[126:129]
	v_mfma_f32_16x16x32_bf16 v[118:121], v[156:159], v[174:177], v[118:121]
	s_waitcnt lgkmcnt(2)
	v_mfma_f32_16x16x32_bf16 v[110:113], v[148:151], v[182:185], v[110:113]
	v_mfma_f32_16x16x32_bf16 v[102:105], v[156:159], v[182:185], v[102:105]
	s_waitcnt lgkmcnt(1)
	v_mfma_f32_16x16x32_bf16 v[92:95], v[148:151], v[190:193], v[92:95]
	v_mfma_f32_16x16x32_bf16 v[84:87], v[156:159], v[190:193], v[84:87]
	s_waitcnt lgkmcnt(0)
	v_mfma_f32_16x16x32_bf16 v[76:79], v[148:151], v[198:201], v[76:79]
	v_mfma_f32_16x16x32_bf16 v[68:71], v[156:159], v[198:201], v[68:71]
	s_barrier
	s_add_i32 s64, 0, 0x14000
	s_add_i32 s62, s62, s51
	v_add_u32_e32 v96, s64, v162
	v_lshl_add_u64 v[160:161], s[30:31], 0, v[134:135]
	s_mov_b32 m0, s62
	ds_read_b128 v[202:205], v96
	ds_read_b128 v[212:215], v96 offset:2048
	ds_read_b128 v[208:211], v96 offset:1024
	ds_read_b128 v[216:219], v96 offset:3072
	global_load_lds_dwordx4 v[160:161], off
	v_lshl_add_u64 v[220:221], s[30:31], 0, v[130:131]
	s_add_i32 m0, s62, 0x2000
	s_nop 0
	global_load_lds_dwordx4 v[220:221], off
	s_barrier
	s_waitcnt lgkmcnt(3)
	v_mfma_f32_16x16x32_bf16 v[122:125], v[202:205], v[170:173], v[122:125]
	s_waitcnt lgkmcnt(2)
	v_mfma_f32_16x16x32_bf16 v[114:117], v[212:215], v[170:173], v[114:117]
	v_mfma_f32_16x16x32_bf16 v[106:109], v[202:205], v[178:181], v[106:109]
	v_mfma_f32_16x16x32_bf16 v[98:101], v[212:215], v[178:181], v[98:101]
	v_mfma_f32_16x16x32_bf16 v[88:91], v[202:205], v[186:189], v[88:91]
	v_mfma_f32_16x16x32_bf16 v[80:83], v[212:215], v[186:189], v[80:83]
	v_mfma_f32_16x16x32_bf16 v[72:75], v[202:205], v[194:197], v[72:75]
	v_mfma_f32_16x16x32_bf16 v[64:67], v[212:215], v[194:197], v[64:67]
	s_waitcnt lgkmcnt(1)
	v_mfma_f32_16x16x32_bf16 v[122:125], v[208:211], v[174:177], v[122:125]
	s_waitcnt lgkmcnt(0)
	v_mfma_f32_16x16x32_bf16 v[114:117], v[216:219], v[174:177], v[114:117]
	v_mfma_f32_16x16x32_bf16 v[106:109], v[208:211], v[182:185], v[106:109]
	v_mfma_f32_16x16x32_bf16 v[98:101], v[216:219], v[182:185], v[98:101]
	v_mfma_f32_16x16x32_bf16 v[88:91], v[208:211], v[190:193], v[88:91]
	v_mfma_f32_16x16x32_bf16 v[80:83], v[216:219], v[190:193], v[80:83]
	v_mfma_f32_16x16x32_bf16 v[72:75], v[208:211], v[198:201], v[72:75]
	v_mfma_f32_16x16x32_bf16 v[64:67], v[216:219], v[198:201], v[64:67]
	s_mov_b32 m0, s52
	v_lshl_add_u64 v[222:223], s[48:49], 0, v[136:137]
	s_barrier
	ds_read_b128 v[170:173], v168 offset:16384
	ds_read_b128 v[178:181], v168 offset:18432
	ds_read_b128 v[186:189], v168 offset:20480
	ds_read_b128 v[194:197], v168 offset:22528
	ds_read_b128 v[174:177], v168 offset:17408
	ds_read_b128 v[182:185], v168 offset:19456
	ds_read_b128 v[190:193], v168 offset:21504
	ds_read_b128 v[198:201], v168 offset:23552
	global_load_lds_dwordx4 v[222:223], off
	v_lshl_add_u64 v[224:225], s[48:49], 0, v[132:133]
	s_mov_b32 m0, s53
	s_nop 0
	global_load_lds_dwordx4 v[224:225], off
	s_barrier
	s_waitcnt lgkmcnt(7)
	v_mfma_f32_16x16x32_bf16 v[60:63], v[144:147], v[170:173], v[60:63]
	v_mfma_f32_16x16x32_bf16 v[52:55], v[152:155], v[170:173], v[52:55]
	s_waitcnt lgkmcnt(6)
	v_mfma_f32_16x16x32_bf16 v[44:47], v[144:147], v[178:181], v[44:47]
	v_mfma_f32_16x16x32_bf16 v[36:39], v[152:155], v[178:181], v[36:39]
	s_waitcnt lgkmcnt(5)
	v_mfma_f32_16x16x32_bf16 v[28:31], v[144:147], v[186:189], v[28:31]
	v_mfma_f32_16x16x32_bf16 v[20:23], v[152:155], v[186:189], v[20:23]
	s_waitcnt lgkmcnt(4)
	v_mfma_f32_16x16x32_bf16 v[12:15], v[144:147], v[194:197], v[12:15]
	v_mfma_f32_16x16x32_bf16 v[4:7], v[152:155], v[194:197], v[4:7]
	s_waitcnt lgkmcnt(3)
	v_mfma_f32_16x16x32_bf16 v[60:63], v[148:151], v[174:177], v[60:63]
	v_mfma_f32_16x16x32_bf16 v[52:55], v[156:159], v[174:177], v[52:55]
	s_waitcnt lgkmcnt(2)
	v_mfma_f32_16x16x32_bf16 v[44:47], v[148:151], v[182:185], v[44:47]
	v_mfma_f32_16x16x32_bf16 v[36:39], v[156:159], v[182:185], v[36:39]
	s_waitcnt lgkmcnt(1)
	v_mfma_f32_16x16x32_bf16 v[28:31], v[148:151], v[190:193], v[28:31]
	v_mfma_f32_16x16x32_bf16 v[20:23], v[156:159], v[190:193], v[20:23]
	s_waitcnt lgkmcnt(0)
	v_mfma_f32_16x16x32_bf16 v[12:15], v[148:151], v[198:201], v[12:15]
	v_mfma_f32_16x16x32_bf16 v[4:7], v[156:159], v[198:201], v[4:7]
	s_barrier
; #define PG8_STAGE(bufoff, gbase, voff) do { _Pragma("unroll") for (int _i = 0; _i < 2; ++_i) \
;         __builtin_amdgcn_global_load_lds((const unsigned*)((const char*)(gbase) + (voff)[_i]), (PG8_LAS unsigned*)(lds + (bufoff) + ldsw + _i * 8192), 16, 0, 0); } while (0)
; #define PG8_LDA(dst, b, h) do { _Pragma("unroll") for (int m = 0; m < 4; ++m) _Pragma("unroll") for (int k = 0; k < 2; ++k) dst[m][k] = *(const PG8_LAS bf16x8*)(lds + PG8_SA(b, h) + aoff + m * 2048 + k * 1024); } while (0)
; #define PG8_LDB(dst, b, h) do { _Pragma("unroll") for (int n = 0; n < 2; ++n) _Pragma("unroll") for (int k = 0; k < 2; ++k) dst[n][k] = *(const PG8_LAS bf16x8*)(lds + PG8_SB(b, h) + boff + n * 2048 + k * 1024); } while (0)
; #define PG8_MMA(ai, bj, At, Bt) do { __builtin_amdgcn_s_setprio(1); _Pragma("unroll") for (int m = 0; m < 4; ++m) _Pragma("unroll") for (int n = 0; n < 2; ++n) _Pragma("unroll") for (int k = 0; k < 2; ++k) \
;         acc[ai][bj][m][n] = __builtin_amdgcn_mfma_f32_16x16x32_bf16(Bt[n][k], At[m][k], acc[ai][bj][m][n], 0, 0, 0); __builtin_amdgcn_s_setprio(0); } while (0)
; #define PG8_WAIT_V(n) asm volatile("s_waitcnt vmcnt(" #n ")" ::: "memory")
; #define PG8_WAIT_L(n) asm volatile("s_waitcnt lgkmcnt(" #n ")" ::: "memory")
; #define PG8_BAR __builtin_amdgcn_s_barrier()
; #define PG8_SCHED __builtin_amdgcn_sched_barrier(0)
; template <class Epi, class Sched>
; __device__ __forceinline__ void gemm_phase(PG8_LAS unsigned char* lds, const Gemm g, const Sched& S, const Epi& E) {
;     ...
;             PG8_STAGE(PG8_SB(0, 1), b2 + hstep, voffB);
;             PG8_WAIT_V(6); PG8_BAR; PG8_MMA(1, 1, At, B1); PG8_BAR;
;             PG8_LDB(B0, 1, 0); PG8_SCHED; PG8_LDA(At, 1, 0); PG8_STAGE(PG8_SA(0, 1), a2 + hstep, voffA);
;             PG8_WAIT_L(8); PG8_BAR; PG8_WAIT_L(0); PG8_MMA(0, 0, At, B0); PG8_BAR; PG8_SCHED;
;             PG8_LDB(B1, 1, 1); PG8_STAGE(PG8_SB(1, 0), b3, voffB);
;             PG8_BAR; PG8_WAIT_L(0); PG8_MMA(0, 1, At, B1); PG8_BAR;
;             PG8_LDA(At, 1, 1); PG8_STAGE(PG8_SA(1, 0), a3, voffA);
;             PG8_BAR; PG8_WAIT_L(0); PG8_MMA(1, 0, At, B0); PG8_BAR; PG8_SCHED;
	s_add_u32 s62, s30, 0x40000
	s_addc_u32 s63, s31, 0
	s_add_i32 s64, s64, s51
	v_lshl_add_u64 v[144:145], s[62:63], 0, v[134:135]
	s_mov_b32 m0, s64
	s_nop 0
	global_load_lds_dwordx4 v[144:145], off
	v_lshl_add_u64 v[144:145], s[62:63], 0, v[130:131]
	s_add_i32 m0, s64, 0x2000
	s_nop 0
	global_load_lds_dwordx4 v[144:145], off
	s_waitcnt vmcnt(6)
	s_barrier
	v_mfma_f32_16x16x32_bf16 v[56:59], v[202:205], v[170:173], v[56:59]
	v_mfma_f32_16x16x32_bf16 v[48:51], v[212:215], v[170:173], v[48:51]
	v_mfma_f32_16x16x32_bf16 v[40:43], v[202:205], v[178:181], v[40:43]
	v_mfma_f32_16x16x32_bf16 v[32:35], v[212:215], v[178:181], v[32:35]
	v_mfma_f32_16x16x32_bf16 v[24:27], v[202:205], v[186:189], v[24:27]
	v_mfma_f32_16x16x32_bf16 v[16:19], v[212:215], v[186:189], v[16:19]
	v_mfma_f32_16x16x32_bf16 v[8:11], v[202:205], v[194:197], v[8:11]
	v_mfma_f32_16x16x32_bf16 v[0:3], v[212:215], v[194:197], v[0:3]
	v_mfma_f32_16x16x32_bf16 v[56:59], v[208:211], v[174:177], v[56:59]
	v_mfma_f32_16x16x32_bf16 v[48:51], v[216:219], v[174:177], v[48:51]
	v_mfma_f32_16x16x32_bf16 v[40:43], v[208:211], v[182:185], v[40:43]
	v_mfma_f32_16x16x32_bf16 v[32:35], v[216:219], v[182:185], v[32:35]
	v_mfma_f32_16x16x32_bf16 v[24:27], v[208:211], v[190:193], v[24:27]
	v_mfma_f32_16x16x32_bf16 v[16:19], v[216:219], v[190:193], v[16:19]
	v_mfma_f32_16x16x32_bf16 v[8:11], v[208:211], v[198:201], v[8:11]
	v_mfma_f32_16x16x32_bf16 v[0:3], v[216:219], v[198:201], v[0:3]
	s_add_i32 s62, 0, 0x18000
	v_add_u32_e32 v96, s62, v162
	s_barrier
	ds_read_b128 v[144:147], v96
	ds_read_b128 v[148:151], v96 offset:1024
	ds_read_b128 v[152:155], v96 offset:2048
	ds_read_b128 v[156:159], v96 offset:3072
	s_add_u32 s48, s48, 0x40000
	s_addc_u32 s49, s49, 0
	s_mov_b32 m0, s54
	v_lshl_add_u64 v[202:203], s[48:49], 0, v[136:137]
	ds_read_b128 v[170:173], v168 offset:32768
	ds_read_b128 v[178:181], v168 offset:34816
	ds_read_b128 v[186:189], v168 offset:36864
	ds_read_b128 v[194:197], v168 offset:38912
	ds_read_b128 v[174:177], v168 offset:33792
	ds_read_b128 v[182:185], v168 offset:35840
	ds_read_b128 v[190:193], v168 offset:37888
	ds_read_b128 v[198:201], v168 offset:39936
	global_load_lds_dwordx4 v[202:203], off
	v_lshl_add_u64 v[202:203], s[48:49], 0, v[132:133]
	s_mov_b32 m0, s96
	s_nop 0
	global_load_lds_dwordx4 v[202:203], off
	s_waitcnt lgkmcnt(8)
	s_barrier
	s_waitcnt lgkmcnt(7)
	v_mfma_f32_16x16x32_bf16 v[126:129], v[144:147], v[170:173], v[126:129]
	v_mfma_f32_16x16x32_bf16 v[118:121], v[152:155], v[170:173], v[118:121]
	s_waitcnt lgkmcnt(6)
	v_mfma_f32_16x16x32_bf16 v[110:113], v[144:147], v[178:181], v[110:113]
	v_mfma_f32_16x16x32_bf16 v[102:105], v[152:155], v[178:181], v[102:105]
	s_waitcnt lgkmcnt(5)
	v_mfma_f32_16x16x32_bf16 v[92:95], v[144:147], v[186:189], v[92:95]
	v_mfma_f32_16x16x32_bf16 v[84:87], v[152:155], v[186:189], v[84:87]
	s_waitcnt lgkmcnt(4)
	v_mfma_f32_16x16x32_bf16 v[76:79], v[144:147], v[194:197], v[76:79]
	v_mfma_f32_16x16x32_bf16 v[68:71], v[152:155], v[194:197], v[68:71]
	s_waitcnt lgkmcnt(3)
	v_mfma_f32_16x16x32_bf16 v[126:129], v[148:151], v[174:177], v[126:129]
	v_mfma_f32_16x16x32_bf16 v[118:121], v[156:159], v[174:177], v[118:121]
	s_waitcnt lgkmcnt(2)
	v_mfma_f32_16x16x32_bf16 v[110:113], v[148:151], v[182:185], v[110:113]
	v_mfma_f32_16x16x32_bf16 v[102:105], v[156:159], v[182:185], v[102:105]
	s_waitcnt lgkmcnt(1)
	v_mfma_f32_16x16x32_bf16 v[92:95], v[148:151], v[190:193], v[92:95]
	v_mfma_f32_16x16x32_bf16 v[84:87], v[156:159], v[190:193], v[84:87]
	s_waitcnt lgkmcnt(0)
	v_mfma_f32_16x16x32_bf16 v[76:79], v[148:151], v[198:201], v[76:79]
	v_mfma_f32_16x16x32_bf16 v[68:71], v[156:159], v[198:201], v[68:71]
	s_barrier
	s_add_i32 s48, 0, 0x1c000
	s_add_i32 s49, s62, s51
	v_add_u32_e32 v96, s48, v162
	v_lshl_add_u64 v[160:161], v[160:161], 0, s[2:3]
	s_mov_b32 m0, s49
	ds_read_b128 v[202:205], v96
	ds_read_b128 v[212:215], v96 offset:2048
	ds_read_b128 v[208:211], v96 offset:1024
	ds_read_b128 v[216:219], v96 offset:3072
	global_load_lds_dwordx4 v[160:161], off
	v_lshl_add_u64 v[160:161], v[220:221], 0, s[2:3]
	s_add_i32 m0, s49, 0x2000
	s_nop 0
	global_load_lds_dwordx4 v[160:161], off
	s_barrier
	s_waitcnt lgkmcnt(3)
	v_mfma_f32_16x16x32_bf16 v[122:125], v[202:205], v[170:173], v[122:125]
	s_waitcnt lgkmcnt(2)
	v_mfma_f32_16x16x32_bf16 v[114:117], v[212:215], v[170:173], v[114:117]
	v_mfma_f32_16x16x32_bf16 v[106:109], v[202:205], v[178:181], v[106:109]
	v_mfma_f32_16x16x32_bf16 v[98:101], v[212:215], v[178:181], v[98:101]
	v_mfma_f32_16x16x32_bf16 v[88:91], v[202:205], v[186:189], v[88:91]
	v_mfma_f32_16x16x32_bf16 v[80:83], v[212:215], v[186:189], v[80:83]
	v_mfma_f32_16x16x32_bf16 v[72:75], v[202:205], v[194:197], v[72:75]
	v_mfma_f32_16x16x32_bf16 v[64:67], v[212:215], v[194:197], v[64:67]
	s_waitcnt lgkmcnt(1)
	v_mfma_f32_16x16x32_bf16 v[122:125], v[208:211], v[174:177], v[122:125]
	s_waitcnt lgkmcnt(0)
	v_mfma_f32_16x16x32_bf16 v[114:117], v[216:219], v[174:177], v[114:117]
	v_mfma_f32_16x16x32_bf16 v[106:109], v[208:211], v[182:185], v[106:109]
	v_mfma_f32_16x16x32_bf16 v[98:101], v[216:219], v[182:185], v[98:101]
	v_mfma_f32_16x16x32_bf16 v[88:91], v[208:211], v[190:193], v[88:91]
	v_mfma_f32_16x16x32_bf16 v[80:83], v[216:219], v[190:193], v[80:83]
	v_mfma_f32_16x16x32_bf16 v[72:75], v[208:211], v[198:201], v[72:75]
	v_mfma_f32_16x16x32_bf16 v[64:67], v[216:219], v[198:201], v[64:67]
	s_mov_b32 m0, s97
	v_lshl_add_u64 v[160:161], v[222:223], 0, s[2:3]
	s_barrier
; #define PG8_STAGE(bufoff, gbase, voff) do { _Pragma("unroll") for (int _i = 0; _i < 2; ++_i) \
;         __builtin_amdgcn_global_load_lds((const unsigned*)((const char*)(gbase) + (voff)[_i]), (PG8_LAS unsigned*)(lds + (bufoff) + ldsw + _i * 8192), 16, 0, 0); } while (0)
; #define PG8_LDA(dst, b, h) do { _Pragma("unroll") for (int m = 0; m < 4; ++m) _Pragma("unroll") for (int k = 0; k < 2; ++k) dst[m][k] = *(const PG8_LAS bf16x8*)(lds + PG8_SA(b, h) + aoff + m * 2048 + k * 1024); } while (0)
; #define PG8_MMA(ai, bj, At, Bt) do { __builtin_amdgcn_s_setprio(1); _Pragma("unroll") for (int m = 0; m < 4; ++m) _Pragma("unroll") for (int n = 0; n < 2; ++n) _Pragma("unroll") for (int k = 0; k < 2; ++k) \
;         acc[ai][bj][m][n] = __builtin_amdgcn_mfma_f32_16x16x32_bf16(Bt[n][k], At[m][k], acc[ai][bj][m][n], 0, 0, 0); __builtin_amdgcn_s_setprio(0); } while (0)
; #define PG8_WAIT_V(n) asm volatile("s_waitcnt vmcnt(" #n ")" ::: "memory")
; #define PG8_WAIT_L(n) asm volatile("s_waitcnt lgkmcnt(" #n ")" ::: "memory")
; #define PG8_BAR __builtin_amdgcn_s_barrier()
; #define PG8_SCHED __builtin_amdgcn_sched_barrier(0)
; template <class Epi, class Sched>
; __device__ __forceinline__ void gemm_phase(PG8_LAS unsigned char* lds, const Gemm g, const Sched& S, const Epi& E) {
;     ...
;             PG8_LDA(At, 1, 1); PG8_STAGE(PG8_SA(1, 0), a3, voffA);
;             PG8_BAR; PG8_WAIT_L(0); PG8_MMA(1, 0, At, B0); PG8_BAR; PG8_SCHED;
;             PG8_STAGE(PG8_SB(1, 1), b3 + hstep, voffB);
;             PG8_WAIT_V(6); PG8_BAR; PG8_MMA(1, 1, At, B1); PG8_BAR;
;   DEV void operator()(const f32x4 (&acc)[2][2][4][2], const pg8::Unit& u, int wr, int wc, int fr, int fq) const {
;     ...
;     } else {
; #pragma unroll
;       for (int ai = 0; ai < 2; ++ai)
; #pragma unroll
;         for (int m = 0; m < 4; ++m) {
;           const int row = row0 + ai * 128 + m * 16;
; #pragma unroll
;           for (int bj = 0; bj < 2; ++bj) {
;             const int c = (pn - 10) * 256 + bj * 128 + cl;
;             if (c < 1920) {
;               u32x4 o;
;               o[0] = pk2(acc[ai][bj][m][0][0], acc[ai][bj][m][0][1]); o[1] = pk2(acc[ai][bj][m][0][2], acc[ai][bj][m][0][3]);
;               o[2] = pk2(acc[ai][bj][m][1][0], acc[ai][bj][m][1][1]); o[3] = pk2(acc[ai][bj][m][1][2], acc[ai][bj][m][1][3]);
;               *(u32x4*)(ZRW + (size_t)row * 1920 + c) = o;
;             }
;           }
	ds_read_b128 v[170:173], v168 offset:49152
	ds_read_b128 v[178:181], v168 offset:51200
	ds_read_b128 v[186:189], v168 offset:53248
	ds_read_b128 v[194:197], v168 offset:55296
	ds_read_b128 v[174:177], v168 offset:50176
	ds_read_b128 v[182:185], v168 offset:52224
	ds_read_b128 v[190:193], v168 offset:54272
	ds_read_b128 v[198:201], v168 offset:56320
	global_load_lds_dwordx4 v[160:161], off
	v_lshl_add_u64 v[160:161], v[224:225], 0, s[2:3]
	s_mov_b32 m0, s50
	s_nop 0
	global_load_lds_dwordx4 v[160:161], off
	s_barrier
	s_waitcnt lgkmcnt(7)
	v_mfma_f32_16x16x32_bf16 v[60:63], v[144:147], v[170:173], v[60:63]
	v_mfma_f32_16x16x32_bf16 v[52:55], v[152:155], v[170:173], v[52:55]
	s_waitcnt lgkmcnt(6)
	v_mfma_f32_16x16x32_bf16 v[44:47], v[144:147], v[178:181], v[44:47]
	v_mfma_f32_16x16x32_bf16 v[36:39], v[152:155], v[178:181], v[36:39]
	s_waitcnt lgkmcnt(5)
	v_mfma_f32_16x16x32_bf16 v[28:31], v[144:147], v[186:189], v[28:31]
	v_mfma_f32_16x16x32_bf16 v[20:23], v[152:155], v[186:189], v[20:23]
	s_waitcnt lgkmcnt(4)
	v_mfma_f32_16x16x32_bf16 v[12:15], v[144:147], v[194:197], v[12:15]
	v_mfma_f32_16x16x32_bf16 v[4:7], v[152:155], v[194:197], v[4:7]
	s_waitcnt lgkmcnt(3)
	v_mfma_f32_16x16x32_bf16 v[60:63], v[148:151], v[174:177], v[60:63]
	v_mfma_f32_16x16x32_bf16 v[52:55], v[156:159], v[174:177], v[52:55]
	s_waitcnt lgkmcnt(2)
	v_mfma_f32_16x16x32_bf16 v[44:47], v[148:151], v[182:185], v[44:47]
	v_mfma_f32_16x16x32_bf16 v[36:39], v[156:159], v[182:185], v[36:39]
	s_waitcnt lgkmcnt(1)
	v_mfma_f32_16x16x32_bf16 v[28:31], v[148:151], v[190:193], v[28:31]
	v_mfma_f32_16x16x32_bf16 v[20:23], v[156:159], v[190:193], v[20:23]
	s_waitcnt lgkmcnt(0)
	v_mfma_f32_16x16x32_bf16 v[12:15], v[148:151], v[198:201], v[12:15]
	v_mfma_f32_16x16x32_bf16 v[4:7], v[156:159], v[198:201], v[4:7]
	s_barrier
	s_add_u32 s30, s30, 0x40080
	s_addc_u32 s31, s31, 0
	s_add_i32 s48, s48, s51
	v_lshl_add_u64 v[144:145], s[30:31], 0, v[134:135]
	s_mov_b32 m0, s48
	s_nop 0
	global_load_lds_dwordx4 v[144:145], off
	v_lshl_add_u64 v[144:145], s[30:31], 0, v[130:131]
	s_add_i32 m0, s48, 0x2000
	s_nop 0
	global_load_lds_dwordx4 v[144:145], off
	s_waitcnt vmcnt(6)
	s_barrier
	v_mfma_f32_16x16x32_bf16 v[56:59], v[202:205], v[170:173], v[56:59]
	v_mfma_f32_16x16x32_bf16 v[48:51], v[212:215], v[170:173], v[48:51]
	v_mfma_f32_16x16x32_bf16 v[40:43], v[202:205], v[178:181], v[40:43]
	v_mfma_f32_16x16x32_bf16 v[32:35], v[212:215], v[178:181], v[32:35]
	v_mfma_f32_16x16x32_bf16 v[24:27], v[202:205], v[186:189], v[24:27]
	v_mfma_f32_16x16x32_bf16 v[16:19], v[212:215], v[186:189], v[16:19]
	v_mfma_f32_16x16x32_bf16 v[8:11], v[202:205], v[194:197], v[8:11]
	v_mfma_f32_16x16x32_bf16 v[0:3], v[212:215], v[194:197], v[0:3]
	v_mfma_f32_16x16x32_bf16 v[56:59], v[208:211], v[174:177], v[56:59]
	v_mfma_f32_16x16x32_bf16 v[48:51], v[216:219], v[174:177], v[48:51]
	v_mfma_f32_16x16x32_bf16 v[40:43], v[208:211], v[182:185], v[40:43]
	v_mfma_f32_16x16x32_bf16 v[32:35], v[216:219], v[182:185], v[32:35]
	v_mfma_f32_16x16x32_bf16 v[24:27], v[208:211], v[190:193], v[24:27]
	v_mfma_f32_16x16x32_bf16 v[16:19], v[216:219], v[190:193], v[16:19]
	v_mfma_f32_16x16x32_bf16 v[8:11], v[208:211], v[198:201], v[8:11]
	v_mfma_f32_16x16x32_bf16 v[0:3], v[216:219], v[198:201], v[0:3]
	s_add_i32 s61, s61, 2
	s_add_u32 s0, s0, 0x100
	s_addc_u32 s1, s1, 0
	s_add_u32 s59, s59, 0x100
	s_addc_u32 s60, s60, 0
	s_cmp_gt_u32 s61, 13
	s_barrier
	s_cbranch_scc0 .LBB0_654
	s_lshl_b32 s41, s56, 8
	s_add_i32 s41, s41, s79
	v_readlane_b32 s60, v255, 32
	v_readlane_b32 s64, v255, 38
	v_or_b32_e32 v144, s41, v139
	s_cmp_gt_i32 s37, 3
	s_mov_b64 s[0:1], -1
	v_readlane_b32 s61, v255, 33
	v_readlane_b32 s65, v255, 39
	s_movk_i32 s56, 0x2000
	s_cbranch_scc0 .LBB0_729
	s_cmp_gt_u32 s37, 7
	s_cbranch_scc0 .LBB0_694
	s_lshl_b32 s43, s37, 8
	s_cmp_lt_u32 s37, 10
	s_cbranch_scc1 .LBB0_691
	s_movk_i32 s0, 0xf00
	v_mad_i64_i32 v[146:147], s[0:1], v144, s0, 0
	v_add_u32_e32 v96, s43, v163
	s_movk_i32 s0, 0x780
	v_cmp_gt_i32_e32 vcc, s0, v96
	v_readlane_b32 s0, v251, 49
	v_readlane_b32 s1, v251, 50
	s_nop 1
	v_lshl_add_u64 v[146:147], s[0:1], 0, v[146:147]
	s_and_saveexec_b64 s[0:1], vcc
	s_cbranch_execz .LBB0_660
	v_cvt_pk_bf16_f32 v148, v126, v127
	v_cvt_pk_bf16_f32 v149, v128, v129
	v_cvt_pk_bf16_f32 v150, v118, v119
	v_cvt_pk_bf16_f32 v151, v120, v121
	v_lshl_add_u64 v[152:153], v[96:97], 1, v[146:147]
	global_store_dwordx4 v[152:153], v[148:151], off
